# MFMA order: the two k-half MFMAs of each accumulator issued back to back (SrcC forwarding chain); on top of v37
# speedup vs baseline: 1.0106x; 1.0106x over previous
; #define PG8_STAGEX(rs, bufoff, soff, voff) do { _Pragma("unroll") for (int _i = 0; _i < 2; ++_i) \
;         __builtin_amdgcn_raw_ptr_buffer_load_lds(rs, (LAS unsigned*)(lds + (bufoff) + ldsw + _i * 8192), 16, (voff)[_i], (soff), 0, 0); } while (0)
; #define PG8_LDA(dst, b, h) do { _Pragma("unroll") for (int m = 0; m < 4; ++m) _Pragma("unroll") for (int k = 0; k < 2; ++k) dst[m][k] = *(const LAS bf16x8*)(lds + PG8_SA(b, h) + aoff + m * 2048 + k * 1024); } while (0)
; #define PG8_LDB(dst, b, h) do { _Pragma("unroll") for (int n = 0; n < 2; ++n) _Pragma("unroll") for (int k = 0; k < 2; ++k) dst[n][k] = *(const LAS bf16x8*)(lds + PG8_SB(b, h) + boff + n * 2048 + k * 1024); } while (0)
; #define PG8_WAIT_V(n) asm volatile("s_waitcnt vmcnt(" #n ")" ::: "memory")
; #define PG8_WAIT_L(n) asm volatile("s_waitcnt lgkmcnt(" #n ")" ::: "memory")
; #define PG8_BAR __builtin_amdgcn_s_barrier()
; #define PG8_SCHED __builtin_amdgcn_sched_barrier(0)
;     ...
;             PG8_LDB(B0, 0, 0); PG8_LDB(B1, 0, 1); PG8_SCHED; PG8_LDA(At, 0, 0); PG8_STAGEX(rsA, PG8_SA(1, 1), a1 + hstepA, voffA);
;             PG8_WAIT_V(8); PG8_WAIT_L(0); PG8_BAR; PG8_MMA(0, 0, At, B0); PG8_MMA(0, 1, At, B1); PG8_BAR; PG8_SCHED;
;             PG8_LDA(At, 0, 1); PG8_STAGEX(rsB, PG8_SB(0, 0), b2, voffB); PG8_STAGEX(rsB, PG8_SB(0, 1), b2 + hstepB, voffB); PG8_STAGEX(rsA, PG8_SA(0, 0), a2, voffA);
;             PG8_WAIT_V(8); PG8_WAIT_L(0); PG8_BAR; PG8_MMA(1, 0, At, B0); PG8_MMA(1, 1, At, B1); PG8_BAR; PG8_SCHED;
;             PG8_LDB(B0, 1, 0); PG8_LDB(B1, 1, 1); PG8_SCHED; PG8_LDA(At, 1, 0); PG8_STAGEX(rsA, PG8_SA(0, 1), a2 + hstepA, voffA);
;             PG8_WAIT_V(8); PG8_WAIT_L(0); PG8_BAR; PG8_MMA(0, 0, At, B0); PG8_MMA(0, 1, At, B1); PG8_BAR; PG8_SCHED;
;             PG8_LDA(At, 1, 1); PG8_STAGEX(rsB, PG8_SB(1, 0), b3, voffB); PG8_STAGEX(rsB, PG8_SB(1, 1), b3 + hstepB, voffB); PG8_STAGEX(rsA, PG8_SA(1, 0), a3, voffA);
;             PG8_WAIT_V(8); PG8_WAIT_L(0); PG8_BAR; PG8_MMA(1, 0, At, B0); PG8_MMA(1, 1, At, B1); PG8_BAR; PG8_SCHED;
.LBB0_223:
	v_add_u32_e32 v102, 0x10000, v172
	v_add_u32_e32 v146, 0x14000, v172
	ds_read_b128 v[82:85], v102
	ds_read_b128 v[86:89], v102 offset:1024
	ds_read_b128 v[98:101], v102 offset:2048
	ds_read_b128 v[102:105], v102 offset:3072
	ds_read_b128 v[150:153], v146
	ds_read_b128 v[154:157], v146 offset:1024
	ds_read_b128 v[182:185], v146 offset:2048
	ds_read_b128 v[186:189], v146 offset:3072
	s_add_i32 s42, s50, 0xfff80080
	s_cmp_eq_u32 s52, 28
	s_cselect_b32 s55, s30, s42
	s_cselect_b32 s54, s31, s51
	s_or_b32 s53, s55, 0x80
	s_mov_b32 m0, s22
	ds_read_b128 v[190:193], v173
	ds_read_b128 v[194:197], v173 offset:1024
	ds_read_b128 v[198:201], v173 offset:2048
	ds_read_b128 v[202:205], v173 offset:3072
	ds_read_b128 v[206:209], v173 offset:4096
	ds_read_b128 v[210:213], v173 offset:5120
	ds_read_b128 v[214:217], v173 offset:6144
	ds_read_b128 v[218:221], v173 offset:7168
	buffer_load_dwordx4 v159, s[76:79], s50 offen lds
	s_mov_b32 m0, s23
	s_nop 0
	buffer_load_dwordx4 v163, s[76:79], s50 offen lds
	s_waitcnt vmcnt(8)
	s_waitcnt lgkmcnt(0)
	s_setprio 1
	s_barrier
	v_mfma_f32_16x16x32_bf16 v[142:145], v[82:85], v[190:193], v[142:145]
	v_mfma_f32_16x16x32_bf16 v[142:145], v[86:89], v[194:197], v[142:145]
	v_mfma_f32_16x16x32_bf16 v[134:137], v[98:101], v[190:193], v[134:137]
	v_mfma_f32_16x16x32_bf16 v[134:137], v[102:105], v[194:197], v[134:137]
	v_mfma_f32_16x16x32_bf16 v[126:129], v[82:85], v[198:201], v[126:129]
	v_mfma_f32_16x16x32_bf16 v[126:129], v[86:89], v[202:205], v[126:129]
	v_mfma_f32_16x16x32_bf16 v[118:121], v[98:101], v[198:201], v[118:121]
	v_mfma_f32_16x16x32_bf16 v[118:121], v[102:105], v[202:205], v[118:121]
	v_mfma_f32_16x16x32_bf16 v[110:113], v[82:85], v[206:209], v[110:113]
	v_mfma_f32_16x16x32_bf16 v[110:113], v[86:89], v[210:213], v[110:113]
	v_mfma_f32_16x16x32_bf16 v[94:97], v[98:101], v[206:209], v[94:97]
	v_mfma_f32_16x16x32_bf16 v[94:97], v[102:105], v[210:213], v[94:97]
	v_mfma_f32_16x16x32_bf16 v[78:81], v[82:85], v[214:217], v[78:81]
	v_mfma_f32_16x16x32_bf16 v[78:81], v[86:89], v[218:221], v[78:81]
	v_mfma_f32_16x16x32_bf16 v[70:73], v[98:101], v[214:217], v[70:73]
	v_mfma_f32_16x16x32_bf16 v[70:73], v[102:105], v[218:221], v[70:73]
	v_mfma_f32_16x16x32_bf16 v[138:141], v[150:153], v[190:193], v[138:141]
	v_mfma_f32_16x16x32_bf16 v[138:141], v[154:157], v[194:197], v[138:141]
	v_mfma_f32_16x16x32_bf16 v[130:133], v[182:185], v[190:193], v[130:133]
	v_mfma_f32_16x16x32_bf16 v[130:133], v[186:189], v[194:197], v[130:133]
	v_mfma_f32_16x16x32_bf16 v[122:125], v[150:153], v[198:201], v[122:125]
	v_mfma_f32_16x16x32_bf16 v[122:125], v[154:157], v[202:205], v[122:125]
	v_mfma_f32_16x16x32_bf16 v[114:117], v[182:185], v[198:201], v[114:117]
	v_mfma_f32_16x16x32_bf16 v[114:117], v[186:189], v[202:205], v[114:117]
	v_mfma_f32_16x16x32_bf16 v[106:109], v[150:153], v[206:209], v[106:109]
	v_mfma_f32_16x16x32_bf16 v[106:109], v[154:157], v[210:213], v[106:109]
	v_mfma_f32_16x16x32_bf16 v[90:93], v[182:185], v[206:209], v[90:93]
	v_mfma_f32_16x16x32_bf16 v[90:93], v[186:189], v[210:213], v[90:93]
	v_mfma_f32_16x16x32_bf16 v[74:77], v[150:153], v[214:217], v[74:77]
	v_mfma_f32_16x16x32_bf16 v[74:77], v[154:157], v[218:221], v[74:77]
	v_mfma_f32_16x16x32_bf16 v[66:69], v[182:185], v[214:217], v[66:69]
	v_mfma_f32_16x16x32_bf16 v[66:69], v[186:189], v[218:221], v[66:69]
	s_barrier
	s_setprio 0
	s_mov_b32 m0, s9
	s_mov_b32 s42, s78
	s_mov_b32 s43, s79
	ds_read_b128 v[190:193], v173 offset:16384
	ds_read_b128 v[194:197], v173 offset:17408
	ds_read_b128 v[198:201], v173 offset:18432
	ds_read_b128 v[202:205], v173 offset:19456
	ds_read_b128 v[206:209], v173 offset:20480
	ds_read_b128 v[210:213], v173 offset:21504
	ds_read_b128 v[214:217], v173 offset:22528
	ds_read_b128 v[218:221], v173 offset:23552
	buffer_load_dwordx4 v161, s[40:43], s54 offen lds
	s_mov_b32 m0, s10
	s_add_i32 s56, s54, 0x80000
	buffer_load_dwordx4 v165, s[40:43], s54 offen lds
	s_mov_b32 m0, s11
	s_nop 0
	buffer_load_dwordx4 v161, s[40:43], s56 offen lds
	s_mov_b32 m0, s12
	s_nop 0
	buffer_load_dwordx4 v165, s[40:43], s56 offen lds
	s_mov_b32 m0, s8
	s_nop 0
	buffer_load_dwordx4 v159, s[76:79], s55 offen lds
	s_mov_b32 m0, s13
	s_nop 0
	buffer_load_dwordx4 v163, s[76:79], s55 offen lds
	s_waitcnt vmcnt(8)
	s_waitcnt lgkmcnt(0)
	s_setprio 1
	s_barrier
	v_mfma_f32_16x16x32_bf16 v[62:65], v[82:85], v[190:193], v[62:65]
	v_mfma_f32_16x16x32_bf16 v[62:65], v[86:89], v[194:197], v[62:65]
	v_mfma_f32_16x16x32_bf16 v[54:57], v[98:101], v[190:193], v[54:57]
	v_mfma_f32_16x16x32_bf16 v[54:57], v[102:105], v[194:197], v[54:57]
	v_mfma_f32_16x16x32_bf16 v[46:49], v[82:85], v[198:201], v[46:49]
	v_mfma_f32_16x16x32_bf16 v[46:49], v[86:89], v[202:205], v[46:49]
	v_mfma_f32_16x16x32_bf16 v[38:41], v[98:101], v[198:201], v[38:41]
	v_mfma_f32_16x16x32_bf16 v[38:41], v[102:105], v[202:205], v[38:41]
	v_mfma_f32_16x16x32_bf16 v[30:33], v[82:85], v[206:209], v[30:33]
	v_mfma_f32_16x16x32_bf16 v[30:33], v[86:89], v[210:213], v[30:33]
	v_mfma_f32_16x16x32_bf16 v[22:25], v[98:101], v[206:209], v[22:25]
	v_mfma_f32_16x16x32_bf16 v[22:25], v[102:105], v[210:213], v[22:25]
	v_mfma_f32_16x16x32_bf16 v[14:17], v[82:85], v[214:217], v[14:17]
	v_mfma_f32_16x16x32_bf16 v[14:17], v[86:89], v[218:221], v[14:17]
	v_mfma_f32_16x16x32_bf16 v[6:9], v[98:101], v[214:217], v[6:9]
	v_mfma_f32_16x16x32_bf16 v[6:9], v[102:105], v[218:221], v[6:9]
	v_mfma_f32_16x16x32_bf16 v[58:61], v[150:153], v[190:193], v[58:61]
	v_mfma_f32_16x16x32_bf16 v[58:61], v[154:157], v[194:197], v[58:61]
	v_mfma_f32_16x16x32_bf16 v[50:53], v[182:185], v[190:193], v[50:53]
	v_mfma_f32_16x16x32_bf16 v[50:53], v[186:189], v[194:197], v[50:53]
	v_mfma_f32_16x16x32_bf16 v[42:45], v[150:153], v[198:201], v[42:45]
	v_mfma_f32_16x16x32_bf16 v[42:45], v[154:157], v[202:205], v[42:45]
	v_mfma_f32_16x16x32_bf16 v[34:37], v[182:185], v[198:201], v[34:37]
	v_mfma_f32_16x16x32_bf16 v[34:37], v[186:189], v[202:205], v[34:37]
	v_mfma_f32_16x16x32_bf16 v[26:29], v[150:153], v[206:209], v[26:29]
	v_mfma_f32_16x16x32_bf16 v[26:29], v[154:157], v[210:213], v[26:29]
	v_mfma_f32_16x16x32_bf16 v[18:21], v[182:185], v[206:209], v[18:21]
	v_mfma_f32_16x16x32_bf16 v[18:21], v[186:189], v[210:213], v[18:21]
	v_mfma_f32_16x16x32_bf16 v[10:13], v[150:153], v[214:217], v[10:13]
	v_mfma_f32_16x16x32_bf16 v[10:13], v[154:157], v[218:221], v[10:13]
	v_mfma_f32_16x16x32_bf16 v[2:5], v[182:185], v[214:217], v[2:5]
	v_mfma_f32_16x16x32_bf16 v[2:5], v[186:189], v[218:221], v[2:5]
	s_barrier
; #define PG8_STAGEX(rs, bufoff, soff, voff) do { _Pragma("unroll") for (int _i = 0; _i < 2; ++_i) \
;         __builtin_amdgcn_raw_ptr_buffer_load_lds(rs, (LAS unsigned*)(lds + (bufoff) + ldsw + _i * 8192), 16, (voff)[_i], (soff), 0, 0); } while (0)
; #define PG8_LDA(dst, b, h) do { _Pragma("unroll") for (int m = 0; m < 4; ++m) _Pragma("unroll") for (int k = 0; k < 2; ++k) dst[m][k] = *(const LAS bf16x8*)(lds + PG8_SA(b, h) + aoff + m * 2048 + k * 1024); } while (0)
; #define PG8_LDB(dst, b, h) do { _Pragma("unroll") for (int n = 0; n < 2; ++n) _Pragma("unroll") for (int k = 0; k < 2; ++k) dst[n][k] = *(const LAS bf16x8*)(lds + PG8_SB(b, h) + boff + n * 2048 + k * 1024); } while (0)
; #define PG8_WAIT_V(n) asm volatile("s_waitcnt vmcnt(" #n ")" ::: "memory")
; #define PG8_WAIT_L(n) asm volatile("s_waitcnt lgkmcnt(" #n ")" ::: "memory")
; #define PG8_BAR __builtin_amdgcn_s_barrier()
; #define PG8_SCHED __builtin_amdgcn_sched_barrier(0)
;     ...
;             PG8_LDB(B0, 1, 0); PG8_LDB(B1, 1, 1); PG8_SCHED; PG8_LDA(At, 1, 0); PG8_STAGEX(rsA, PG8_SA(0, 1), a2 + hstepA, voffA);
;             PG8_WAIT_V(8); PG8_WAIT_L(0); PG8_BAR; PG8_MMA(0, 0, At, B0); PG8_MMA(0, 1, At, B1); PG8_BAR; PG8_SCHED;
;             PG8_LDA(At, 1, 1); PG8_STAGEX(rsB, PG8_SB(1, 0), b3, voffB); PG8_STAGEX(rsB, PG8_SB(1, 1), b3 + hstepB, voffB); PG8_STAGEX(rsA, PG8_SA(1, 0), a3, voffA);
;             PG8_WAIT_V(8); PG8_WAIT_L(0); PG8_BAR; PG8_MMA(1, 0, At, B0); PG8_MMA(1, 1, At, B1); PG8_BAR; PG8_SCHED;
;         }
	s_setprio 0
	v_add_u32_e32 v102, 0x18000, v172
	v_add_u32_e32 v146, 0x1c000, v172
	ds_read_b128 v[82:85], v102
	ds_read_b128 v[86:89], v102 offset:1024
	ds_read_b128 v[98:101], v102 offset:2048
	ds_read_b128 v[102:105], v102 offset:3072
	ds_read_b128 v[150:153], v146
	ds_read_b128 v[154:157], v146 offset:1024
	ds_read_b128 v[182:185], v146 offset:2048
	ds_read_b128 v[186:189], v146 offset:3072
	s_add_i32 s55, s55, 0x80000
	s_mov_b32 m0, s14
	ds_read_b128 v[190:193], v173 offset:32768
	ds_read_b128 v[194:197], v173 offset:33792
	ds_read_b128 v[198:201], v173 offset:34816
	ds_read_b128 v[202:205], v173 offset:35840
	ds_read_b128 v[206:209], v173 offset:36864
	ds_read_b128 v[210:213], v173 offset:37888
	ds_read_b128 v[214:217], v173 offset:38912
	ds_read_b128 v[218:221], v173 offset:39936
	buffer_load_dwordx4 v159, s[76:79], s55 offen lds
	s_mov_b32 m0, s15
	s_nop 0
	buffer_load_dwordx4 v163, s[76:79], s55 offen lds
	s_waitcnt vmcnt(8)
	s_waitcnt lgkmcnt(0)
	s_setprio 1
	s_barrier
	v_mfma_f32_16x16x32_bf16 v[142:145], v[82:85], v[190:193], v[142:145]
	v_mfma_f32_16x16x32_bf16 v[142:145], v[86:89], v[194:197], v[142:145]
	v_mfma_f32_16x16x32_bf16 v[134:137], v[98:101], v[190:193], v[134:137]
	v_mfma_f32_16x16x32_bf16 v[134:137], v[102:105], v[194:197], v[134:137]
	v_mfma_f32_16x16x32_bf16 v[126:129], v[82:85], v[198:201], v[126:129]
	v_mfma_f32_16x16x32_bf16 v[126:129], v[86:89], v[202:205], v[126:129]
	v_mfma_f32_16x16x32_bf16 v[118:121], v[98:101], v[198:201], v[118:121]
	v_mfma_f32_16x16x32_bf16 v[118:121], v[102:105], v[202:205], v[118:121]
	v_mfma_f32_16x16x32_bf16 v[110:113], v[82:85], v[206:209], v[110:113]
	v_mfma_f32_16x16x32_bf16 v[110:113], v[86:89], v[210:213], v[110:113]
	v_mfma_f32_16x16x32_bf16 v[94:97], v[98:101], v[206:209], v[94:97]
	v_mfma_f32_16x16x32_bf16 v[94:97], v[102:105], v[210:213], v[94:97]
	v_mfma_f32_16x16x32_bf16 v[78:81], v[82:85], v[214:217], v[78:81]
	v_mfma_f32_16x16x32_bf16 v[78:81], v[86:89], v[218:221], v[78:81]
	v_mfma_f32_16x16x32_bf16 v[70:73], v[98:101], v[214:217], v[70:73]
	v_mfma_f32_16x16x32_bf16 v[70:73], v[102:105], v[218:221], v[70:73]
	v_mfma_f32_16x16x32_bf16 v[138:141], v[150:153], v[190:193], v[138:141]
	v_mfma_f32_16x16x32_bf16 v[138:141], v[154:157], v[194:197], v[138:141]
	v_mfma_f32_16x16x32_bf16 v[130:133], v[182:185], v[190:193], v[130:133]
	v_mfma_f32_16x16x32_bf16 v[130:133], v[186:189], v[194:197], v[130:133]
	v_mfma_f32_16x16x32_bf16 v[122:125], v[150:153], v[198:201], v[122:125]
	v_mfma_f32_16x16x32_bf16 v[122:125], v[154:157], v[202:205], v[122:125]
	v_mfma_f32_16x16x32_bf16 v[114:117], v[182:185], v[198:201], v[114:117]
	v_mfma_f32_16x16x32_bf16 v[114:117], v[186:189], v[202:205], v[114:117]
	v_mfma_f32_16x16x32_bf16 v[106:109], v[150:153], v[206:209], v[106:109]
	v_mfma_f32_16x16x32_bf16 v[106:109], v[154:157], v[210:213], v[106:109]
	v_mfma_f32_16x16x32_bf16 v[90:93], v[182:185], v[206:209], v[90:93]
	v_mfma_f32_16x16x32_bf16 v[90:93], v[186:189], v[210:213], v[90:93]
	v_mfma_f32_16x16x32_bf16 v[74:77], v[150:153], v[214:217], v[74:77]
	v_mfma_f32_16x16x32_bf16 v[74:77], v[154:157], v[218:221], v[74:77]
	v_mfma_f32_16x16x32_bf16 v[66:69], v[182:185], v[214:217], v[66:69]
	v_mfma_f32_16x16x32_bf16 v[66:69], v[186:189], v[218:221], v[66:69]
	s_barrier
	s_setprio 0
	s_mov_b32 m0, s16
	s_or_b32 s55, s54, 0x80
	ds_read_b128 v[190:193], v173 offset:49152
	ds_read_b128 v[194:197], v173 offset:50176
	ds_read_b128 v[198:201], v173 offset:51200
	ds_read_b128 v[202:205], v173 offset:52224
	ds_read_b128 v[206:209], v173 offset:53248
	ds_read_b128 v[210:213], v173 offset:54272
	ds_read_b128 v[214:217], v173 offset:55296
	ds_read_b128 v[218:221], v173 offset:56320
	buffer_load_dwordx4 v161, s[40:43], s55 offen lds
	s_mov_b32 m0, s17
	s_add_i32 s54, s54, 0x80080
	buffer_load_dwordx4 v165, s[40:43], s55 offen lds
	s_mov_b32 m0, s20
	s_nop 0
	buffer_load_dwordx4 v161, s[40:43], s54 offen lds
	s_mov_b32 m0, s21
	s_nop 0
	buffer_load_dwordx4 v165, s[40:43], s54 offen lds
	s_mov_b32 m0, s18
	s_nop 0
	buffer_load_dwordx4 v159, s[76:79], s53 offen lds
	s_mov_b32 m0, s19
	s_nop 0
	buffer_load_dwordx4 v163, s[76:79], s53 offen lds
	s_waitcnt vmcnt(8)
	s_waitcnt lgkmcnt(0)
	s_setprio 1
	s_barrier
	v_mfma_f32_16x16x32_bf16 v[62:65], v[82:85], v[190:193], v[62:65]
	v_mfma_f32_16x16x32_bf16 v[62:65], v[86:89], v[194:197], v[62:65]
	v_mfma_f32_16x16x32_bf16 v[54:57], v[98:101], v[190:193], v[54:57]
	v_mfma_f32_16x16x32_bf16 v[54:57], v[102:105], v[194:197], v[54:57]
	v_mfma_f32_16x16x32_bf16 v[46:49], v[82:85], v[198:201], v[46:49]
	v_mfma_f32_16x16x32_bf16 v[46:49], v[86:89], v[202:205], v[46:49]
	v_mfma_f32_16x16x32_bf16 v[38:41], v[98:101], v[198:201], v[38:41]
	v_mfma_f32_16x16x32_bf16 v[38:41], v[102:105], v[202:205], v[38:41]
	v_mfma_f32_16x16x32_bf16 v[30:33], v[82:85], v[206:209], v[30:33]
	v_mfma_f32_16x16x32_bf16 v[30:33], v[86:89], v[210:213], v[30:33]
	v_mfma_f32_16x16x32_bf16 v[22:25], v[98:101], v[206:209], v[22:25]
	v_mfma_f32_16x16x32_bf16 v[22:25], v[102:105], v[210:213], v[22:25]
	v_mfma_f32_16x16x32_bf16 v[14:17], v[82:85], v[214:217], v[14:17]
	v_mfma_f32_16x16x32_bf16 v[14:17], v[86:89], v[218:221], v[14:17]
	v_mfma_f32_16x16x32_bf16 v[6:9], v[98:101], v[214:217], v[6:9]
	v_mfma_f32_16x16x32_bf16 v[6:9], v[102:105], v[218:221], v[6:9]
	v_mfma_f32_16x16x32_bf16 v[58:61], v[150:153], v[190:193], v[58:61]
	v_mfma_f32_16x16x32_bf16 v[58:61], v[154:157], v[194:197], v[58:61]
	v_mfma_f32_16x16x32_bf16 v[50:53], v[182:185], v[190:193], v[50:53]
	v_mfma_f32_16x16x32_bf16 v[50:53], v[186:189], v[194:197], v[50:53]
	v_mfma_f32_16x16x32_bf16 v[42:45], v[150:153], v[198:201], v[42:45]
	v_mfma_f32_16x16x32_bf16 v[42:45], v[154:157], v[202:205], v[42:45]
	v_mfma_f32_16x16x32_bf16 v[34:37], v[182:185], v[198:201], v[34:37]
	v_mfma_f32_16x16x32_bf16 v[34:37], v[186:189], v[202:205], v[34:37]
	v_mfma_f32_16x16x32_bf16 v[26:29], v[150:153], v[206:209], v[26:29]
	v_mfma_f32_16x16x32_bf16 v[26:29], v[154:157], v[210:213], v[26:29]
	v_mfma_f32_16x16x32_bf16 v[18:21], v[182:185], v[206:209], v[18:21]
	v_mfma_f32_16x16x32_bf16 v[18:21], v[186:189], v[210:213], v[18:21]
	v_mfma_f32_16x16x32_bf16 v[10:13], v[150:153], v[214:217], v[10:13]
	v_mfma_f32_16x16x32_bf16 v[10:13], v[154:157], v[218:221], v[10:13]
	v_mfma_f32_16x16x32_bf16 v[2:5], v[182:185], v[214:217], v[2:5]
	v_mfma_f32_16x16x32_bf16 v[2:5], v[186:189], v[218:221], v[2:5]
	s_barrier
	s_setprio 0
	s_add_i32 s52, s52, 2
	s_addk_i32 s50, 0x100
	s_addk_i32 s51, 0x100
	s_cmp_gt_u32 s52, 29
	s_cbranch_scc0 .LBB0_223
	s_and_b64 vcc, exec, s[46:47]
	s_cbranch_vccz .LBB0_226
	s_barrier

; #define PG8_STAGEX(rs, bufoff, soff, voff) do { _Pragma("unroll") for (int _i = 0; _i < 2; ++_i) \
;         __builtin_amdgcn_raw_ptr_buffer_load_lds(rs, (LAS unsigned*)(lds + (bufoff) + ldsw + _i * 8192), 16, (voff)[_i], (soff), 0, 0); } while (0)
; #define PG8_LDA(dst, b, h) do { _Pragma("unroll") for (int m = 0; m < 4; ++m) _Pragma("unroll") for (int k = 0; k < 2; ++k) dst[m][k] = *(const LAS bf16x8*)(lds + PG8_SA(b, h) + aoff + m * 2048 + k * 1024); } while (0)
; #define PG8_LDB(dst, b, h) do { _Pragma("unroll") for (int n = 0; n < 2; ++n) _Pragma("unroll") for (int k = 0; k < 2; ++k) dst[n][k] = *(const LAS bf16x8*)(lds + PG8_SB(b, h) + boff + n * 2048 + k * 1024); } while (0)
; #define PG8_WAIT_V(n) asm volatile("s_waitcnt vmcnt(" #n ")" ::: "memory")
; #define PG8_WAIT_L(n) asm volatile("s_waitcnt lgkmcnt(" #n ")" ::: "memory")
; #define PG8_BAR __builtin_amdgcn_s_barrier()
; #define PG8_SCHED __builtin_amdgcn_sched_barrier(0)
;     ...
;                 if (w0) { PG8_LDB(B0, 0, 0); PG8_LDB(B1, 0, 1); PG8_SCHED; PG8_LDA(At, 0, 0); }
;                 PG8_WAIT_L(0); PG8_BAR; if (w0) { PG8_MMA(0, 0, At, B0); PG8_MMA(0, 1, At, B1); } PG8_BAR; PG8_SCHED;
;                 PG8_STAGEX(rsB, PG8_SB(0, 0), b2, voffB); PG8_STAGEX(rsB, PG8_SB(0, 1), b2 + hstepB, voffB); PG8_STAGEX(rsA, PG8_SA(0, 0), a2, voffA);
;                 PG8_WAIT_V(6); PG8_BAR; PG8_BAR; PG8_SCHED;
.LBB0_240:
	v_add_u32_e32 v86, 0x10000, v72
	v_add_u32_e32 v102, 0x14000, v72
	ds_read_b128 v[74:77], v86
	ds_read_b128 v[78:81], v86 offset:1024
	ds_read_b128 v[82:85], v86 offset:2048
	ds_read_b128 v[86:89], v86 offset:3072
	ds_read_b128 v[90:93], v102
	ds_read_b128 v[94:97], v102 offset:1024
	ds_read_b128 v[98:101], v102 offset:2048
	ds_read_b128 v[102:105], v102 offset:3072
	s_cmp_lg_u32 s27, 28
	s_cselect_b32 s28, s26, 0
	s_add_i32 s29, s28, s17
	s_or_b32 s30, s29, 0x80
	s_add_i32 s28, s28, s11
	ds_read_b128 v[106:109], v73
	ds_read_b128 v[110:113], v73 offset:1024
	ds_read_b128 v[114:117], v73 offset:2048
	ds_read_b128 v[118:121], v73 offset:3072
	ds_read_b128 v[122:125], v73 offset:4096
	ds_read_b128 v[126:129], v73 offset:5120
	ds_read_b128 v[130:133], v73 offset:6144
	ds_read_b128 v[134:137], v73 offset:7168
	s_waitcnt lgkmcnt(0)
	s_setprio 1
	s_barrier
	v_mfma_f32_16x16x32_bf16 v[62:65], v[74:77], v[106:109], v[62:65]
	v_mfma_f32_16x16x32_bf16 v[62:65], v[78:81], v[110:113], v[62:65]
	v_mfma_f32_16x16x32_bf16 v[58:61], v[82:85], v[106:109], v[58:61]
	v_mfma_f32_16x16x32_bf16 v[58:61], v[86:89], v[110:113], v[58:61]
	v_mfma_f32_16x16x32_bf16 v[54:57], v[74:77], v[114:117], v[54:57]
	v_mfma_f32_16x16x32_bf16 v[54:57], v[78:81], v[118:121], v[54:57]
	v_mfma_f32_16x16x32_bf16 v[38:41], v[82:85], v[114:117], v[38:41]
	v_mfma_f32_16x16x32_bf16 v[38:41], v[86:89], v[118:121], v[38:41]
	v_mfma_f32_16x16x32_bf16 v[30:33], v[74:77], v[122:125], v[30:33]
	v_mfma_f32_16x16x32_bf16 v[30:33], v[78:81], v[126:129], v[30:33]
	v_mfma_f32_16x16x32_bf16 v[22:25], v[82:85], v[122:125], v[22:25]
	v_mfma_f32_16x16x32_bf16 v[22:25], v[86:89], v[126:129], v[22:25]
	v_mfma_f32_16x16x32_bf16 v[14:17], v[74:77], v[130:133], v[14:17]
	v_mfma_f32_16x16x32_bf16 v[14:17], v[78:81], v[134:137], v[14:17]
	v_mfma_f32_16x16x32_bf16 v[6:9], v[82:85], v[130:133], v[6:9]
	v_mfma_f32_16x16x32_bf16 v[6:9], v[86:89], v[134:137], v[6:9]
	v_mfma_f32_16x16x32_bf16 v[50:53], v[90:93], v[106:109], v[50:53]
	v_mfma_f32_16x16x32_bf16 v[50:53], v[94:97], v[110:113], v[50:53]
	v_mfma_f32_16x16x32_bf16 v[46:49], v[98:101], v[106:109], v[46:49]
	v_mfma_f32_16x16x32_bf16 v[46:49], v[102:105], v[110:113], v[46:49]
	v_mfma_f32_16x16x32_bf16 v[42:45], v[90:93], v[114:117], v[42:45]
	v_mfma_f32_16x16x32_bf16 v[42:45], v[94:97], v[118:121], v[42:45]
	v_mfma_f32_16x16x32_bf16 v[34:37], v[98:101], v[114:117], v[34:37]
	v_mfma_f32_16x16x32_bf16 v[34:37], v[102:105], v[118:121], v[34:37]
	v_mfma_f32_16x16x32_bf16 v[26:29], v[90:93], v[122:125], v[26:29]
	v_mfma_f32_16x16x32_bf16 v[26:29], v[94:97], v[126:129], v[26:29]
	v_mfma_f32_16x16x32_bf16 v[18:21], v[98:101], v[122:125], v[18:21]
	v_mfma_f32_16x16x32_bf16 v[18:21], v[102:105], v[126:129], v[18:21]
	v_mfma_f32_16x16x32_bf16 v[10:13], v[90:93], v[130:133], v[10:13]
	v_mfma_f32_16x16x32_bf16 v[10:13], v[94:97], v[134:137], v[10:13]
	v_mfma_f32_16x16x32_bf16 v[2:5], v[98:101], v[130:133], v[2:5]
	v_mfma_f32_16x16x32_bf16 v[2:5], v[102:105], v[134:137], v[2:5]
	s_barrier
	s_setprio 0
	s_mov_b32 m0, s13
	s_mov_b32 s42, s78
	s_mov_b32 s43, s79
	buffer_load_dwordx4 v67, s[40:43], s28 offen lds
	s_mov_b32 m0, s14
	s_add_i32 s31, s28, 0x80000
	buffer_load_dwordx4 v69, s[40:43], s28 offen lds
	s_mov_b32 m0, s15
	s_nop 0
	buffer_load_dwordx4 v67, s[40:43], s31 offen lds
	s_mov_b32 m0, s16
	s_nop 0
	buffer_load_dwordx4 v69, s[40:43], s31 offen lds
	s_mov_b32 m0, s12
	s_nop 0
	buffer_load_dwordx4 v66, s[76:79], s29 offen lds
	s_mov_b32 m0, s18
	s_nop 0
	buffer_load_dwordx4 v68, s[76:79], s29 offen lds
	s_waitcnt vmcnt(6)
	s_barrier
	s_barrier
; #define PG8_STAGEX(rs, bufoff, soff, voff) do { _Pragma("unroll") for (int _i = 0; _i < 2; ++_i) \
;         __builtin_amdgcn_raw_ptr_buffer_load_lds(rs, (LAS unsigned*)(lds + (bufoff) + ldsw + _i * 8192), 16, (voff)[_i], (soff), 0, 0); } while (0)
; #define PG8_LDA(dst, b, h) do { _Pragma("unroll") for (int m = 0; m < 4; ++m) _Pragma("unroll") for (int k = 0; k < 2; ++k) dst[m][k] = *(const LAS bf16x8*)(lds + PG8_SA(b, h) + aoff + m * 2048 + k * 1024); } while (0)
; #define PG8_LDB(dst, b, h) do { _Pragma("unroll") for (int n = 0; n < 2; ++n) _Pragma("unroll") for (int k = 0; k < 2; ++k) dst[n][k] = *(const LAS bf16x8*)(lds + PG8_SB(b, h) + boff + n * 2048 + k * 1024); } while (0)
; #define PG8_WAIT_V(n) asm volatile("s_waitcnt vmcnt(" #n ")" ::: "memory")
; #define PG8_WAIT_L(n) asm volatile("s_waitcnt lgkmcnt(" #n ")" ::: "memory")
; #define PG8_BAR __builtin_amdgcn_s_barrier()
; #define PG8_SCHED __builtin_amdgcn_sched_barrier(0)
;     ...
;                 if (w0) { PG8_LDB(B0, 1, 0); PG8_LDB(B1, 1, 1); PG8_SCHED; PG8_LDA(At, 1, 0); }
;                 PG8_WAIT_L(0); PG8_BAR; if (w0) { PG8_MMA(0, 0, At, B0); PG8_MMA(0, 1, At, B1); } PG8_BAR; PG8_SCHED;
;                 PG8_STAGEX(rsB, PG8_SB(1, 0), b3, voffB); PG8_STAGEX(rsB, PG8_SB(1, 1), b3 + hstepB, voffB); PG8_STAGEX(rsA, PG8_SA(1, 0), a3, voffA);
;                 PG8_WAIT_V(6); PG8_BAR; PG8_BAR; PG8_SCHED;
;             }
	v_add_u32_e32 v86, 0x18000, v72
	v_add_u32_e32 v102, 0x1c000, v72
	ds_read_b128 v[74:77], v86
	ds_read_b128 v[78:81], v86 offset:1024
	ds_read_b128 v[82:85], v86 offset:2048
	ds_read_b128 v[86:89], v86 offset:3072
	ds_read_b128 v[90:93], v102
	ds_read_b128 v[94:97], v102 offset:1024
	ds_read_b128 v[98:101], v102 offset:2048
	ds_read_b128 v[102:105], v102 offset:3072
	ds_read_b128 v[106:109], v73 offset:32768
	ds_read_b128 v[110:113], v73 offset:33792
	ds_read_b128 v[114:117], v73 offset:34816
	ds_read_b128 v[118:121], v73 offset:35840
	ds_read_b128 v[122:125], v73 offset:36864
	ds_read_b128 v[126:129], v73 offset:37888
	ds_read_b128 v[130:133], v73 offset:38912
	ds_read_b128 v[134:137], v73 offset:39936
	s_waitcnt lgkmcnt(0)
	s_setprio 1
	s_barrier
	v_mfma_f32_16x16x32_bf16 v[62:65], v[74:77], v[106:109], v[62:65]
	v_mfma_f32_16x16x32_bf16 v[58:61], v[82:85], v[106:109], v[58:61]
	v_mfma_f32_16x16x32_bf16 v[54:57], v[74:77], v[114:117], v[54:57]
	v_mfma_f32_16x16x32_bf16 v[38:41], v[82:85], v[114:117], v[38:41]
	v_mfma_f32_16x16x32_bf16 v[30:33], v[74:77], v[122:125], v[30:33]
	v_mfma_f32_16x16x32_bf16 v[22:25], v[82:85], v[122:125], v[22:25]
	v_mfma_f32_16x16x32_bf16 v[14:17], v[74:77], v[130:133], v[14:17]
	v_mfma_f32_16x16x32_bf16 v[6:9], v[82:85], v[130:133], v[6:9]
	v_mfma_f32_16x16x32_bf16 v[62:65], v[78:81], v[110:113], v[62:65]
	v_mfma_f32_16x16x32_bf16 v[58:61], v[86:89], v[110:113], v[58:61]
	v_mfma_f32_16x16x32_bf16 v[54:57], v[78:81], v[118:121], v[54:57]
	v_mfma_f32_16x16x32_bf16 v[38:41], v[86:89], v[118:121], v[38:41]
	v_mfma_f32_16x16x32_bf16 v[30:33], v[78:81], v[126:129], v[30:33]
	v_mfma_f32_16x16x32_bf16 v[22:25], v[86:89], v[126:129], v[22:25]
	v_mfma_f32_16x16x32_bf16 v[14:17], v[78:81], v[134:137], v[14:17]
	v_mfma_f32_16x16x32_bf16 v[6:9], v[86:89], v[134:137], v[6:9]
	v_mfma_f32_16x16x32_bf16 v[50:53], v[90:93], v[106:109], v[50:53]
	s_or_b32 s29, s28, 0x80
	v_mfma_f32_16x16x32_bf16 v[46:49], v[98:101], v[106:109], v[46:49]
	v_mfma_f32_16x16x32_bf16 v[42:45], v[90:93], v[114:117], v[42:45]
	v_mfma_f32_16x16x32_bf16 v[34:37], v[98:101], v[114:117], v[34:37]
	v_mfma_f32_16x16x32_bf16 v[26:29], v[90:93], v[122:125], v[26:29]
	v_mfma_f32_16x16x32_bf16 v[18:21], v[98:101], v[122:125], v[18:21]
	v_mfma_f32_16x16x32_bf16 v[10:13], v[90:93], v[130:133], v[10:13]
	v_mfma_f32_16x16x32_bf16 v[2:5], v[98:101], v[130:133], v[2:5]
	v_mfma_f32_16x16x32_bf16 v[50:53], v[94:97], v[110:113], v[50:53]
	v_mfma_f32_16x16x32_bf16 v[46:49], v[102:105], v[110:113], v[46:49]
	v_mfma_f32_16x16x32_bf16 v[42:45], v[94:97], v[118:121], v[42:45]
	v_mfma_f32_16x16x32_bf16 v[34:37], v[102:105], v[118:121], v[34:37]
	v_mfma_f32_16x16x32_bf16 v[26:29], v[94:97], v[126:129], v[26:29]
	v_mfma_f32_16x16x32_bf16 v[18:21], v[102:105], v[126:129], v[18:21]
	v_mfma_f32_16x16x32_bf16 v[10:13], v[94:97], v[134:137], v[10:13]
	v_mfma_f32_16x16x32_bf16 v[2:5], v[102:105], v[134:137], v[2:5]
	s_barrier
	s_setprio 0
	s_mov_b32 m0, s20
	s_add_i32 s28, s28, 0x80080
	buffer_load_dwordx4 v67, s[40:43], s29 offen lds
	s_mov_b32 m0, s21
	s_nop 0
	buffer_load_dwordx4 v69, s[40:43], s29 offen lds
	s_mov_b32 m0, s24
	s_nop 0
	buffer_load_dwordx4 v67, s[40:43], s28 offen lds
	s_mov_b32 m0, s25
	s_nop 0
	buffer_load_dwordx4 v69, s[40:43], s28 offen lds
	s_mov_b32 m0, s22
	s_nop 0
	buffer_load_dwordx4 v66, s[76:79], s30 offen lds
	s_mov_b32 m0, s23
	s_nop 0
	buffer_load_dwordx4 v68, s[76:79], s30 offen lds
	s_waitcnt vmcnt(6)
	s_barrier
	s_barrier
	s_addk_i32 s26, 0x100
	s_add_i32 s27, s27, 2
	s_cmp_gt_u32 s27, 29
	s_cbranch_scc0 .LBB0_240
	s_cmpk_lt_u32 s8, 0x100
	s_cbranch_scc0 .LBB0_243
	s_barrier

; #define PG8_STAGEX(rs, bufoff, soff, voff) do { _Pragma("unroll") for (int _i = 0; _i < 2; ++_i) \
;         __builtin_amdgcn_raw_ptr_buffer_load_lds(rs, (LAS unsigned*)(lds + (bufoff) + ldsw + _i * 8192), 16, (voff)[_i], (soff), 0, 0); } while (0)
; #define PG8_LDA(dst, b, h) do { _Pragma("unroll") for (int m = 0; m < 4; ++m) _Pragma("unroll") for (int k = 0; k < 2; ++k) dst[m][k] = *(const LAS bf16x8*)(lds + PG8_SA(b, h) + aoff + m * 2048 + k * 1024); } while (0)
; #define PG8_LDB(dst, b, h) do { _Pragma("unroll") for (int n = 0; n < 2; ++n) _Pragma("unroll") for (int k = 0; k < 2; ++k) dst[n][k] = *(const LAS bf16x8*)(lds + PG8_SB(b, h) + boff + n * 2048 + k * 1024); } while (0)
; #define PG8_WAIT_V(n) asm volatile("s_waitcnt vmcnt(" #n ")" ::: "memory")
; #define PG8_WAIT_L(n) asm volatile("s_waitcnt lgkmcnt(" #n ")" ::: "memory")
; #define PG8_BAR __builtin_amdgcn_s_barrier()
; #define PG8_SCHED __builtin_amdgcn_sched_barrier(0)
;     ...
;             PG8_LDB(B0, 0, 0); PG8_LDB(B1, 0, 1); PG8_SCHED; PG8_LDA(At, 0, 0); PG8_STAGEX(rsA, PG8_SA(1, 1), a1 + hstepA, voffA);
;             PG8_WAIT_V(8); PG8_WAIT_L(0); PG8_BAR; PG8_MMA(0, 0, At, B0); PG8_MMA(0, 1, At, B1); PG8_BAR; PG8_SCHED;
;             PG8_LDA(At, 0, 1); PG8_STAGEX(rsB, PG8_SB(0, 0), b2, voffB); PG8_STAGEX(rsB, PG8_SB(0, 1), b2 + hstepB, voffB); PG8_STAGEX(rsA, PG8_SA(0, 0), a2, voffA);
;             PG8_WAIT_V(8); PG8_WAIT_L(0); PG8_BAR; PG8_MMA(1, 0, At, B0); PG8_MMA(1, 1, At, B1); PG8_BAR; PG8_SCHED;
.LBB0_323:
	v_add_u32_e32 v118, 0x10000, v210
	v_add_u32_e32 v160, 0x14000, v210
	ds_read_b128 v[106:109], v118
	ds_read_b128 v[110:113], v118 offset:1024
	ds_read_b128 v[114:117], v118 offset:2048
	ds_read_b128 v[118:121], v118 offset:3072
	ds_read_b128 v[122:125], v160
	ds_read_b128 v[134:137], v160 offset:1024
	ds_read_b128 v[156:159], v160 offset:2048
	ds_read_b128 v[160:163], v160 offset:3072
	s_add_i32 s42, s51, 0xffea8080
	s_cmpk_eq_i32 s58, 0x52
	s_cselect_b32 s61, s30, s42
	s_cselect_b32 s60, s31, s57
	s_or_b32 s59, s61, 0x80
	s_mov_b32 m0, s68
	ds_read_b128 v[164:167], v211
	ds_read_b128 v[168:171], v211 offset:1024
	ds_read_b128 v[182:185], v211 offset:2048
	ds_read_b128 v[186:189], v211 offset:3072
	ds_read_b128 v[190:193], v211 offset:4096
	ds_read_b128 v[194:197], v211 offset:5120
	ds_read_b128 v[198:201], v211 offset:6144
	ds_read_b128 v[202:205], v211 offset:7168
	buffer_load_dwordx4 v178, s[76:79], s51 offen lds
	s_mov_b32 m0, s69
	s_nop 0
	buffer_load_dwordx4 v206, s[76:79], s51 offen lds
	s_waitcnt vmcnt(8)
	s_waitcnt lgkmcnt(0)
	s_setprio 1
	s_barrier
	v_mfma_f32_16x16x32_bf16 v[150:153], v[106:109], v[164:167], v[150:153]
	v_mfma_f32_16x16x32_bf16 v[150:153], v[110:113], v[168:171], v[150:153]
	v_mfma_f32_16x16x32_bf16 v[146:149], v[114:117], v[164:167], v[146:149]
	v_mfma_f32_16x16x32_bf16 v[146:149], v[118:121], v[168:171], v[146:149]
	v_mfma_f32_16x16x32_bf16 v[142:145], v[106:109], v[182:185], v[142:145]
	v_mfma_f32_16x16x32_bf16 v[142:145], v[110:113], v[186:189], v[142:145]
	v_mfma_f32_16x16x32_bf16 v[138:141], v[114:117], v[182:185], v[138:141]
	v_mfma_f32_16x16x32_bf16 v[138:141], v[118:121], v[186:189], v[138:141]
	v_mfma_f32_16x16x32_bf16 v[130:133], v[106:109], v[190:193], v[130:133]
	v_mfma_f32_16x16x32_bf16 v[130:133], v[110:113], v[194:197], v[130:133]
	v_mfma_f32_16x16x32_bf16 v[126:129], v[114:117], v[190:193], v[126:129]
	v_mfma_f32_16x16x32_bf16 v[126:129], v[118:121], v[194:197], v[126:129]
	v_mfma_f32_16x16x32_bf16 v[102:105], v[106:109], v[198:201], v[102:105]
	v_mfma_f32_16x16x32_bf16 v[102:105], v[110:113], v[202:205], v[102:105]
	v_mfma_f32_16x16x32_bf16 v[98:101], v[114:117], v[198:201], v[98:101]
	v_mfma_f32_16x16x32_bf16 v[98:101], v[118:121], v[202:205], v[98:101]
	v_mfma_f32_16x16x32_bf16 v[62:65], v[122:125], v[164:167], v[62:65]
	v_mfma_f32_16x16x32_bf16 v[62:65], v[134:137], v[168:171], v[62:65]
	v_mfma_f32_16x16x32_bf16 v[58:61], v[156:159], v[164:167], v[58:61]
	v_mfma_f32_16x16x32_bf16 v[58:61], v[160:163], v[168:171], v[58:61]
	v_mfma_f32_16x16x32_bf16 v[54:57], v[122:125], v[182:185], v[54:57]
	v_mfma_f32_16x16x32_bf16 v[54:57], v[134:137], v[186:189], v[54:57]
	v_mfma_f32_16x16x32_bf16 v[50:53], v[156:159], v[182:185], v[50:53]
	v_mfma_f32_16x16x32_bf16 v[50:53], v[160:163], v[186:189], v[50:53]
	v_mfma_f32_16x16x32_bf16 v[46:49], v[122:125], v[190:193], v[46:49]
	v_mfma_f32_16x16x32_bf16 v[46:49], v[134:137], v[194:197], v[46:49]
	v_mfma_f32_16x16x32_bf16 v[42:45], v[156:159], v[190:193], v[42:45]
	v_mfma_f32_16x16x32_bf16 v[42:45], v[160:163], v[194:197], v[42:45]
	v_mfma_f32_16x16x32_bf16 v[38:41], v[122:125], v[198:201], v[38:41]
	v_mfma_f32_16x16x32_bf16 v[38:41], v[134:137], v[202:205], v[38:41]
	v_mfma_f32_16x16x32_bf16 v[34:37], v[156:159], v[198:201], v[34:37]
	v_mfma_f32_16x16x32_bf16 v[34:37], v[160:163], v[202:205], v[34:37]
	s_barrier
	s_setprio 0
	s_mov_b32 m0, s15
	s_mov_b32 s42, s78
	s_mov_b32 s43, s79
	ds_read_b128 v[164:167], v211 offset:16384
	ds_read_b128 v[168:171], v211 offset:17408
	ds_read_b128 v[182:185], v211 offset:18432
	ds_read_b128 v[186:189], v211 offset:19456
	ds_read_b128 v[190:193], v211 offset:20480
	ds_read_b128 v[194:197], v211 offset:21504
	ds_read_b128 v[198:201], v211 offset:22528
	ds_read_b128 v[202:205], v211 offset:23552
	buffer_load_dwordx4 v179, s[40:43], s60 offen lds
	s_mov_b32 m0, s16
	s_add_i32 s62, s60, 0x158000
	buffer_load_dwordx4 v207, s[40:43], s60 offen lds
	s_mov_b32 m0, s17
	s_nop 0
	buffer_load_dwordx4 v179, s[40:43], s62 offen lds
	s_mov_b32 m0, s18
	s_nop 0
	buffer_load_dwordx4 v207, s[40:43], s62 offen lds
	s_mov_b32 m0, s14
	s_nop 0
	buffer_load_dwordx4 v178, s[76:79], s61 offen lds
	s_mov_b32 m0, s19
	s_nop 0
	buffer_load_dwordx4 v206, s[76:79], s61 offen lds
	s_waitcnt vmcnt(8)
	s_waitcnt lgkmcnt(0)
	s_setprio 1
	s_barrier
	v_mfma_f32_16x16x32_bf16 v[94:97], v[106:109], v[164:167], v[94:97]
	v_mfma_f32_16x16x32_bf16 v[94:97], v[110:113], v[168:171], v[94:97]
	v_mfma_f32_16x16x32_bf16 v[90:93], v[114:117], v[164:167], v[90:93]
	v_mfma_f32_16x16x32_bf16 v[90:93], v[118:121], v[168:171], v[90:93]
	v_mfma_f32_16x16x32_bf16 v[86:89], v[106:109], v[182:185], v[86:89]
	v_mfma_f32_16x16x32_bf16 v[86:89], v[110:113], v[186:189], v[86:89]
	v_mfma_f32_16x16x32_bf16 v[82:85], v[114:117], v[182:185], v[82:85]
	v_mfma_f32_16x16x32_bf16 v[82:85], v[118:121], v[186:189], v[82:85]
	v_mfma_f32_16x16x32_bf16 v[78:81], v[106:109], v[190:193], v[78:81]
	v_mfma_f32_16x16x32_bf16 v[78:81], v[110:113], v[194:197], v[78:81]
	v_mfma_f32_16x16x32_bf16 v[74:77], v[114:117], v[190:193], v[74:77]
	v_mfma_f32_16x16x32_bf16 v[74:77], v[118:121], v[194:197], v[74:77]
	v_mfma_f32_16x16x32_bf16 v[70:73], v[106:109], v[198:201], v[70:73]
	v_mfma_f32_16x16x32_bf16 v[70:73], v[110:113], v[202:205], v[70:73]
	v_mfma_f32_16x16x32_bf16 v[66:69], v[114:117], v[198:201], v[66:69]
	v_mfma_f32_16x16x32_bf16 v[66:69], v[118:121], v[202:205], v[66:69]
	v_mfma_f32_16x16x32_bf16 v[30:33], v[122:125], v[164:167], v[30:33]
	v_mfma_f32_16x16x32_bf16 v[30:33], v[134:137], v[168:171], v[30:33]
	v_mfma_f32_16x16x32_bf16 v[26:29], v[156:159], v[164:167], v[26:29]
	v_mfma_f32_16x16x32_bf16 v[26:29], v[160:163], v[168:171], v[26:29]
	v_mfma_f32_16x16x32_bf16 v[22:25], v[122:125], v[182:185], v[22:25]
	v_mfma_f32_16x16x32_bf16 v[22:25], v[134:137], v[186:189], v[22:25]
	v_mfma_f32_16x16x32_bf16 v[18:21], v[156:159], v[182:185], v[18:21]
	v_mfma_f32_16x16x32_bf16 v[18:21], v[160:163], v[186:189], v[18:21]
	v_mfma_f32_16x16x32_bf16 v[14:17], v[122:125], v[190:193], v[14:17]
	v_mfma_f32_16x16x32_bf16 v[14:17], v[134:137], v[194:197], v[14:17]
	v_mfma_f32_16x16x32_bf16 v[10:13], v[156:159], v[190:193], v[10:13]
	v_mfma_f32_16x16x32_bf16 v[10:13], v[160:163], v[194:197], v[10:13]
	v_mfma_f32_16x16x32_bf16 v[6:9], v[122:125], v[198:201], v[6:9]
	v_mfma_f32_16x16x32_bf16 v[6:9], v[134:137], v[202:205], v[6:9]
	v_mfma_f32_16x16x32_bf16 v[2:5], v[156:159], v[198:201], v[2:5]
	v_mfma_f32_16x16x32_bf16 v[2:5], v[160:163], v[202:205], v[2:5]
	s_barrier
; #define PG8_STAGEX(rs, bufoff, soff, voff) do { _Pragma("unroll") for (int _i = 0; _i < 2; ++_i) \
;         __builtin_amdgcn_raw_ptr_buffer_load_lds(rs, (LAS unsigned*)(lds + (bufoff) + ldsw + _i * 8192), 16, (voff)[_i], (soff), 0, 0); } while (0)
; #define PG8_LDA(dst, b, h) do { _Pragma("unroll") for (int m = 0; m < 4; ++m) _Pragma("unroll") for (int k = 0; k < 2; ++k) dst[m][k] = *(const LAS bf16x8*)(lds + PG8_SA(b, h) + aoff + m * 2048 + k * 1024); } while (0)
; #define PG8_LDB(dst, b, h) do { _Pragma("unroll") for (int n = 0; n < 2; ++n) _Pragma("unroll") for (int k = 0; k < 2; ++k) dst[n][k] = *(const LAS bf16x8*)(lds + PG8_SB(b, h) + boff + n * 2048 + k * 1024); } while (0)
; #define PG8_WAIT_V(n) asm volatile("s_waitcnt vmcnt(" #n ")" ::: "memory")
; #define PG8_WAIT_L(n) asm volatile("s_waitcnt lgkmcnt(" #n ")" ::: "memory")
; #define PG8_BAR __builtin_amdgcn_s_barrier()
; #define PG8_SCHED __builtin_amdgcn_sched_barrier(0)
;     ...
;             PG8_LDB(B0, 1, 0); PG8_LDB(B1, 1, 1); PG8_SCHED; PG8_LDA(At, 1, 0); PG8_STAGEX(rsA, PG8_SA(0, 1), a2 + hstepA, voffA);
;             PG8_WAIT_V(8); PG8_WAIT_L(0); PG8_BAR; PG8_MMA(0, 0, At, B0); PG8_MMA(0, 1, At, B1); PG8_BAR; PG8_SCHED;
;             PG8_LDA(At, 1, 1); PG8_STAGEX(rsB, PG8_SB(1, 0), b3, voffB); PG8_STAGEX(rsB, PG8_SB(1, 1), b3 + hstepB, voffB); PG8_STAGEX(rsA, PG8_SA(1, 0), a3, voffA);
;             PG8_WAIT_V(8); PG8_WAIT_L(0); PG8_BAR; PG8_MMA(1, 0, At, B0); PG8_MMA(1, 1, At, B1); PG8_BAR; PG8_SCHED;
;         }
	s_setprio 0
	v_add_u32_e32 v118, 0x18000, v210
	v_add_u32_e32 v160, 0x1c000, v210
	ds_read_b128 v[106:109], v118
	ds_read_b128 v[110:113], v118 offset:1024
	ds_read_b128 v[114:117], v118 offset:2048
	ds_read_b128 v[118:121], v118 offset:3072
	ds_read_b128 v[122:125], v160
	ds_read_b128 v[134:137], v160 offset:1024
	ds_read_b128 v[156:159], v160 offset:2048
	ds_read_b128 v[160:163], v160 offset:3072
	s_add_i32 s61, s61, 0x158000
	s_mov_b32 m0, s20
	ds_read_b128 v[164:167], v211 offset:32768
	ds_read_b128 v[168:171], v211 offset:33792
	ds_read_b128 v[182:185], v211 offset:34816
	ds_read_b128 v[186:189], v211 offset:35840
	ds_read_b128 v[190:193], v211 offset:36864
	ds_read_b128 v[194:197], v211 offset:37888
	ds_read_b128 v[198:201], v211 offset:38912
	ds_read_b128 v[202:205], v211 offset:39936
	buffer_load_dwordx4 v178, s[76:79], s61 offen lds
	s_mov_b32 m0, s21
	s_nop 0
	buffer_load_dwordx4 v206, s[76:79], s61 offen lds
	s_waitcnt vmcnt(8)
	s_waitcnt lgkmcnt(0)
	s_setprio 1
	s_barrier
	v_mfma_f32_16x16x32_bf16 v[150:153], v[106:109], v[164:167], v[150:153]
	v_mfma_f32_16x16x32_bf16 v[150:153], v[110:113], v[168:171], v[150:153]
	v_mfma_f32_16x16x32_bf16 v[146:149], v[114:117], v[164:167], v[146:149]
	v_mfma_f32_16x16x32_bf16 v[146:149], v[118:121], v[168:171], v[146:149]
	v_mfma_f32_16x16x32_bf16 v[142:145], v[106:109], v[182:185], v[142:145]
	v_mfma_f32_16x16x32_bf16 v[142:145], v[110:113], v[186:189], v[142:145]
	v_mfma_f32_16x16x32_bf16 v[138:141], v[114:117], v[182:185], v[138:141]
	v_mfma_f32_16x16x32_bf16 v[138:141], v[118:121], v[186:189], v[138:141]
	v_mfma_f32_16x16x32_bf16 v[130:133], v[106:109], v[190:193], v[130:133]
	v_mfma_f32_16x16x32_bf16 v[130:133], v[110:113], v[194:197], v[130:133]
	v_mfma_f32_16x16x32_bf16 v[126:129], v[114:117], v[190:193], v[126:129]
	v_mfma_f32_16x16x32_bf16 v[126:129], v[118:121], v[194:197], v[126:129]
	v_mfma_f32_16x16x32_bf16 v[102:105], v[106:109], v[198:201], v[102:105]
	v_mfma_f32_16x16x32_bf16 v[102:105], v[110:113], v[202:205], v[102:105]
	v_mfma_f32_16x16x32_bf16 v[98:101], v[114:117], v[198:201], v[98:101]
	v_mfma_f32_16x16x32_bf16 v[98:101], v[118:121], v[202:205], v[98:101]
	v_mfma_f32_16x16x32_bf16 v[62:65], v[122:125], v[164:167], v[62:65]
	v_mfma_f32_16x16x32_bf16 v[62:65], v[134:137], v[168:171], v[62:65]
	v_mfma_f32_16x16x32_bf16 v[58:61], v[156:159], v[164:167], v[58:61]
	v_mfma_f32_16x16x32_bf16 v[58:61], v[160:163], v[168:171], v[58:61]
	v_mfma_f32_16x16x32_bf16 v[54:57], v[122:125], v[182:185], v[54:57]
	v_mfma_f32_16x16x32_bf16 v[54:57], v[134:137], v[186:189], v[54:57]
	v_mfma_f32_16x16x32_bf16 v[50:53], v[156:159], v[182:185], v[50:53]
	v_mfma_f32_16x16x32_bf16 v[50:53], v[160:163], v[186:189], v[50:53]
	v_mfma_f32_16x16x32_bf16 v[46:49], v[122:125], v[190:193], v[46:49]
	v_mfma_f32_16x16x32_bf16 v[46:49], v[134:137], v[194:197], v[46:49]
	v_mfma_f32_16x16x32_bf16 v[42:45], v[156:159], v[190:193], v[42:45]
	v_mfma_f32_16x16x32_bf16 v[42:45], v[160:163], v[194:197], v[42:45]
	v_mfma_f32_16x16x32_bf16 v[38:41], v[122:125], v[198:201], v[38:41]
	v_mfma_f32_16x16x32_bf16 v[38:41], v[134:137], v[202:205], v[38:41]
	v_mfma_f32_16x16x32_bf16 v[34:37], v[156:159], v[198:201], v[34:37]
	v_mfma_f32_16x16x32_bf16 v[34:37], v[160:163], v[202:205], v[34:37]
	s_barrier
	s_setprio 0
	s_mov_b32 m0, s28
	s_or_b32 s61, s60, 0x80
	ds_read_b128 v[164:167], v211 offset:49152
	ds_read_b128 v[168:171], v211 offset:50176
	ds_read_b128 v[182:185], v211 offset:51200
	ds_read_b128 v[186:189], v211 offset:52224
	ds_read_b128 v[190:193], v211 offset:53248
	ds_read_b128 v[194:197], v211 offset:54272
	ds_read_b128 v[198:201], v211 offset:55296
	ds_read_b128 v[202:205], v211 offset:56320
	buffer_load_dwordx4 v179, s[40:43], s61 offen lds
	s_mov_b32 m0, s29
	s_add_i32 s60, s60, 0x158080
	buffer_load_dwordx4 v207, s[40:43], s61 offen lds
	s_mov_b32 m0, s66
	s_nop 0
	buffer_load_dwordx4 v179, s[40:43], s60 offen lds
	s_mov_b32 m0, s67
	s_nop 0
	buffer_load_dwordx4 v207, s[40:43], s60 offen lds
	s_mov_b32 m0, s54
	s_nop 0
	buffer_load_dwordx4 v178, s[76:79], s59 offen lds
	s_mov_b32 m0, s55
	s_nop 0
	buffer_load_dwordx4 v206, s[76:79], s59 offen lds
	s_waitcnt vmcnt(8)
	s_waitcnt lgkmcnt(0)
	s_setprio 1
	s_barrier
	v_mfma_f32_16x16x32_bf16 v[94:97], v[106:109], v[164:167], v[94:97]
	v_mfma_f32_16x16x32_bf16 v[94:97], v[110:113], v[168:171], v[94:97]
	v_mfma_f32_16x16x32_bf16 v[90:93], v[114:117], v[164:167], v[90:93]
	v_mfma_f32_16x16x32_bf16 v[90:93], v[118:121], v[168:171], v[90:93]
	v_mfma_f32_16x16x32_bf16 v[86:89], v[106:109], v[182:185], v[86:89]
	v_mfma_f32_16x16x32_bf16 v[86:89], v[110:113], v[186:189], v[86:89]
	v_mfma_f32_16x16x32_bf16 v[82:85], v[114:117], v[182:185], v[82:85]
	v_mfma_f32_16x16x32_bf16 v[82:85], v[118:121], v[186:189], v[82:85]
	v_mfma_f32_16x16x32_bf16 v[78:81], v[106:109], v[190:193], v[78:81]
	v_mfma_f32_16x16x32_bf16 v[78:81], v[110:113], v[194:197], v[78:81]
	v_mfma_f32_16x16x32_bf16 v[74:77], v[114:117], v[190:193], v[74:77]
	v_mfma_f32_16x16x32_bf16 v[74:77], v[118:121], v[194:197], v[74:77]
	v_mfma_f32_16x16x32_bf16 v[70:73], v[106:109], v[198:201], v[70:73]
	v_mfma_f32_16x16x32_bf16 v[70:73], v[110:113], v[202:205], v[70:73]
	v_mfma_f32_16x16x32_bf16 v[66:69], v[114:117], v[198:201], v[66:69]
	v_mfma_f32_16x16x32_bf16 v[66:69], v[118:121], v[202:205], v[66:69]
	v_mfma_f32_16x16x32_bf16 v[30:33], v[122:125], v[164:167], v[30:33]
	v_mfma_f32_16x16x32_bf16 v[30:33], v[134:137], v[168:171], v[30:33]
	v_mfma_f32_16x16x32_bf16 v[26:29], v[156:159], v[164:167], v[26:29]
	v_mfma_f32_16x16x32_bf16 v[26:29], v[160:163], v[168:171], v[26:29]
	v_mfma_f32_16x16x32_bf16 v[22:25], v[122:125], v[182:185], v[22:25]
	v_mfma_f32_16x16x32_bf16 v[22:25], v[134:137], v[186:189], v[22:25]
	v_mfma_f32_16x16x32_bf16 v[18:21], v[156:159], v[182:185], v[18:21]
	v_mfma_f32_16x16x32_bf16 v[18:21], v[160:163], v[186:189], v[18:21]
	v_mfma_f32_16x16x32_bf16 v[14:17], v[122:125], v[190:193], v[14:17]
	v_mfma_f32_16x16x32_bf16 v[14:17], v[134:137], v[194:197], v[14:17]
	v_mfma_f32_16x16x32_bf16 v[10:13], v[156:159], v[190:193], v[10:13]
	v_mfma_f32_16x16x32_bf16 v[10:13], v[160:163], v[194:197], v[10:13]
	v_mfma_f32_16x16x32_bf16 v[6:9], v[122:125], v[198:201], v[6:9]
	v_mfma_f32_16x16x32_bf16 v[6:9], v[134:137], v[202:205], v[6:9]
	v_mfma_f32_16x16x32_bf16 v[2:5], v[156:159], v[198:201], v[2:5]
	v_mfma_f32_16x16x32_bf16 v[2:5], v[160:163], v[202:205], v[2:5]
	s_barrier
	s_setprio 0
	s_add_i32 s58, s58, 2
	s_addk_i32 s51, 0x100
	s_addk_i32 s57, 0x100
	s_cmpk_gt_u32 s58, 0x53
	s_cbranch_scc0 .LBB0_323
	s_and_b64 vcc, exec, s[48:49]
	s_cbranch_vccz .LBB0_326
	s_barrier

; #define PG8_STAGEX(rs, bufoff, soff, voff) do { _Pragma("unroll") for (int _i = 0; _i < 2; ++_i) \
;         __builtin_amdgcn_raw_ptr_buffer_load_lds(rs, (LAS unsigned*)(lds + (bufoff) + ldsw + _i * 8192), 16, (voff)[_i], (soff), 0, 0); } while (0)
; #define PG8_LDA(dst, b, h) do { _Pragma("unroll") for (int m = 0; m < 4; ++m) _Pragma("unroll") for (int k = 0; k < 2; ++k) dst[m][k] = *(const LAS bf16x8*)(lds + PG8_SA(b, h) + aoff + m * 2048 + k * 1024); } while (0)
; #define PG8_LDB(dst, b, h) do { _Pragma("unroll") for (int n = 0; n < 2; ++n) _Pragma("unroll") for (int k = 0; k < 2; ++k) dst[n][k] = *(const LAS bf16x8*)(lds + PG8_SB(b, h) + boff + n * 2048 + k * 1024); } while (0)
; #define PG8_WAIT_V(n) asm volatile("s_waitcnt vmcnt(" #n ")" ::: "memory")
; #define PG8_WAIT_L(n) asm volatile("s_waitcnt lgkmcnt(" #n ")" ::: "memory")
; #define PG8_BAR __builtin_amdgcn_s_barrier()
; #define PG8_SCHED __builtin_amdgcn_sched_barrier(0)
;     ...
;                 if (w0) { PG8_LDB(B0, 0, 0); PG8_LDB(B1, 0, 1); PG8_SCHED; PG8_LDA(At, 0, 0); }
;                 PG8_WAIT_L(0); PG8_BAR; if (w0) { PG8_MMA(0, 0, At, B0); PG8_MMA(0, 1, At, B1); } PG8_BAR; PG8_SCHED;
;                 PG8_STAGEX(rsB, PG8_SB(0, 0), b2, voffB); PG8_STAGEX(rsB, PG8_SB(0, 1), b2 + hstepB, voffB); PG8_STAGEX(rsA, PG8_SA(0, 0), a2, voffA);
;                 PG8_WAIT_V(6); PG8_BAR; PG8_BAR; PG8_SCHED;
;                 if (w0) { PG8_LDB(B0, 1, 0); PG8_LDB(B1, 1, 1); PG8_SCHED; PG8_LDA(At, 1, 0); }
;                 PG8_WAIT_L(0); PG8_BAR; if (w0) { PG8_MMA(0, 0, At, B0); PG8_MMA(0, 1, At, B1); } PG8_BAR; PG8_SCHED;
.LBB0_355:
	s_waitcnt lgkmcnt(0)
	s_and_b64 vcc, exec, s[38:39]
	s_barrier
	s_cbranch_vccnz .LBB0_357
	s_setprio 1
	s_waitcnt lgkmcnt(7)
	v_mfma_f32_16x16x32_bf16 v[62:65], v[66:69], v[98:101], v[62:65]
	v_mfma_f32_16x16x32_bf16 v[62:65], v[70:73], v[102:105], v[62:65]
	v_mfma_f32_16x16x32_bf16 v[58:61], v[74:77], v[98:101], v[58:61]
	v_mfma_f32_16x16x32_bf16 v[58:61], v[78:81], v[102:105], v[58:61]
	v_mfma_f32_16x16x32_bf16 v[54:57], v[66:69], v[106:109], v[54:57]
	v_mfma_f32_16x16x32_bf16 v[54:57], v[70:73], v[110:113], v[54:57]
	v_mfma_f32_16x16x32_bf16 v[50:53], v[74:77], v[106:109], v[50:53]
	v_mfma_f32_16x16x32_bf16 v[50:53], v[78:81], v[110:113], v[50:53]
	v_mfma_f32_16x16x32_bf16 v[46:49], v[66:69], v[114:117], v[46:49]
	v_mfma_f32_16x16x32_bf16 v[46:49], v[70:73], v[118:121], v[46:49]
	v_mfma_f32_16x16x32_bf16 v[42:45], v[74:77], v[114:117], v[42:45]
	v_mfma_f32_16x16x32_bf16 v[42:45], v[78:81], v[118:121], v[42:45]
	v_mfma_f32_16x16x32_bf16 v[38:41], v[66:69], v[122:125], v[38:41]
	v_mfma_f32_16x16x32_bf16 v[38:41], v[70:73], v[126:129], v[38:41]
	v_mfma_f32_16x16x32_bf16 v[34:37], v[74:77], v[122:125], v[34:37]
	v_mfma_f32_16x16x32_bf16 v[34:37], v[78:81], v[126:129], v[34:37]
	v_mfma_f32_16x16x32_bf16 v[30:33], v[82:85], v[98:101], v[30:33]
	v_mfma_f32_16x16x32_bf16 v[30:33], v[86:89], v[102:105], v[30:33]
	v_mfma_f32_16x16x32_bf16 v[26:29], v[90:93], v[98:101], v[26:29]
	v_mfma_f32_16x16x32_bf16 v[26:29], v[94:97], v[102:105], v[26:29]
	v_mfma_f32_16x16x32_bf16 v[22:25], v[82:85], v[106:109], v[22:25]
	v_mfma_f32_16x16x32_bf16 v[22:25], v[86:89], v[110:113], v[22:25]
	v_mfma_f32_16x16x32_bf16 v[18:21], v[90:93], v[106:109], v[18:21]
	v_mfma_f32_16x16x32_bf16 v[18:21], v[94:97], v[110:113], v[18:21]
	v_mfma_f32_16x16x32_bf16 v[14:17], v[82:85], v[114:117], v[14:17]
	v_mfma_f32_16x16x32_bf16 v[14:17], v[86:89], v[118:121], v[14:17]
	v_mfma_f32_16x16x32_bf16 v[10:13], v[90:93], v[114:117], v[10:13]
	v_mfma_f32_16x16x32_bf16 v[10:13], v[94:97], v[118:121], v[10:13]
	v_mfma_f32_16x16x32_bf16 v[6:9], v[82:85], v[122:125], v[6:9]
	v_mfma_f32_16x16x32_bf16 v[6:9], v[86:89], v[126:129], v[6:9]
	v_mfma_f32_16x16x32_bf16 v[2:5], v[90:93], v[122:125], v[2:5]
	v_mfma_f32_16x16x32_bf16 v[2:5], v[94:97], v[126:129], v[2:5]
	s_setprio 0

; #define PG8_STAGEX(rs, bufoff, soff, voff) do { _Pragma("unroll") for (int _i = 0; _i < 2; ++_i) \
;         __builtin_amdgcn_raw_ptr_buffer_load_lds(rs, (LAS unsigned*)(lds + (bufoff) + ldsw + _i * 8192), 16, (voff)[_i], (soff), 0, 0); } while (0)
; #define PG8_LDA(dst, b, h) do { _Pragma("unroll") for (int m = 0; m < 4; ++m) _Pragma("unroll") for (int k = 0; k < 2; ++k) dst[m][k] = *(const LAS bf16x8*)(lds + PG8_SA(b, h) + aoff + m * 2048 + k * 1024); } while (0)
; #define PG8_LDB(dst, b, h) do { _Pragma("unroll") for (int n = 0; n < 2; ++n) _Pragma("unroll") for (int k = 0; k < 2; ++k) dst[n][k] = *(const LAS bf16x8*)(lds + PG8_SB(b, h) + boff + n * 2048 + k * 1024); } while (0)
; #define PG8_WAIT_V(n) asm volatile("s_waitcnt vmcnt(" #n ")" ::: "memory")
; #define PG8_WAIT_L(n) asm volatile("s_waitcnt lgkmcnt(" #n ")" ::: "memory")
; #define PG8_BAR __builtin_amdgcn_s_barrier()
; #define PG8_SCHED __builtin_amdgcn_sched_barrier(0)
;     ...
;                 if (w0) { PG8_LDB(B0, 1, 0); PG8_LDB(B1, 1, 1); PG8_SCHED; PG8_LDA(At, 1, 0); }
;                 PG8_WAIT_L(0); PG8_BAR; if (w0) { PG8_MMA(0, 0, At, B0); PG8_MMA(0, 1, At, B1); } PG8_BAR; PG8_SCHED;
;                 PG8_STAGEX(rsB, PG8_SB(1, 0), b3, voffB); PG8_STAGEX(rsB, PG8_SB(1, 1), b3 + hstepB, voffB); PG8_STAGEX(rsA, PG8_SA(1, 0), a3, voffA);
;                 PG8_WAIT_V(6); PG8_BAR; PG8_BAR; PG8_SCHED;
;             }
.LBB0_359:
	s_waitcnt lgkmcnt(0)
	s_and_b64 vcc, exec, s[38:39]
	s_barrier
	s_cbranch_vccnz .LBB0_352
	s_setprio 1
	s_waitcnt lgkmcnt(7)
	v_mfma_f32_16x16x32_bf16 v[62:65], v[66:69], v[98:101], v[62:65]
	v_mfma_f32_16x16x32_bf16 v[62:65], v[70:73], v[102:105], v[62:65]
	v_mfma_f32_16x16x32_bf16 v[58:61], v[74:77], v[98:101], v[58:61]
	v_mfma_f32_16x16x32_bf16 v[58:61], v[78:81], v[102:105], v[58:61]
	v_mfma_f32_16x16x32_bf16 v[54:57], v[66:69], v[106:109], v[54:57]
	v_mfma_f32_16x16x32_bf16 v[54:57], v[70:73], v[110:113], v[54:57]
	v_mfma_f32_16x16x32_bf16 v[50:53], v[74:77], v[106:109], v[50:53]
	v_mfma_f32_16x16x32_bf16 v[50:53], v[78:81], v[110:113], v[50:53]
	v_mfma_f32_16x16x32_bf16 v[46:49], v[66:69], v[114:117], v[46:49]
	v_mfma_f32_16x16x32_bf16 v[46:49], v[70:73], v[118:121], v[46:49]
	v_mfma_f32_16x16x32_bf16 v[42:45], v[74:77], v[114:117], v[42:45]
	v_mfma_f32_16x16x32_bf16 v[42:45], v[78:81], v[118:121], v[42:45]
	v_mfma_f32_16x16x32_bf16 v[38:41], v[66:69], v[122:125], v[38:41]
	v_mfma_f32_16x16x32_bf16 v[38:41], v[70:73], v[126:129], v[38:41]
	v_mfma_f32_16x16x32_bf16 v[34:37], v[74:77], v[122:125], v[34:37]
	v_mfma_f32_16x16x32_bf16 v[34:37], v[78:81], v[126:129], v[34:37]
	v_mfma_f32_16x16x32_bf16 v[30:33], v[82:85], v[98:101], v[30:33]
	v_mfma_f32_16x16x32_bf16 v[30:33], v[86:89], v[102:105], v[30:33]
	v_mfma_f32_16x16x32_bf16 v[26:29], v[90:93], v[98:101], v[26:29]
	v_mfma_f32_16x16x32_bf16 v[26:29], v[94:97], v[102:105], v[26:29]
	v_mfma_f32_16x16x32_bf16 v[22:25], v[82:85], v[106:109], v[22:25]
	v_mfma_f32_16x16x32_bf16 v[22:25], v[86:89], v[110:113], v[22:25]
	v_mfma_f32_16x16x32_bf16 v[18:21], v[90:93], v[106:109], v[18:21]
	v_mfma_f32_16x16x32_bf16 v[18:21], v[94:97], v[110:113], v[18:21]
	v_mfma_f32_16x16x32_bf16 v[14:17], v[82:85], v[114:117], v[14:17]
	v_mfma_f32_16x16x32_bf16 v[14:17], v[86:89], v[118:121], v[14:17]
	v_mfma_f32_16x16x32_bf16 v[10:13], v[90:93], v[114:117], v[10:13]
	v_mfma_f32_16x16x32_bf16 v[10:13], v[94:97], v[118:121], v[10:13]
	v_mfma_f32_16x16x32_bf16 v[6:9], v[82:85], v[122:125], v[6:9]
	v_mfma_f32_16x16x32_bf16 v[6:9], v[86:89], v[126:129], v[6:9]
	v_mfma_f32_16x16x32_bf16 v[2:5], v[90:93], v[122:125], v[2:5]
	v_mfma_f32_16x16x32_bf16 v[2:5], v[94:97], v[126:129], v[2:5]
	s_setprio 0
	s_branch .LBB0_352

; #define PG8_STAGEX(rs, bufoff, soff, voff) do { _Pragma("unroll") for (int _i = 0; _i < 2; ++_i) \
;         __builtin_amdgcn_raw_ptr_buffer_load_lds(rs, (LAS unsigned*)(lds + (bufoff) + ldsw + _i * 8192), 16, (voff)[_i], (soff), 0, 0); } while (0)
; #define PG8_LDA(dst, b, h) do { _Pragma("unroll") for (int m = 0; m < 4; ++m) _Pragma("unroll") for (int k = 0; k < 2; ++k) dst[m][k] = *(const LAS bf16x8*)(lds + PG8_SA(b, h) + aoff + m * 2048 + k * 1024); } while (0)
; #define PG8_LDB(dst, b, h) do { _Pragma("unroll") for (int n = 0; n < 2; ++n) _Pragma("unroll") for (int k = 0; k < 2; ++k) dst[n][k] = *(const LAS bf16x8*)(lds + PG8_SB(b, h) + boff + n * 2048 + k * 1024); } while (0)
; #define PG8_WAIT_V(n) asm volatile("s_waitcnt vmcnt(" #n ")" ::: "memory")
; #define PG8_WAIT_L(n) asm volatile("s_waitcnt lgkmcnt(" #n ")" ::: "memory")
; #define PG8_BAR __builtin_amdgcn_s_barrier()
; #define PG8_SCHED __builtin_amdgcn_sched_barrier(0)
;     ...
;             PG8_LDB(B0, 0, 0); PG8_LDB(B1, 0, 1); PG8_SCHED; PG8_LDA(At, 0, 0); PG8_STAGEX(rsA, PG8_SA(1, 1), a1 + hstepA, voffA);
;             PG8_WAIT_V(8); PG8_WAIT_L(0); PG8_BAR; PG8_MMA(0, 0, At, B0); PG8_MMA(0, 1, At, B1); PG8_BAR; PG8_SCHED;
;             PG8_LDA(At, 0, 1); PG8_STAGEX(rsB, PG8_SB(0, 0), b2, voffB); PG8_STAGEX(rsB, PG8_SB(0, 1), b2 + hstepB, voffB); PG8_STAGEX(rsA, PG8_SA(0, 0), a2, voffA);
;             PG8_WAIT_V(8); PG8_WAIT_L(0); PG8_BAR; PG8_MMA(1, 0, At, B0); PG8_MMA(1, 1, At, B1); PG8_BAR; PG8_SCHED;
.LBB0_437:
	v_add_u32_e32 v142, 0x10000, v220
	v_add_u32_e32 v158, 0x14000, v220
	ds_read_b128 v[130:133], v142
	ds_read_b128 v[134:137], v142 offset:1024
	ds_read_b128 v[138:141], v142 offset:2048
	ds_read_b128 v[142:145], v142 offset:3072
	ds_read_b128 v[146:149], v158
	ds_read_b128 v[150:153], v158 offset:1024
	ds_read_b128 v[154:157], v158 offset:2048
	ds_read_b128 v[158:161], v158 offset:3072
	s_add_i32 s30, s7, 0xfff80080
	s_cmp_eq_u32 s29, 28
	s_cselect_b32 s50, s2, s30
	s_cselect_b32 s31, s5, s28
	s_or_b32 s30, s50, 0x80
	s_mov_b32 m0, s20
	ds_read_b128 v[162:165], v221
	ds_read_b128 v[170:173], v221 offset:1024
	ds_read_b128 v[182:185], v221 offset:2048
	ds_read_b128 v[186:189], v221 offset:3072
	ds_read_b128 v[190:193], v221 offset:4096
	ds_read_b128 v[194:197], v221 offset:5120
	ds_read_b128 v[198:201], v221 offset:6144
	ds_read_b128 v[202:205], v221 offset:7168
	buffer_load_dwordx4 v178, s[76:79], s7 offen lds
	s_mov_b32 m0, s22
	s_nop 0
	buffer_load_dwordx4 v210, s[76:79], s7 offen lds
	s_waitcnt vmcnt(8)
	s_waitcnt lgkmcnt(0)
	s_setprio 1
	s_barrier
	v_mfma_f32_16x16x32_bf16 v[126:129], v[130:133], v[162:165], v[126:129]
	v_mfma_f32_16x16x32_bf16 v[126:129], v[134:137], v[170:173], v[126:129]
	v_mfma_f32_16x16x32_bf16 v[110:113], v[138:141], v[162:165], v[110:113]
	v_mfma_f32_16x16x32_bf16 v[110:113], v[142:145], v[170:173], v[110:113]
	v_mfma_f32_16x16x32_bf16 v[118:121], v[130:133], v[182:185], v[118:121]
	v_mfma_f32_16x16x32_bf16 v[118:121], v[134:137], v[186:189], v[118:121]
	v_mfma_f32_16x16x32_bf16 v[102:105], v[138:141], v[182:185], v[102:105]
	v_mfma_f32_16x16x32_bf16 v[102:105], v[142:145], v[186:189], v[102:105]
	v_mfma_f32_16x16x32_bf16 v[114:117], v[130:133], v[190:193], v[114:117]
	v_mfma_f32_16x16x32_bf16 v[114:117], v[134:137], v[194:197], v[114:117]
	v_mfma_f32_16x16x32_bf16 v[98:101], v[138:141], v[190:193], v[98:101]
	v_mfma_f32_16x16x32_bf16 v[98:101], v[142:145], v[194:197], v[98:101]
	v_mfma_f32_16x16x32_bf16 v[122:125], v[130:133], v[198:201], v[122:125]
	v_mfma_f32_16x16x32_bf16 v[122:125], v[134:137], v[202:205], v[122:125]
	v_mfma_f32_16x16x32_bf16 v[106:109], v[138:141], v[198:201], v[106:109]
	v_mfma_f32_16x16x32_bf16 v[106:109], v[142:145], v[202:205], v[106:109]
	v_mfma_f32_16x16x32_bf16 v[62:65], v[146:149], v[162:165], v[62:65]
	v_mfma_f32_16x16x32_bf16 v[62:65], v[150:153], v[170:173], v[62:65]
	v_mfma_f32_16x16x32_bf16 v[46:49], v[154:157], v[162:165], v[46:49]
	v_mfma_f32_16x16x32_bf16 v[46:49], v[158:161], v[170:173], v[46:49]
	v_mfma_f32_16x16x32_bf16 v[54:57], v[146:149], v[182:185], v[54:57]
	v_mfma_f32_16x16x32_bf16 v[54:57], v[150:153], v[186:189], v[54:57]
	v_mfma_f32_16x16x32_bf16 v[38:41], v[154:157], v[182:185], v[38:41]
	v_mfma_f32_16x16x32_bf16 v[38:41], v[158:161], v[186:189], v[38:41]
	v_mfma_f32_16x16x32_bf16 v[50:53], v[146:149], v[190:193], v[50:53]
	v_mfma_f32_16x16x32_bf16 v[50:53], v[150:153], v[194:197], v[50:53]
	v_mfma_f32_16x16x32_bf16 v[34:37], v[154:157], v[190:193], v[34:37]
	v_mfma_f32_16x16x32_bf16 v[34:37], v[158:161], v[194:197], v[34:37]
	v_mfma_f32_16x16x32_bf16 v[58:61], v[146:149], v[198:201], v[58:61]
	v_mfma_f32_16x16x32_bf16 v[58:61], v[150:153], v[202:205], v[58:61]
	v_mfma_f32_16x16x32_bf16 v[42:45], v[154:157], v[198:201], v[42:45]
	v_mfma_f32_16x16x32_bf16 v[42:45], v[158:161], v[202:205], v[42:45]
	s_barrier
	s_setprio 0
	s_mov_b32 m0, s90
	s_mov_b32 s58, s78
	s_mov_b32 s59, s79
	ds_read_b128 v[162:165], v221 offset:16384
	ds_read_b128 v[170:173], v221 offset:17408
	ds_read_b128 v[182:185], v221 offset:18432
	ds_read_b128 v[186:189], v221 offset:19456
	ds_read_b128 v[190:193], v221 offset:20480
	ds_read_b128 v[194:197], v221 offset:21504
	ds_read_b128 v[198:201], v221 offset:22528
	ds_read_b128 v[202:205], v221 offset:23552
	buffer_load_dwordx4 v179, s[56:59], s31 offen lds
	s_mov_b32 m0, s91
	s_add_i32 s51, s31, 0x80000
	buffer_load_dwordx4 v211, s[56:59], s31 offen lds
	s_mov_b32 m0, s9
	s_nop 0
	buffer_load_dwordx4 v179, s[56:59], s51 offen lds
	s_mov_b32 m0, s10
	s_nop 0
	buffer_load_dwordx4 v211, s[56:59], s51 offen lds
	s_mov_b32 m0, s89
	s_nop 0
	buffer_load_dwordx4 v178, s[76:79], s50 offen lds
	s_mov_b32 m0, s11
	s_nop 0
	buffer_load_dwordx4 v210, s[76:79], s50 offen lds
	s_waitcnt vmcnt(8)
	s_waitcnt lgkmcnt(0)
	s_setprio 1
	s_barrier
	v_mfma_f32_16x16x32_bf16 v[94:97], v[130:133], v[162:165], v[94:97]
	v_mfma_f32_16x16x32_bf16 v[94:97], v[134:137], v[170:173], v[94:97]
	v_mfma_f32_16x16x32_bf16 v[78:81], v[138:141], v[162:165], v[78:81]
	v_mfma_f32_16x16x32_bf16 v[78:81], v[142:145], v[170:173], v[78:81]
	v_mfma_f32_16x16x32_bf16 v[86:89], v[130:133], v[182:185], v[86:89]
	v_mfma_f32_16x16x32_bf16 v[86:89], v[134:137], v[186:189], v[86:89]
	v_mfma_f32_16x16x32_bf16 v[70:73], v[138:141], v[182:185], v[70:73]
	v_mfma_f32_16x16x32_bf16 v[70:73], v[142:145], v[186:189], v[70:73]
	v_mfma_f32_16x16x32_bf16 v[82:85], v[130:133], v[190:193], v[82:85]
	v_mfma_f32_16x16x32_bf16 v[82:85], v[134:137], v[194:197], v[82:85]
	v_mfma_f32_16x16x32_bf16 v[66:69], v[138:141], v[190:193], v[66:69]
	v_mfma_f32_16x16x32_bf16 v[66:69], v[142:145], v[194:197], v[66:69]
	v_mfma_f32_16x16x32_bf16 v[90:93], v[130:133], v[198:201], v[90:93]
	v_mfma_f32_16x16x32_bf16 v[90:93], v[134:137], v[202:205], v[90:93]
	v_mfma_f32_16x16x32_bf16 v[74:77], v[138:141], v[198:201], v[74:77]
	v_mfma_f32_16x16x32_bf16 v[74:77], v[142:145], v[202:205], v[74:77]
	v_mfma_f32_16x16x32_bf16 v[30:33], v[146:149], v[162:165], v[30:33]
	v_mfma_f32_16x16x32_bf16 v[30:33], v[150:153], v[170:173], v[30:33]
	v_mfma_f32_16x16x32_bf16 v[14:17], v[154:157], v[162:165], v[14:17]
	v_mfma_f32_16x16x32_bf16 v[14:17], v[158:161], v[170:173], v[14:17]
	v_mfma_f32_16x16x32_bf16 v[22:25], v[146:149], v[182:185], v[22:25]
	v_mfma_f32_16x16x32_bf16 v[22:25], v[150:153], v[186:189], v[22:25]
	v_mfma_f32_16x16x32_bf16 v[10:13], v[154:157], v[182:185], v[10:13]
	v_mfma_f32_16x16x32_bf16 v[10:13], v[158:161], v[186:189], v[10:13]
	v_mfma_f32_16x16x32_bf16 v[18:21], v[146:149], v[190:193], v[18:21]
	v_mfma_f32_16x16x32_bf16 v[18:21], v[150:153], v[194:197], v[18:21]
	v_mfma_f32_16x16x32_bf16 v[2:5], v[154:157], v[190:193], v[2:5]
	v_mfma_f32_16x16x32_bf16 v[2:5], v[158:161], v[194:197], v[2:5]
	v_mfma_f32_16x16x32_bf16 v[26:29], v[146:149], v[198:201], v[26:29]
	v_mfma_f32_16x16x32_bf16 v[26:29], v[150:153], v[202:205], v[26:29]
	v_mfma_f32_16x16x32_bf16 v[6:9], v[154:157], v[198:201], v[6:9]
	v_mfma_f32_16x16x32_bf16 v[6:9], v[158:161], v[202:205], v[6:9]
	s_barrier
; #define PG8_STAGEX(rs, bufoff, soff, voff) do { _Pragma("unroll") for (int _i = 0; _i < 2; ++_i) \
;         __builtin_amdgcn_raw_ptr_buffer_load_lds(rs, (LAS unsigned*)(lds + (bufoff) + ldsw + _i * 8192), 16, (voff)[_i], (soff), 0, 0); } while (0)
; #define PG8_LDA(dst, b, h) do { _Pragma("unroll") for (int m = 0; m < 4; ++m) _Pragma("unroll") for (int k = 0; k < 2; ++k) dst[m][k] = *(const LAS bf16x8*)(lds + PG8_SA(b, h) + aoff + m * 2048 + k * 1024); } while (0)
; #define PG8_LDB(dst, b, h) do { _Pragma("unroll") for (int n = 0; n < 2; ++n) _Pragma("unroll") for (int k = 0; k < 2; ++k) dst[n][k] = *(const LAS bf16x8*)(lds + PG8_SB(b, h) + boff + n * 2048 + k * 1024); } while (0)
; #define PG8_WAIT_V(n) asm volatile("s_waitcnt vmcnt(" #n ")" ::: "memory")
; #define PG8_WAIT_L(n) asm volatile("s_waitcnt lgkmcnt(" #n ")" ::: "memory")
; #define PG8_BAR __builtin_amdgcn_s_barrier()
; #define PG8_SCHED __builtin_amdgcn_sched_barrier(0)
;     ...
;             PG8_LDB(B0, 1, 0); PG8_LDB(B1, 1, 1); PG8_SCHED; PG8_LDA(At, 1, 0); PG8_STAGEX(rsA, PG8_SA(0, 1), a2 + hstepA, voffA);
;             PG8_WAIT_V(8); PG8_WAIT_L(0); PG8_BAR; PG8_MMA(0, 0, At, B0); PG8_MMA(0, 1, At, B1); PG8_BAR; PG8_SCHED;
;             PG8_LDA(At, 1, 1); PG8_STAGEX(rsB, PG8_SB(1, 0), b3, voffB); PG8_STAGEX(rsB, PG8_SB(1, 1), b3 + hstepB, voffB); PG8_STAGEX(rsA, PG8_SA(1, 0), a3, voffA);
;             PG8_WAIT_V(8); PG8_WAIT_L(0); PG8_BAR; PG8_MMA(1, 0, At, B0); PG8_MMA(1, 1, At, B1); PG8_BAR; PG8_SCHED;
;         }
	s_setprio 0
	v_add_u32_e32 v142, 0x18000, v220
	v_add_u32_e32 v158, 0x1c000, v220
	ds_read_b128 v[130:133], v142
	ds_read_b128 v[134:137], v142 offset:1024
	ds_read_b128 v[138:141], v142 offset:2048
	ds_read_b128 v[142:145], v142 offset:3072
	ds_read_b128 v[146:149], v158
	ds_read_b128 v[150:153], v158 offset:1024
	ds_read_b128 v[154:157], v158 offset:2048
	ds_read_b128 v[158:161], v158 offset:3072
	s_add_i32 s50, s50, 0x80000
	s_mov_b32 m0, s74
	ds_read_b128 v[162:165], v221 offset:32768
	ds_read_b128 v[170:173], v221 offset:33792
	ds_read_b128 v[182:185], v221 offset:34816
	ds_read_b128 v[186:189], v221 offset:35840
	ds_read_b128 v[190:193], v221 offset:36864
	ds_read_b128 v[194:197], v221 offset:37888
	ds_read_b128 v[198:201], v221 offset:38912
	ds_read_b128 v[202:205], v221 offset:39936
	buffer_load_dwordx4 v178, s[76:79], s50 offen lds
	s_mov_b32 m0, s12
	s_nop 0
	buffer_load_dwordx4 v210, s[76:79], s50 offen lds
	s_waitcnt vmcnt(8)
	s_waitcnt lgkmcnt(0)
	s_setprio 1
	s_barrier
	v_mfma_f32_16x16x32_bf16 v[126:129], v[130:133], v[162:165], v[126:129]
	v_mfma_f32_16x16x32_bf16 v[126:129], v[134:137], v[170:173], v[126:129]
	v_mfma_f32_16x16x32_bf16 v[110:113], v[138:141], v[162:165], v[110:113]
	v_mfma_f32_16x16x32_bf16 v[110:113], v[142:145], v[170:173], v[110:113]
	v_mfma_f32_16x16x32_bf16 v[118:121], v[130:133], v[182:185], v[118:121]
	v_mfma_f32_16x16x32_bf16 v[118:121], v[134:137], v[186:189], v[118:121]
	v_mfma_f32_16x16x32_bf16 v[102:105], v[138:141], v[182:185], v[102:105]
	v_mfma_f32_16x16x32_bf16 v[102:105], v[142:145], v[186:189], v[102:105]
	v_mfma_f32_16x16x32_bf16 v[114:117], v[130:133], v[190:193], v[114:117]
	v_mfma_f32_16x16x32_bf16 v[114:117], v[134:137], v[194:197], v[114:117]
	v_mfma_f32_16x16x32_bf16 v[98:101], v[138:141], v[190:193], v[98:101]
	v_mfma_f32_16x16x32_bf16 v[98:101], v[142:145], v[194:197], v[98:101]
	v_mfma_f32_16x16x32_bf16 v[122:125], v[130:133], v[198:201], v[122:125]
	v_mfma_f32_16x16x32_bf16 v[122:125], v[134:137], v[202:205], v[122:125]
	v_mfma_f32_16x16x32_bf16 v[106:109], v[138:141], v[198:201], v[106:109]
	v_mfma_f32_16x16x32_bf16 v[106:109], v[142:145], v[202:205], v[106:109]
	v_mfma_f32_16x16x32_bf16 v[62:65], v[146:149], v[162:165], v[62:65]
	v_mfma_f32_16x16x32_bf16 v[62:65], v[150:153], v[170:173], v[62:65]
	v_mfma_f32_16x16x32_bf16 v[46:49], v[154:157], v[162:165], v[46:49]
	v_mfma_f32_16x16x32_bf16 v[46:49], v[158:161], v[170:173], v[46:49]
	v_mfma_f32_16x16x32_bf16 v[54:57], v[146:149], v[182:185], v[54:57]
	v_mfma_f32_16x16x32_bf16 v[54:57], v[150:153], v[186:189], v[54:57]
	v_mfma_f32_16x16x32_bf16 v[38:41], v[154:157], v[182:185], v[38:41]
	v_mfma_f32_16x16x32_bf16 v[38:41], v[158:161], v[186:189], v[38:41]
	v_mfma_f32_16x16x32_bf16 v[50:53], v[146:149], v[190:193], v[50:53]
	v_mfma_f32_16x16x32_bf16 v[50:53], v[150:153], v[194:197], v[50:53]
	v_mfma_f32_16x16x32_bf16 v[34:37], v[154:157], v[190:193], v[34:37]
	v_mfma_f32_16x16x32_bf16 v[34:37], v[158:161], v[194:197], v[34:37]
	v_mfma_f32_16x16x32_bf16 v[58:61], v[146:149], v[198:201], v[58:61]
	v_mfma_f32_16x16x32_bf16 v[58:61], v[150:153], v[202:205], v[58:61]
	v_mfma_f32_16x16x32_bf16 v[42:45], v[154:157], v[198:201], v[42:45]
	v_mfma_f32_16x16x32_bf16 v[42:45], v[158:161], v[202:205], v[42:45]
	s_barrier
	s_setprio 0
	s_mov_b32 m0, s13
	s_or_b32 s50, s31, 0x80
	ds_read_b128 v[162:165], v221 offset:49152
	ds_read_b128 v[170:173], v221 offset:50176
	ds_read_b128 v[182:185], v221 offset:51200
	ds_read_b128 v[186:189], v221 offset:52224
	ds_read_b128 v[190:193], v221 offset:53248
	ds_read_b128 v[194:197], v221 offset:54272
	ds_read_b128 v[198:201], v221 offset:55296
	ds_read_b128 v[202:205], v221 offset:56320
	buffer_load_dwordx4 v179, s[56:59], s50 offen lds
	s_mov_b32 m0, s14
	s_add_i32 s31, s31, 0x80080
	buffer_load_dwordx4 v211, s[56:59], s50 offen lds
	s_mov_b32 m0, s17
	s_nop 0
	buffer_load_dwordx4 v179, s[56:59], s31 offen lds
	s_mov_b32 m0, s18
	s_nop 0
	buffer_load_dwordx4 v211, s[56:59], s31 offen lds
	s_mov_b32 m0, s15
	s_nop 0
	buffer_load_dwordx4 v178, s[76:79], s30 offen lds
	s_mov_b32 m0, s16
	s_nop 0
	buffer_load_dwordx4 v210, s[76:79], s30 offen lds
	s_waitcnt vmcnt(8)
	s_waitcnt lgkmcnt(0)
	s_setprio 1
	s_barrier
	v_mfma_f32_16x16x32_bf16 v[94:97], v[130:133], v[162:165], v[94:97]
	v_mfma_f32_16x16x32_bf16 v[94:97], v[134:137], v[170:173], v[94:97]
	v_mfma_f32_16x16x32_bf16 v[78:81], v[138:141], v[162:165], v[78:81]
	v_mfma_f32_16x16x32_bf16 v[78:81], v[142:145], v[170:173], v[78:81]
	v_mfma_f32_16x16x32_bf16 v[86:89], v[130:133], v[182:185], v[86:89]
	v_mfma_f32_16x16x32_bf16 v[86:89], v[134:137], v[186:189], v[86:89]
	v_mfma_f32_16x16x32_bf16 v[70:73], v[138:141], v[182:185], v[70:73]
	v_mfma_f32_16x16x32_bf16 v[70:73], v[142:145], v[186:189], v[70:73]
	v_mfma_f32_16x16x32_bf16 v[82:85], v[130:133], v[190:193], v[82:85]
	v_mfma_f32_16x16x32_bf16 v[82:85], v[134:137], v[194:197], v[82:85]
	v_mfma_f32_16x16x32_bf16 v[66:69], v[138:141], v[190:193], v[66:69]
	v_mfma_f32_16x16x32_bf16 v[66:69], v[142:145], v[194:197], v[66:69]
	v_mfma_f32_16x16x32_bf16 v[90:93], v[130:133], v[198:201], v[90:93]
	v_mfma_f32_16x16x32_bf16 v[90:93], v[134:137], v[202:205], v[90:93]
	v_mfma_f32_16x16x32_bf16 v[74:77], v[138:141], v[198:201], v[74:77]
	v_mfma_f32_16x16x32_bf16 v[74:77], v[142:145], v[202:205], v[74:77]
	v_mfma_f32_16x16x32_bf16 v[30:33], v[146:149], v[162:165], v[30:33]
	v_mfma_f32_16x16x32_bf16 v[30:33], v[150:153], v[170:173], v[30:33]
	v_mfma_f32_16x16x32_bf16 v[14:17], v[154:157], v[162:165], v[14:17]
	v_mfma_f32_16x16x32_bf16 v[14:17], v[158:161], v[170:173], v[14:17]
	v_mfma_f32_16x16x32_bf16 v[22:25], v[146:149], v[182:185], v[22:25]
	v_mfma_f32_16x16x32_bf16 v[22:25], v[150:153], v[186:189], v[22:25]
	v_mfma_f32_16x16x32_bf16 v[10:13], v[154:157], v[182:185], v[10:13]
	v_mfma_f32_16x16x32_bf16 v[10:13], v[158:161], v[186:189], v[10:13]
	v_mfma_f32_16x16x32_bf16 v[18:21], v[146:149], v[190:193], v[18:21]
	v_mfma_f32_16x16x32_bf16 v[18:21], v[150:153], v[194:197], v[18:21]
	v_mfma_f32_16x16x32_bf16 v[2:5], v[154:157], v[190:193], v[2:5]
	v_mfma_f32_16x16x32_bf16 v[2:5], v[158:161], v[194:197], v[2:5]
	v_mfma_f32_16x16x32_bf16 v[26:29], v[146:149], v[198:201], v[26:29]
	v_mfma_f32_16x16x32_bf16 v[26:29], v[150:153], v[202:205], v[26:29]
	v_mfma_f32_16x16x32_bf16 v[6:9], v[154:157], v[198:201], v[6:9]
	v_mfma_f32_16x16x32_bf16 v[6:9], v[158:161], v[202:205], v[6:9]
	s_barrier
	s_setprio 0
	s_add_i32 s29, s29, 2
	s_addk_i32 s7, 0x100
	s_addk_i32 s28, 0x100
	s_cmp_gt_u32 s29, 29
	s_cbranch_scc0 .LBB0_437
	s_and_b64 vcc, exec, s[84:85]
	s_cbranch_vccz .LBB0_440
	s_barrier

; #define PG8_STAGEX(rs, bufoff, soff, voff) do { _Pragma("unroll") for (int _i = 0; _i < 2; ++_i) \
;         __builtin_amdgcn_raw_ptr_buffer_load_lds(rs, (LAS unsigned*)(lds + (bufoff) + ldsw + _i * 8192), 16, (voff)[_i], (soff), 0, 0); } while (0)
; #define PG8_LDA(dst, b, h) do { _Pragma("unroll") for (int m = 0; m < 4; ++m) _Pragma("unroll") for (int k = 0; k < 2; ++k) dst[m][k] = *(const LAS bf16x8*)(lds + PG8_SA(b, h) + aoff + m * 2048 + k * 1024); } while (0)
; #define PG8_LDB(dst, b, h) do { _Pragma("unroll") for (int n = 0; n < 2; ++n) _Pragma("unroll") for (int k = 0; k < 2; ++k) dst[n][k] = *(const LAS bf16x8*)(lds + PG8_SB(b, h) + boff + n * 2048 + k * 1024); } while (0)
; #define PG8_WAIT_V(n) asm volatile("s_waitcnt vmcnt(" #n ")" ::: "memory")
; #define PG8_WAIT_L(n) asm volatile("s_waitcnt lgkmcnt(" #n ")" ::: "memory")
; #define PG8_BAR __builtin_amdgcn_s_barrier()
; #define PG8_SCHED __builtin_amdgcn_sched_barrier(0)
;     ...
;                 if (w0) { PG8_LDB(B0, 0, 0); PG8_LDB(B1, 0, 1); PG8_SCHED; PG8_LDA(At, 0, 0); }
;                 PG8_WAIT_L(0); PG8_BAR; if (w0) { PG8_MMA(0, 0, At, B0); PG8_MMA(0, 1, At, B1); } PG8_BAR; PG8_SCHED;
;                 PG8_STAGEX(rsB, PG8_SB(0, 0), b2, voffB); PG8_STAGEX(rsB, PG8_SB(0, 1), b2 + hstepB, voffB); PG8_STAGEX(rsA, PG8_SA(0, 0), a2, voffA);
;                 PG8_WAIT_V(6); PG8_BAR; PG8_BAR; PG8_SCHED;
.LBB0_542:
	v_add_u32_e32 v73, 0x10000, v71
	ds_read_b128 v[74:77], v73
	ds_read_b128 v[78:81], v73 offset:1024
	ds_read_b128 v[82:85], v73 offset:2048
	ds_read_b128 v[86:89], v73 offset:3072
	v_add_u32_e32 v73, 0x14000, v71
	ds_read_b128 v[90:93], v73
	ds_read_b128 v[94:97], v73 offset:1024
	ds_read_b128 v[98:101], v73 offset:2048
	ds_read_b128 v[110:113], v73 offset:3072
	s_cmp_lg_u32 s26, 28
	s_cselect_b32 s27, s25, 0
	s_add_i32 s28, s27, s17
	s_or_b32 s29, s28, 0x80
	s_add_i32 s27, s27, s10
	ds_read_b128 v[114:117], v72
	ds_read_b128 v[118:121], v72 offset:1024
	ds_read_b128 v[122:125], v72 offset:2048
	ds_read_b128 v[126:129], v72 offset:3072
	ds_read_b128 v[130:133], v72 offset:4096
	ds_read_b128 v[134:137], v72 offset:5120
	ds_read_b128 v[138:141], v72 offset:6144
	ds_read_b128 v[142:145], v72 offset:7168
	s_waitcnt lgkmcnt(0)
	s_setprio 1
	s_barrier
	v_mfma_f32_16x16x32_bf16 v[62:65], v[74:77], v[114:117], v[62:65]
	v_mfma_f32_16x16x32_bf16 v[62:65], v[78:81], v[118:121], v[62:65]
	v_mfma_f32_16x16x32_bf16 v[46:49], v[82:85], v[114:117], v[46:49]
	v_mfma_f32_16x16x32_bf16 v[46:49], v[86:89], v[118:121], v[46:49]
	v_mfma_f32_16x16x32_bf16 v[54:57], v[74:77], v[122:125], v[54:57]
	v_mfma_f32_16x16x32_bf16 v[54:57], v[78:81], v[126:129], v[54:57]
	v_mfma_f32_16x16x32_bf16 v[38:41], v[82:85], v[122:125], v[38:41]
	v_mfma_f32_16x16x32_bf16 v[38:41], v[86:89], v[126:129], v[38:41]
	v_mfma_f32_16x16x32_bf16 v[50:53], v[74:77], v[130:133], v[50:53]
	v_mfma_f32_16x16x32_bf16 v[50:53], v[78:81], v[134:137], v[50:53]
	v_mfma_f32_16x16x32_bf16 v[34:37], v[82:85], v[130:133], v[34:37]
	v_mfma_f32_16x16x32_bf16 v[34:37], v[86:89], v[134:137], v[34:37]
	v_mfma_f32_16x16x32_bf16 v[58:61], v[74:77], v[138:141], v[58:61]
	v_mfma_f32_16x16x32_bf16 v[58:61], v[78:81], v[142:145], v[58:61]
	v_mfma_f32_16x16x32_bf16 v[42:45], v[82:85], v[138:141], v[42:45]
	v_mfma_f32_16x16x32_bf16 v[42:45], v[86:89], v[142:145], v[42:45]
	v_mfma_f32_16x16x32_bf16 v[30:33], v[90:93], v[114:117], v[30:33]
	v_mfma_f32_16x16x32_bf16 v[30:33], v[94:97], v[118:121], v[30:33]
	v_mfma_f32_16x16x32_bf16 v[14:17], v[98:101], v[114:117], v[14:17]
	v_mfma_f32_16x16x32_bf16 v[14:17], v[110:113], v[118:121], v[14:17]
	v_mfma_f32_16x16x32_bf16 v[22:25], v[90:93], v[122:125], v[22:25]
	v_mfma_f32_16x16x32_bf16 v[22:25], v[94:97], v[126:129], v[22:25]
	v_mfma_f32_16x16x32_bf16 v[10:13], v[98:101], v[122:125], v[10:13]
	v_mfma_f32_16x16x32_bf16 v[10:13], v[110:113], v[126:129], v[10:13]
	v_mfma_f32_16x16x32_bf16 v[18:21], v[90:93], v[130:133], v[18:21]
	v_mfma_f32_16x16x32_bf16 v[18:21], v[94:97], v[134:137], v[18:21]
	v_mfma_f32_16x16x32_bf16 v[2:5], v[98:101], v[130:133], v[2:5]
	v_mfma_f32_16x16x32_bf16 v[2:5], v[110:113], v[134:137], v[2:5]
	v_mfma_f32_16x16x32_bf16 v[26:29], v[90:93], v[138:141], v[26:29]
	v_mfma_f32_16x16x32_bf16 v[26:29], v[94:97], v[142:145], v[26:29]
	v_mfma_f32_16x16x32_bf16 v[6:9], v[98:101], v[138:141], v[6:9]
	v_mfma_f32_16x16x32_bf16 v[6:9], v[110:113], v[142:145], v[6:9]
	s_barrier
	s_setprio 0
	s_mov_b32 m0, s12
	s_mov_b32 s58, s78
	s_mov_b32 s59, s79
	buffer_load_dwordx4 v67, s[56:59], s27 offen lds
	s_mov_b32 m0, s13
	s_add_i32 s30, s27, 0x80000
	buffer_load_dwordx4 v69, s[56:59], s27 offen lds
	s_mov_b32 m0, s14
	s_nop 0
	buffer_load_dwordx4 v67, s[56:59], s30 offen lds
	s_mov_b32 m0, s15
	s_nop 0
	buffer_load_dwordx4 v69, s[56:59], s30 offen lds
	s_mov_b32 m0, s11
	s_nop 0
	buffer_load_dwordx4 v66, s[76:79], s28 offen lds
	s_mov_b32 m0, s18
	s_nop 0
	buffer_load_dwordx4 v68, s[76:79], s28 offen lds
	s_waitcnt vmcnt(6)
	s_barrier
	s_barrier
; #define PG8_STAGEX(rs, bufoff, soff, voff) do { _Pragma("unroll") for (int _i = 0; _i < 2; ++_i) \
;         __builtin_amdgcn_raw_ptr_buffer_load_lds(rs, (LAS unsigned*)(lds + (bufoff) + ldsw + _i * 8192), 16, (voff)[_i], (soff), 0, 0); } while (0)
; #define PG8_LDA(dst, b, h) do { _Pragma("unroll") for (int m = 0; m < 4; ++m) _Pragma("unroll") for (int k = 0; k < 2; ++k) dst[m][k] = *(const LAS bf16x8*)(lds + PG8_SA(b, h) + aoff + m * 2048 + k * 1024); } while (0)
; #define PG8_LDB(dst, b, h) do { _Pragma("unroll") for (int n = 0; n < 2; ++n) _Pragma("unroll") for (int k = 0; k < 2; ++k) dst[n][k] = *(const LAS bf16x8*)(lds + PG8_SB(b, h) + boff + n * 2048 + k * 1024); } while (0)
; #define PG8_WAIT_V(n) asm volatile("s_waitcnt vmcnt(" #n ")" ::: "memory")
; #define PG8_WAIT_L(n) asm volatile("s_waitcnt lgkmcnt(" #n ")" ::: "memory")
; #define PG8_BAR __builtin_amdgcn_s_barrier()
; #define PG8_SCHED __builtin_amdgcn_sched_barrier(0)
;     ...
;                 if (w0) { PG8_LDB(B0, 1, 0); PG8_LDB(B1, 1, 1); PG8_SCHED; PG8_LDA(At, 1, 0); }
;                 PG8_WAIT_L(0); PG8_BAR; if (w0) { PG8_MMA(0, 0, At, B0); PG8_MMA(0, 1, At, B1); } PG8_BAR; PG8_SCHED;
;                 PG8_STAGEX(rsB, PG8_SB(1, 0), b3, voffB); PG8_STAGEX(rsB, PG8_SB(1, 1), b3 + hstepB, voffB); PG8_STAGEX(rsA, PG8_SA(1, 0), a3, voffA);
;                 PG8_WAIT_V(6); PG8_BAR; PG8_BAR; PG8_SCHED;
;             }
	v_add_u32_e32 v73, 0x18000, v71
	ds_read_b128 v[74:77], v73
	ds_read_b128 v[78:81], v73 offset:1024
	ds_read_b128 v[82:85], v73 offset:2048
	ds_read_b128 v[86:89], v73 offset:3072
	v_add_u32_e32 v73, 0x1c000, v71
	ds_read_b128 v[90:93], v73
	ds_read_b128 v[94:97], v73 offset:1024
	ds_read_b128 v[98:101], v73 offset:2048
	ds_read_b128 v[110:113], v73 offset:3072
	ds_read_b128 v[114:117], v72 offset:32768
	ds_read_b128 v[118:121], v72 offset:33792
	ds_read_b128 v[122:125], v72 offset:34816
	ds_read_b128 v[126:129], v72 offset:35840
	ds_read_b128 v[130:133], v72 offset:36864
	ds_read_b128 v[134:137], v72 offset:37888
	ds_read_b128 v[138:141], v72 offset:38912
	ds_read_b128 v[142:145], v72 offset:39936
	s_waitcnt lgkmcnt(0)
	s_setprio 1
	s_barrier
	v_mfma_f32_16x16x32_bf16 v[62:65], v[74:77], v[114:117], v[62:65]
	v_mfma_f32_16x16x32_bf16 v[46:49], v[82:85], v[114:117], v[46:49]
	v_mfma_f32_16x16x32_bf16 v[54:57], v[74:77], v[122:125], v[54:57]
	v_mfma_f32_16x16x32_bf16 v[38:41], v[82:85], v[122:125], v[38:41]
	v_mfma_f32_16x16x32_bf16 v[50:53], v[74:77], v[130:133], v[50:53]
	v_mfma_f32_16x16x32_bf16 v[34:37], v[82:85], v[130:133], v[34:37]
	v_mfma_f32_16x16x32_bf16 v[58:61], v[74:77], v[138:141], v[58:61]
	v_mfma_f32_16x16x32_bf16 v[42:45], v[82:85], v[138:141], v[42:45]
	v_mfma_f32_16x16x32_bf16 v[62:65], v[78:81], v[118:121], v[62:65]
	v_mfma_f32_16x16x32_bf16 v[46:49], v[86:89], v[118:121], v[46:49]
	v_mfma_f32_16x16x32_bf16 v[54:57], v[78:81], v[126:129], v[54:57]
	v_mfma_f32_16x16x32_bf16 v[38:41], v[86:89], v[126:129], v[38:41]
	v_mfma_f32_16x16x32_bf16 v[50:53], v[78:81], v[134:137], v[50:53]
	v_mfma_f32_16x16x32_bf16 v[34:37], v[86:89], v[134:137], v[34:37]
	v_mfma_f32_16x16x32_bf16 v[58:61], v[78:81], v[142:145], v[58:61]
	v_mfma_f32_16x16x32_bf16 v[42:45], v[86:89], v[142:145], v[42:45]
	v_mfma_f32_16x16x32_bf16 v[30:33], v[90:93], v[114:117], v[30:33]
	s_or_b32 s28, s27, 0x80
	v_mfma_f32_16x16x32_bf16 v[14:17], v[98:101], v[114:117], v[14:17]
	v_mfma_f32_16x16x32_bf16 v[22:25], v[90:93], v[122:125], v[22:25]
	v_mfma_f32_16x16x32_bf16 v[10:13], v[98:101], v[122:125], v[10:13]
	v_mfma_f32_16x16x32_bf16 v[18:21], v[90:93], v[130:133], v[18:21]
	v_mfma_f32_16x16x32_bf16 v[2:5], v[98:101], v[130:133], v[2:5]
	v_mfma_f32_16x16x32_bf16 v[26:29], v[90:93], v[138:141], v[26:29]
	v_mfma_f32_16x16x32_bf16 v[6:9], v[98:101], v[138:141], v[6:9]
	v_mfma_f32_16x16x32_bf16 v[30:33], v[94:97], v[118:121], v[30:33]
	v_mfma_f32_16x16x32_bf16 v[14:17], v[110:113], v[118:121], v[14:17]
	v_mfma_f32_16x16x32_bf16 v[22:25], v[94:97], v[126:129], v[22:25]
	v_mfma_f32_16x16x32_bf16 v[10:13], v[110:113], v[126:129], v[10:13]
	v_mfma_f32_16x16x32_bf16 v[18:21], v[94:97], v[134:137], v[18:21]
	v_mfma_f32_16x16x32_bf16 v[2:5], v[110:113], v[134:137], v[2:5]
	v_mfma_f32_16x16x32_bf16 v[26:29], v[94:97], v[142:145], v[26:29]
	v_mfma_f32_16x16x32_bf16 v[6:9], v[110:113], v[142:145], v[6:9]
	s_barrier
	s_setprio 0
	s_mov_b32 m0, s19
	s_add_i32 s27, s27, 0x80080
	buffer_load_dwordx4 v67, s[56:59], s28 offen lds
	s_mov_b32 m0, s20
	s_nop 0
	buffer_load_dwordx4 v69, s[56:59], s28 offen lds
	s_mov_b32 m0, s23
	s_nop 0
	buffer_load_dwordx4 v67, s[56:59], s27 offen lds
	s_mov_b32 m0, s24
	s_nop 0
	buffer_load_dwordx4 v69, s[56:59], s27 offen lds
	s_mov_b32 m0, s21
	s_nop 0
	buffer_load_dwordx4 v66, s[76:79], s29 offen lds
	s_mov_b32 m0, s22
	s_nop 0
	buffer_load_dwordx4 v68, s[76:79], s29 offen lds
	s_waitcnt vmcnt(6)
	s_barrier
	s_barrier
	s_addk_i32 s25, 0x100
	s_add_i32 s26, s26, 2
	s_cmp_gt_u32 s26, 29
	s_cbranch_scc0 .LBB0_542
	s_cmpk_lt_u32 s1, 0x100
	s_cbranch_scc0 .LBB0_545
	s_barrier

; #define PG8_STAGEX(rs, bufoff, soff, voff) do { _Pragma("unroll") for (int _i = 0; _i < 2; ++_i) \
;         __builtin_amdgcn_raw_ptr_buffer_load_lds(rs, (LAS unsigned*)(lds + (bufoff) + ldsw + _i * 8192), 16, (voff)[_i], (soff), 0, 0); } while (0)
; #define PG8_LDA(dst, b, h) do { _Pragma("unroll") for (int m = 0; m < 4; ++m) _Pragma("unroll") for (int k = 0; k < 2; ++k) dst[m][k] = *(const LAS bf16x8*)(lds + PG8_SA(b, h) + aoff + m * 2048 + k * 1024); } while (0)
; #define PG8_LDB(dst, b, h) do { _Pragma("unroll") for (int n = 0; n < 2; ++n) _Pragma("unroll") for (int k = 0; k < 2; ++k) dst[n][k] = *(const LAS bf16x8*)(lds + PG8_SB(b, h) + boff + n * 2048 + k * 1024); } while (0)
; #define PG8_WAIT_V(n) asm volatile("s_waitcnt vmcnt(" #n ")" ::: "memory")
; #define PG8_WAIT_L(n) asm volatile("s_waitcnt lgkmcnt(" #n ")" ::: "memory")
; #define PG8_BAR __builtin_amdgcn_s_barrier()
; #define PG8_SCHED __builtin_amdgcn_sched_barrier(0)
;     ...
;             PG8_LDB(B0, 0, 0); PG8_LDB(B1, 0, 1); PG8_SCHED; PG8_LDA(At, 0, 0); PG8_STAGEX(rsA, PG8_SA(1, 1), a1 + hstepA, voffA);
;             PG8_WAIT_V(8); PG8_WAIT_L(0); PG8_BAR; PG8_MMA(0, 0, At, B0); PG8_MMA(0, 1, At, B1); PG8_BAR; PG8_SCHED;
;             PG8_LDA(At, 0, 1); PG8_STAGEX(rsB, PG8_SB(0, 0), b2, voffB); PG8_STAGEX(rsB, PG8_SB(0, 1), b2 + hstepB, voffB); PG8_STAGEX(rsA, PG8_SA(0, 0), a2, voffA);
;             PG8_WAIT_V(8); PG8_WAIT_L(0); PG8_BAR; PG8_MMA(1, 0, At, B0); PG8_MMA(1, 1, At, B1); PG8_BAR; PG8_SCHED;
.LBB0_788:
	v_add_u32_e32 v150, 0x10000, v153
	ds_read_b128 v[138:141], v150
	ds_read_b128 v[142:145], v150 offset:1024
	ds_read_b128 v[146:149], v150 offset:2048
	ds_read_b128 v[156:159], v150 offset:3072
	v_add_u32_e32 v150, 0x14000, v153
	ds_read_b128 v[160:163], v150
	ds_read_b128 v[164:167], v150 offset:1024
	ds_read_b128 v[182:185], v150 offset:2048
	ds_read_b128 v[186:189], v150 offset:3072
	s_add_i32 s48, s31, 0xfffc0080
	s_cmp_eq_u32 s55, s47
	s_cselect_b32 s50, s7, s48
	s_cselect_b32 s49, s30, s46
	s_add_i32 s48, s50, 0x80
	s_mov_b32 m0, s35
	ds_read_b128 v[190:193], v154
	ds_read_b128 v[194:197], v154 offset:1024
	ds_read_b128 v[198:201], v154 offset:2048
	ds_read_b128 v[202:205], v154 offset:3072
	ds_read_b128 v[206:209], v154 offset:4096
	ds_read_b128 v[210:213], v154 offset:5120
	ds_read_b128 v[214:217], v154 offset:6144
	ds_read_b128 v[218:221], v154 offset:7168
	buffer_load_dwordx4 v130, s[76:79], s31 offen lds
	s_mov_b32 m0, s82
	s_nop 0
	buffer_load_dwordx4 v134, s[76:79], s31 offen lds
	s_waitcnt vmcnt(8)
	s_waitcnt lgkmcnt(0)
	s_setprio 1
	s_barrier
	v_mfma_f32_16x16x32_bf16 v[126:129], v[190:193], v[138:141], v[126:129]
	v_mfma_f32_16x16x32_bf16 v[126:129], v[194:197], v[142:145], v[126:129]
	v_mfma_f32_16x16x32_bf16 v[62:65], v[190:193], v[146:149], v[62:65]
	v_mfma_f32_16x16x32_bf16 v[62:65], v[194:197], v[156:159], v[62:65]
	v_mfma_f32_16x16x32_bf16 v[118:121], v[198:201], v[138:141], v[118:121]
	v_mfma_f32_16x16x32_bf16 v[118:121], v[202:205], v[142:145], v[118:121]
	v_mfma_f32_16x16x32_bf16 v[54:57], v[198:201], v[146:149], v[54:57]
	v_mfma_f32_16x16x32_bf16 v[54:57], v[202:205], v[156:159], v[54:57]
	v_mfma_f32_16x16x32_bf16 v[110:113], v[206:209], v[138:141], v[110:113]
	v_mfma_f32_16x16x32_bf16 v[110:113], v[210:213], v[142:145], v[110:113]
	v_mfma_f32_16x16x32_bf16 v[46:49], v[206:209], v[146:149], v[46:49]
	v_mfma_f32_16x16x32_bf16 v[46:49], v[210:213], v[156:159], v[46:49]
	v_mfma_f32_16x16x32_bf16 v[102:105], v[214:217], v[138:141], v[102:105]
	v_mfma_f32_16x16x32_bf16 v[102:105], v[218:221], v[142:145], v[102:105]
	v_mfma_f32_16x16x32_bf16 v[38:41], v[214:217], v[146:149], v[38:41]
	v_mfma_f32_16x16x32_bf16 v[38:41], v[218:221], v[156:159], v[38:41]
	v_mfma_f32_16x16x32_bf16 v[122:125], v[190:193], v[160:163], v[122:125]
	v_mfma_f32_16x16x32_bf16 v[122:125], v[194:197], v[164:167], v[122:125]
	v_mfma_f32_16x16x32_bf16 v[58:61], v[190:193], v[182:185], v[58:61]
	v_mfma_f32_16x16x32_bf16 v[58:61], v[194:197], v[186:189], v[58:61]
	v_mfma_f32_16x16x32_bf16 v[114:117], v[198:201], v[160:163], v[114:117]
	v_mfma_f32_16x16x32_bf16 v[114:117], v[202:205], v[164:167], v[114:117]
	v_mfma_f32_16x16x32_bf16 v[50:53], v[198:201], v[182:185], v[50:53]
	v_mfma_f32_16x16x32_bf16 v[50:53], v[202:205], v[186:189], v[50:53]
	v_mfma_f32_16x16x32_bf16 v[106:109], v[206:209], v[160:163], v[106:109]
	v_mfma_f32_16x16x32_bf16 v[106:109], v[210:213], v[164:167], v[106:109]
	v_mfma_f32_16x16x32_bf16 v[42:45], v[206:209], v[182:185], v[42:45]
	v_mfma_f32_16x16x32_bf16 v[42:45], v[210:213], v[186:189], v[42:45]
	v_mfma_f32_16x16x32_bf16 v[98:101], v[214:217], v[160:163], v[98:101]
	v_mfma_f32_16x16x32_bf16 v[98:101], v[218:221], v[164:167], v[98:101]
	v_mfma_f32_16x16x32_bf16 v[34:37], v[214:217], v[182:185], v[34:37]
	v_mfma_f32_16x16x32_bf16 v[34:37], v[218:221], v[186:189], v[34:37]
	s_barrier
	s_setprio 0
	s_mov_b32 m0, s15
	s_mov_b32 s86, s78
	s_mov_b32 s87, s79
	ds_read_b128 v[190:193], v154 offset:16384
	ds_read_b128 v[194:197], v154 offset:17408
	ds_read_b128 v[198:201], v154 offset:18432
	ds_read_b128 v[202:205], v154 offset:19456
	ds_read_b128 v[206:209], v154 offset:20480
	ds_read_b128 v[210:213], v154 offset:21504
	ds_read_b128 v[214:217], v154 offset:22528
	ds_read_b128 v[218:221], v154 offset:23552
	buffer_load_dwordx4 v132, s[84:87], s49 offen lds
	s_mov_b32 m0, s16
	s_add_i32 s51, s49, 0x8000
	buffer_load_dwordx4 v136, s[84:87], s49 offen lds
	s_mov_b32 m0, s17
	s_nop 0
	buffer_load_dwordx4 v132, s[84:87], s51 offen lds
	s_mov_b32 m0, s18
	s_nop 0
	buffer_load_dwordx4 v136, s[84:87], s51 offen lds
	s_mov_b32 m0, s14
	s_nop 0
	buffer_load_dwordx4 v130, s[76:79], s50 offen lds
	s_mov_b32 m0, s19
	s_nop 0
	buffer_load_dwordx4 v134, s[76:79], s50 offen lds
	s_waitcnt vmcnt(8)
	s_waitcnt lgkmcnt(0)
	s_setprio 1
	s_barrier
	v_mfma_f32_16x16x32_bf16 v[94:97], v[190:193], v[138:141], v[94:97]
	v_mfma_f32_16x16x32_bf16 v[94:97], v[194:197], v[142:145], v[94:97]
	v_mfma_f32_16x16x32_bf16 v[30:33], v[190:193], v[146:149], v[30:33]
	v_mfma_f32_16x16x32_bf16 v[30:33], v[194:197], v[156:159], v[30:33]
	v_mfma_f32_16x16x32_bf16 v[86:89], v[198:201], v[138:141], v[86:89]
	v_mfma_f32_16x16x32_bf16 v[86:89], v[202:205], v[142:145], v[86:89]
	v_mfma_f32_16x16x32_bf16 v[22:25], v[198:201], v[146:149], v[22:25]
	v_mfma_f32_16x16x32_bf16 v[22:25], v[202:205], v[156:159], v[22:25]
	v_mfma_f32_16x16x32_bf16 v[78:81], v[206:209], v[138:141], v[78:81]
	v_mfma_f32_16x16x32_bf16 v[78:81], v[210:213], v[142:145], v[78:81]
	v_mfma_f32_16x16x32_bf16 v[14:17], v[206:209], v[146:149], v[14:17]
	v_mfma_f32_16x16x32_bf16 v[14:17], v[210:213], v[156:159], v[14:17]
	v_mfma_f32_16x16x32_bf16 v[70:73], v[214:217], v[138:141], v[70:73]
	v_mfma_f32_16x16x32_bf16 v[70:73], v[218:221], v[142:145], v[70:73]
	v_mfma_f32_16x16x32_bf16 v[6:9], v[214:217], v[146:149], v[6:9]
	v_mfma_f32_16x16x32_bf16 v[6:9], v[218:221], v[156:159], v[6:9]
	v_mfma_f32_16x16x32_bf16 v[90:93], v[190:193], v[160:163], v[90:93]
	v_mfma_f32_16x16x32_bf16 v[90:93], v[194:197], v[164:167], v[90:93]
	v_mfma_f32_16x16x32_bf16 v[26:29], v[190:193], v[182:185], v[26:29]
	v_mfma_f32_16x16x32_bf16 v[26:29], v[194:197], v[186:189], v[26:29]
	v_mfma_f32_16x16x32_bf16 v[82:85], v[198:201], v[160:163], v[82:85]
	v_mfma_f32_16x16x32_bf16 v[82:85], v[202:205], v[164:167], v[82:85]
	v_mfma_f32_16x16x32_bf16 v[18:21], v[198:201], v[182:185], v[18:21]
	v_mfma_f32_16x16x32_bf16 v[18:21], v[202:205], v[186:189], v[18:21]
	v_mfma_f32_16x16x32_bf16 v[74:77], v[206:209], v[160:163], v[74:77]
	v_mfma_f32_16x16x32_bf16 v[74:77], v[210:213], v[164:167], v[74:77]
	v_mfma_f32_16x16x32_bf16 v[10:13], v[206:209], v[182:185], v[10:13]
	v_mfma_f32_16x16x32_bf16 v[10:13], v[210:213], v[186:189], v[10:13]
	v_mfma_f32_16x16x32_bf16 v[66:69], v[214:217], v[160:163], v[66:69]
	v_mfma_f32_16x16x32_bf16 v[66:69], v[218:221], v[164:167], v[66:69]
	v_mfma_f32_16x16x32_bf16 v[2:5], v[214:217], v[182:185], v[2:5]
	v_mfma_f32_16x16x32_bf16 v[2:5], v[218:221], v[186:189], v[2:5]
	s_barrier
; #define PG8_STAGEX(rs, bufoff, soff, voff) do { _Pragma("unroll") for (int _i = 0; _i < 2; ++_i) \
;         __builtin_amdgcn_raw_ptr_buffer_load_lds(rs, (LAS unsigned*)(lds + (bufoff) + ldsw + _i * 8192), 16, (voff)[_i], (soff), 0, 0); } while (0)
; #define PG8_LDA(dst, b, h) do { _Pragma("unroll") for (int m = 0; m < 4; ++m) _Pragma("unroll") for (int k = 0; k < 2; ++k) dst[m][k] = *(const LAS bf16x8*)(lds + PG8_SA(b, h) + aoff + m * 2048 + k * 1024); } while (0)
; #define PG8_LDB(dst, b, h) do { _Pragma("unroll") for (int n = 0; n < 2; ++n) _Pragma("unroll") for (int k = 0; k < 2; ++k) dst[n][k] = *(const LAS bf16x8*)(lds + PG8_SB(b, h) + boff + n * 2048 + k * 1024); } while (0)
; #define PG8_WAIT_V(n) asm volatile("s_waitcnt vmcnt(" #n ")" ::: "memory")
; #define PG8_WAIT_L(n) asm volatile("s_waitcnt lgkmcnt(" #n ")" ::: "memory")
; #define PG8_BAR __builtin_amdgcn_s_barrier()
; #define PG8_SCHED __builtin_amdgcn_sched_barrier(0)
;     ...
;             PG8_LDB(B0, 1, 0); PG8_LDB(B1, 1, 1); PG8_SCHED; PG8_LDA(At, 1, 0); PG8_STAGEX(rsA, PG8_SA(0, 1), a2 + hstepA, voffA);
;             PG8_WAIT_V(8); PG8_WAIT_L(0); PG8_BAR; PG8_MMA(0, 0, At, B0); PG8_MMA(0, 1, At, B1); PG8_BAR; PG8_SCHED;
;             PG8_LDA(At, 1, 1); PG8_STAGEX(rsB, PG8_SB(1, 0), b3, voffB); PG8_STAGEX(rsB, PG8_SB(1, 1), b3 + hstepB, voffB); PG8_STAGEX(rsA, PG8_SA(1, 0), a3, voffA);
;             PG8_WAIT_V(8); PG8_WAIT_L(0); PG8_BAR; PG8_MMA(1, 0, At, B0); PG8_MMA(1, 1, At, B1); PG8_BAR; PG8_SCHED;
;         }
	s_setprio 0
	v_add_u32_e32 v150, 0x18000, v153
	ds_read_b128 v[138:141], v150
	ds_read_b128 v[142:145], v150 offset:1024
	ds_read_b128 v[146:149], v150 offset:2048
	ds_read_b128 v[156:159], v150 offset:3072
	v_add_u32_e32 v150, 0x1c000, v153
	ds_read_b128 v[160:163], v150
	ds_read_b128 v[164:167], v150 offset:1024
	ds_read_b128 v[182:185], v150 offset:2048
	ds_read_b128 v[186:189], v150 offset:3072
	s_add_i32 s50, s50, 0x40000
	s_mov_b32 m0, s20
	ds_read_b128 v[190:193], v154 offset:32768
	ds_read_b128 v[194:197], v154 offset:33792
	ds_read_b128 v[198:201], v154 offset:34816
	ds_read_b128 v[202:205], v154 offset:35840
	ds_read_b128 v[206:209], v154 offset:36864
	ds_read_b128 v[210:213], v154 offset:37888
	ds_read_b128 v[214:217], v154 offset:38912
	ds_read_b128 v[218:221], v154 offset:39936
	buffer_load_dwordx4 v130, s[76:79], s50 offen lds
	s_mov_b32 m0, s21
	s_nop 0
	buffer_load_dwordx4 v134, s[76:79], s50 offen lds
	s_waitcnt vmcnt(8)
	s_waitcnt lgkmcnt(0)
	s_setprio 1
	s_barrier
	v_mfma_f32_16x16x32_bf16 v[126:129], v[190:193], v[138:141], v[126:129]
	v_mfma_f32_16x16x32_bf16 v[126:129], v[194:197], v[142:145], v[126:129]
	v_mfma_f32_16x16x32_bf16 v[62:65], v[190:193], v[146:149], v[62:65]
	v_mfma_f32_16x16x32_bf16 v[62:65], v[194:197], v[156:159], v[62:65]
	v_mfma_f32_16x16x32_bf16 v[118:121], v[198:201], v[138:141], v[118:121]
	v_mfma_f32_16x16x32_bf16 v[118:121], v[202:205], v[142:145], v[118:121]
	v_mfma_f32_16x16x32_bf16 v[54:57], v[198:201], v[146:149], v[54:57]
	v_mfma_f32_16x16x32_bf16 v[54:57], v[202:205], v[156:159], v[54:57]
	v_mfma_f32_16x16x32_bf16 v[110:113], v[206:209], v[138:141], v[110:113]
	v_mfma_f32_16x16x32_bf16 v[110:113], v[210:213], v[142:145], v[110:113]
	v_mfma_f32_16x16x32_bf16 v[46:49], v[206:209], v[146:149], v[46:49]
	v_mfma_f32_16x16x32_bf16 v[46:49], v[210:213], v[156:159], v[46:49]
	v_mfma_f32_16x16x32_bf16 v[102:105], v[214:217], v[138:141], v[102:105]
	v_mfma_f32_16x16x32_bf16 v[102:105], v[218:221], v[142:145], v[102:105]
	v_mfma_f32_16x16x32_bf16 v[38:41], v[214:217], v[146:149], v[38:41]
	v_mfma_f32_16x16x32_bf16 v[38:41], v[218:221], v[156:159], v[38:41]
	v_mfma_f32_16x16x32_bf16 v[122:125], v[190:193], v[160:163], v[122:125]
	v_mfma_f32_16x16x32_bf16 v[122:125], v[194:197], v[164:167], v[122:125]
	v_mfma_f32_16x16x32_bf16 v[58:61], v[190:193], v[182:185], v[58:61]
	v_mfma_f32_16x16x32_bf16 v[58:61], v[194:197], v[186:189], v[58:61]
	v_mfma_f32_16x16x32_bf16 v[114:117], v[198:201], v[160:163], v[114:117]
	v_mfma_f32_16x16x32_bf16 v[114:117], v[202:205], v[164:167], v[114:117]
	v_mfma_f32_16x16x32_bf16 v[50:53], v[198:201], v[182:185], v[50:53]
	v_mfma_f32_16x16x32_bf16 v[50:53], v[202:205], v[186:189], v[50:53]
	v_mfma_f32_16x16x32_bf16 v[106:109], v[206:209], v[160:163], v[106:109]
	v_mfma_f32_16x16x32_bf16 v[106:109], v[210:213], v[164:167], v[106:109]
	v_mfma_f32_16x16x32_bf16 v[42:45], v[206:209], v[182:185], v[42:45]
	v_mfma_f32_16x16x32_bf16 v[42:45], v[210:213], v[186:189], v[42:45]
	v_mfma_f32_16x16x32_bf16 v[98:101], v[214:217], v[160:163], v[98:101]
	v_mfma_f32_16x16x32_bf16 v[98:101], v[218:221], v[164:167], v[98:101]
	v_mfma_f32_16x16x32_bf16 v[34:37], v[214:217], v[182:185], v[34:37]
	v_mfma_f32_16x16x32_bf16 v[34:37], v[218:221], v[186:189], v[34:37]
	s_barrier
	s_setprio 0
	s_mov_b32 m0, s93
	s_or_b32 s50, s49, 0x80
	ds_read_b128 v[190:193], v154 offset:49152
	ds_read_b128 v[194:197], v154 offset:50176
	ds_read_b128 v[198:201], v154 offset:51200
	ds_read_b128 v[202:205], v154 offset:52224
	ds_read_b128 v[206:209], v154 offset:53248
	ds_read_b128 v[210:213], v154 offset:54272
	ds_read_b128 v[214:217], v154 offset:55296
	ds_read_b128 v[218:221], v154 offset:56320
	buffer_load_dwordx4 v132, s[84:87], s50 offen lds
	s_mov_b32 m0, s94
	s_add_i32 s49, s49, 0x8080
	buffer_load_dwordx4 v136, s[84:87], s50 offen lds
	s_mov_b32 m0, s9
	s_nop 0
	buffer_load_dwordx4 v132, s[84:87], s49 offen lds
	s_mov_b32 m0, s54
	s_nop 0
	buffer_load_dwordx4 v136, s[84:87], s49 offen lds
	s_mov_b32 m0, s95
	s_nop 0
	buffer_load_dwordx4 v130, s[76:79], s48 offen lds
	s_mov_b32 m0, s97
	s_nop 0
	buffer_load_dwordx4 v134, s[76:79], s48 offen lds
	s_waitcnt vmcnt(8)
	s_waitcnt lgkmcnt(0)
	s_setprio 1
	s_barrier
	v_mfma_f32_16x16x32_bf16 v[94:97], v[190:193], v[138:141], v[94:97]
	v_mfma_f32_16x16x32_bf16 v[94:97], v[194:197], v[142:145], v[94:97]
	v_mfma_f32_16x16x32_bf16 v[30:33], v[190:193], v[146:149], v[30:33]
	v_mfma_f32_16x16x32_bf16 v[30:33], v[194:197], v[156:159], v[30:33]
	v_mfma_f32_16x16x32_bf16 v[86:89], v[198:201], v[138:141], v[86:89]
	v_mfma_f32_16x16x32_bf16 v[86:89], v[202:205], v[142:145], v[86:89]
	v_mfma_f32_16x16x32_bf16 v[22:25], v[198:201], v[146:149], v[22:25]
	v_mfma_f32_16x16x32_bf16 v[22:25], v[202:205], v[156:159], v[22:25]
	v_mfma_f32_16x16x32_bf16 v[78:81], v[206:209], v[138:141], v[78:81]
	v_mfma_f32_16x16x32_bf16 v[78:81], v[210:213], v[142:145], v[78:81]
	v_mfma_f32_16x16x32_bf16 v[14:17], v[206:209], v[146:149], v[14:17]
	v_mfma_f32_16x16x32_bf16 v[14:17], v[210:213], v[156:159], v[14:17]
	v_mfma_f32_16x16x32_bf16 v[70:73], v[214:217], v[138:141], v[70:73]
	v_mfma_f32_16x16x32_bf16 v[70:73], v[218:221], v[142:145], v[70:73]
	v_mfma_f32_16x16x32_bf16 v[6:9], v[214:217], v[146:149], v[6:9]
	v_mfma_f32_16x16x32_bf16 v[6:9], v[218:221], v[156:159], v[6:9]
	v_mfma_f32_16x16x32_bf16 v[90:93], v[190:193], v[160:163], v[90:93]
	v_mfma_f32_16x16x32_bf16 v[90:93], v[194:197], v[164:167], v[90:93]
	v_mfma_f32_16x16x32_bf16 v[26:29], v[190:193], v[182:185], v[26:29]
	v_mfma_f32_16x16x32_bf16 v[26:29], v[194:197], v[186:189], v[26:29]
	v_mfma_f32_16x16x32_bf16 v[82:85], v[198:201], v[160:163], v[82:85]
	v_mfma_f32_16x16x32_bf16 v[82:85], v[202:205], v[164:167], v[82:85]
	v_mfma_f32_16x16x32_bf16 v[18:21], v[198:201], v[182:185], v[18:21]
	v_mfma_f32_16x16x32_bf16 v[18:21], v[202:205], v[186:189], v[18:21]
	v_mfma_f32_16x16x32_bf16 v[74:77], v[206:209], v[160:163], v[74:77]
	v_mfma_f32_16x16x32_bf16 v[74:77], v[210:213], v[164:167], v[74:77]
	v_mfma_f32_16x16x32_bf16 v[10:13], v[206:209], v[182:185], v[10:13]
	v_mfma_f32_16x16x32_bf16 v[10:13], v[210:213], v[186:189], v[10:13]
	v_mfma_f32_16x16x32_bf16 v[66:69], v[214:217], v[160:163], v[66:69]
	v_mfma_f32_16x16x32_bf16 v[66:69], v[218:221], v[164:167], v[66:69]
	v_mfma_f32_16x16x32_bf16 v[2:5], v[214:217], v[182:185], v[2:5]
	v_mfma_f32_16x16x32_bf16 v[2:5], v[218:221], v[186:189], v[2:5]
	s_barrier
	s_setprio 0
	s_add_i32 s47, s47, 2
	s_addk_i32 s31, 0x100
	s_addk_i32 s46, 0x100
	s_cmp_ge_i32 s47, s34
	s_cbranch_scc0 .LBB0_788
	s_mov_b32 s61, s96
	s_and_b64 vcc, exec, s[62:63]
	s_cbranch_vccz .LBB0_791

; #define PG8_STAGEX(rs, bufoff, soff, voff) do { _Pragma("unroll") for (int _i = 0; _i < 2; ++_i) \
;         __builtin_amdgcn_raw_ptr_buffer_load_lds(rs, (LAS unsigned*)(lds + (bufoff) + ldsw + _i * 8192), 16, (voff)[_i], (soff), 0, 0); } while (0)
; #define PG8_LDA(dst, b, h) do { _Pragma("unroll") for (int m = 0; m < 4; ++m) _Pragma("unroll") for (int k = 0; k < 2; ++k) dst[m][k] = *(const LAS bf16x8*)(lds + PG8_SA(b, h) + aoff + m * 2048 + k * 1024); } while (0)
; #define PG8_LDB(dst, b, h) do { _Pragma("unroll") for (int n = 0; n < 2; ++n) _Pragma("unroll") for (int k = 0; k < 2; ++k) dst[n][k] = *(const LAS bf16x8*)(lds + PG8_SB(b, h) + boff + n * 2048 + k * 1024); } while (0)
; #define PG8_WAIT_V(n) asm volatile("s_waitcnt vmcnt(" #n ")" ::: "memory")
; #define PG8_WAIT_L(n) asm volatile("s_waitcnt lgkmcnt(" #n ")" ::: "memory")
; #define PG8_BAR __builtin_amdgcn_s_barrier()
; #define PG8_SCHED __builtin_amdgcn_sched_barrier(0)
;     ...
;             PG8_LDB(B0, 0, 0); PG8_LDB(B1, 0, 1); PG8_SCHED; PG8_LDA(At, 0, 0); PG8_STAGEX(rsA, PG8_SA(1, 1), a1 + hstepA, voffA);
;             PG8_WAIT_V(8); PG8_WAIT_L(0); PG8_BAR; PG8_MMA(0, 0, At, B0); PG8_MMA(0, 1, At, B1); PG8_BAR; PG8_SCHED;
;             PG8_LDA(At, 0, 1); PG8_STAGEX(rsB, PG8_SB(0, 0), b2, voffB); PG8_STAGEX(rsB, PG8_SB(0, 1), b2 + hstepB, voffB); PG8_STAGEX(rsA, PG8_SA(0, 0), a2, voffA);
;             PG8_WAIT_V(8); PG8_WAIT_L(0); PG8_BAR; PG8_MMA(1, 0, At, B0); PG8_MMA(1, 1, At, B1); PG8_BAR; PG8_SCHED;
.LBB0_1274:
	v_add_u32_e32 v142, 0x10000, v157
	v_add_u32_e32 v159, 0x14000, v157
	ds_read_b128 v[130:133], v142
	ds_read_b128 v[134:137], v142 offset:1024
	ds_read_b128 v[138:141], v142 offset:2048
	ds_read_b128 v[142:145], v142 offset:3072
	ds_read_b128 v[146:149], v159
	ds_read_b128 v[164:167], v159 offset:1024
	ds_read_b128 v[168:171], v159 offset:2048
	ds_read_b128 v[182:185], v159 offset:3072
	s_add_i32 s42, s62, 0xfff80080
	s_cmp_eq_u32 s67, 28
	s_cselect_b32 s70, s30, s42
	s_cselect_b32 s69, s31, s63
	s_or_b32 s68, s70, 0x80
	s_mov_b32 m0, s29
	ds_read_b128 v[186:189], v158
	ds_read_b128 v[190:193], v158 offset:1024
	ds_read_b128 v[194:197], v158 offset:2048
	ds_read_b128 v[198:201], v158 offset:3072
	ds_read_b128 v[202:205], v158 offset:4096
	ds_read_b128 v[206:209], v158 offset:5120
	ds_read_b128 v[210:213], v158 offset:6144
	ds_read_b128 v[214:217], v158 offset:7168
	buffer_load_dwordx4 v150, s[76:79], s62 offen lds
	s_mov_b32 m0, s35
	s_nop 0
	buffer_load_dwordx4 v152, s[76:79], s62 offen lds
	s_waitcnt vmcnt(8)
	s_waitcnt lgkmcnt(0)
	s_setprio 1
	s_barrier
	v_mfma_f32_16x16x32_bf16 v[126:129], v[130:133], v[186:189], v[126:129]
	v_mfma_f32_16x16x32_bf16 v[126:129], v[134:137], v[190:193], v[126:129]
	v_mfma_f32_16x16x32_bf16 v[122:125], v[138:141], v[186:189], v[122:125]
	v_mfma_f32_16x16x32_bf16 v[122:125], v[142:145], v[190:193], v[122:125]
	v_mfma_f32_16x16x32_bf16 v[118:121], v[130:133], v[194:197], v[118:121]
	v_mfma_f32_16x16x32_bf16 v[118:121], v[134:137], v[198:201], v[118:121]
	v_mfma_f32_16x16x32_bf16 v[114:117], v[138:141], v[194:197], v[114:117]
	v_mfma_f32_16x16x32_bf16 v[114:117], v[142:145], v[198:201], v[114:117]
	v_mfma_f32_16x16x32_bf16 v[110:113], v[130:133], v[202:205], v[110:113]
	v_mfma_f32_16x16x32_bf16 v[110:113], v[134:137], v[206:209], v[110:113]
	v_mfma_f32_16x16x32_bf16 v[106:109], v[138:141], v[202:205], v[106:109]
	v_mfma_f32_16x16x32_bf16 v[106:109], v[142:145], v[206:209], v[106:109]
	v_mfma_f32_16x16x32_bf16 v[102:105], v[130:133], v[210:213], v[102:105]
	v_mfma_f32_16x16x32_bf16 v[102:105], v[134:137], v[214:217], v[102:105]
	v_mfma_f32_16x16x32_bf16 v[98:101], v[138:141], v[210:213], v[98:101]
	v_mfma_f32_16x16x32_bf16 v[98:101], v[142:145], v[214:217], v[98:101]
	v_mfma_f32_16x16x32_bf16 v[62:65], v[146:149], v[186:189], v[62:65]
	v_mfma_f32_16x16x32_bf16 v[62:65], v[164:167], v[190:193], v[62:65]
	v_mfma_f32_16x16x32_bf16 v[58:61], v[168:171], v[186:189], v[58:61]
	v_mfma_f32_16x16x32_bf16 v[58:61], v[182:185], v[190:193], v[58:61]
	v_mfma_f32_16x16x32_bf16 v[54:57], v[146:149], v[194:197], v[54:57]
	v_mfma_f32_16x16x32_bf16 v[54:57], v[164:167], v[198:201], v[54:57]
	v_mfma_f32_16x16x32_bf16 v[50:53], v[168:171], v[194:197], v[50:53]
	v_mfma_f32_16x16x32_bf16 v[50:53], v[182:185], v[198:201], v[50:53]
	v_mfma_f32_16x16x32_bf16 v[46:49], v[146:149], v[202:205], v[46:49]
	v_mfma_f32_16x16x32_bf16 v[46:49], v[164:167], v[206:209], v[46:49]
	v_mfma_f32_16x16x32_bf16 v[42:45], v[168:171], v[202:205], v[42:45]
	v_mfma_f32_16x16x32_bf16 v[42:45], v[182:185], v[206:209], v[42:45]
	v_mfma_f32_16x16x32_bf16 v[38:41], v[146:149], v[210:213], v[38:41]
	v_mfma_f32_16x16x32_bf16 v[38:41], v[164:167], v[214:217], v[38:41]
	v_mfma_f32_16x16x32_bf16 v[34:37], v[168:171], v[210:213], v[34:37]
	v_mfma_f32_16x16x32_bf16 v[34:37], v[182:185], v[214:217], v[34:37]
	s_barrier
	s_setprio 0
	s_mov_b32 m0, s16
	s_mov_b32 s42, s78
	s_mov_b32 s43, s79
	ds_read_b128 v[186:189], v158 offset:16384
	ds_read_b128 v[190:193], v158 offset:17408
	ds_read_b128 v[194:197], v158 offset:18432
	ds_read_b128 v[198:201], v158 offset:19456
	ds_read_b128 v[202:205], v158 offset:20480
	ds_read_b128 v[206:209], v158 offset:21504
	ds_read_b128 v[210:213], v158 offset:22528
	ds_read_b128 v[214:217], v158 offset:23552
	buffer_load_dwordx4 v151, s[40:43], s69 offen lds
	s_mov_b32 m0, s17
	s_add_i32 s71, s69, 0x80000
	buffer_load_dwordx4 v153, s[40:43], s69 offen lds
	s_mov_b32 m0, s18
	s_nop 0
	buffer_load_dwordx4 v151, s[40:43], s71 offen lds
	s_mov_b32 m0, s19
	s_nop 0
	buffer_load_dwordx4 v153, s[40:43], s71 offen lds
	s_mov_b32 m0, s15
	s_nop 0
	buffer_load_dwordx4 v150, s[76:79], s70 offen lds
	s_mov_b32 m0, s20
	s_nop 0
	buffer_load_dwordx4 v152, s[76:79], s70 offen lds
	s_waitcnt vmcnt(8)
	s_waitcnt lgkmcnt(0)
	s_setprio 1
	s_barrier
	v_mfma_f32_16x16x32_bf16 v[94:97], v[130:133], v[186:189], v[94:97]
	v_mfma_f32_16x16x32_bf16 v[94:97], v[134:137], v[190:193], v[94:97]
	v_mfma_f32_16x16x32_bf16 v[90:93], v[138:141], v[186:189], v[90:93]
	v_mfma_f32_16x16x32_bf16 v[90:93], v[142:145], v[190:193], v[90:93]
	v_mfma_f32_16x16x32_bf16 v[86:89], v[130:133], v[194:197], v[86:89]
	v_mfma_f32_16x16x32_bf16 v[86:89], v[134:137], v[198:201], v[86:89]
	v_mfma_f32_16x16x32_bf16 v[82:85], v[138:141], v[194:197], v[82:85]
	v_mfma_f32_16x16x32_bf16 v[82:85], v[142:145], v[198:201], v[82:85]
	v_mfma_f32_16x16x32_bf16 v[78:81], v[130:133], v[202:205], v[78:81]
	v_mfma_f32_16x16x32_bf16 v[78:81], v[134:137], v[206:209], v[78:81]
	v_mfma_f32_16x16x32_bf16 v[74:77], v[138:141], v[202:205], v[74:77]
	v_mfma_f32_16x16x32_bf16 v[74:77], v[142:145], v[206:209], v[74:77]
	v_mfma_f32_16x16x32_bf16 v[70:73], v[130:133], v[210:213], v[70:73]
	v_mfma_f32_16x16x32_bf16 v[70:73], v[134:137], v[214:217], v[70:73]
	v_mfma_f32_16x16x32_bf16 v[66:69], v[138:141], v[210:213], v[66:69]
	v_mfma_f32_16x16x32_bf16 v[66:69], v[142:145], v[214:217], v[66:69]
	v_mfma_f32_16x16x32_bf16 v[30:33], v[146:149], v[186:189], v[30:33]
	v_mfma_f32_16x16x32_bf16 v[30:33], v[164:167], v[190:193], v[30:33]
	v_mfma_f32_16x16x32_bf16 v[26:29], v[168:171], v[186:189], v[26:29]
	v_mfma_f32_16x16x32_bf16 v[26:29], v[182:185], v[190:193], v[26:29]
	v_mfma_f32_16x16x32_bf16 v[22:25], v[146:149], v[194:197], v[22:25]
	v_mfma_f32_16x16x32_bf16 v[22:25], v[164:167], v[198:201], v[22:25]
	v_mfma_f32_16x16x32_bf16 v[18:21], v[168:171], v[194:197], v[18:21]
	v_mfma_f32_16x16x32_bf16 v[18:21], v[182:185], v[198:201], v[18:21]
	v_mfma_f32_16x16x32_bf16 v[14:17], v[146:149], v[202:205], v[14:17]
	v_mfma_f32_16x16x32_bf16 v[14:17], v[164:167], v[206:209], v[14:17]
	v_mfma_f32_16x16x32_bf16 v[10:13], v[168:171], v[202:205], v[10:13]
	v_mfma_f32_16x16x32_bf16 v[10:13], v[182:185], v[206:209], v[10:13]
	v_mfma_f32_16x16x32_bf16 v[6:9], v[146:149], v[210:213], v[6:9]
	v_mfma_f32_16x16x32_bf16 v[6:9], v[164:167], v[214:217], v[6:9]
	v_mfma_f32_16x16x32_bf16 v[2:5], v[168:171], v[210:213], v[2:5]
	v_mfma_f32_16x16x32_bf16 v[2:5], v[182:185], v[214:217], v[2:5]
	s_barrier
; #define PG8_STAGEX(rs, bufoff, soff, voff) do { _Pragma("unroll") for (int _i = 0; _i < 2; ++_i) \
;         __builtin_amdgcn_raw_ptr_buffer_load_lds(rs, (LAS unsigned*)(lds + (bufoff) + ldsw + _i * 8192), 16, (voff)[_i], (soff), 0, 0); } while (0)
; #define PG8_LDA(dst, b, h) do { _Pragma("unroll") for (int m = 0; m < 4; ++m) _Pragma("unroll") for (int k = 0; k < 2; ++k) dst[m][k] = *(const LAS bf16x8*)(lds + PG8_SA(b, h) + aoff + m * 2048 + k * 1024); } while (0)
; #define PG8_LDB(dst, b, h) do { _Pragma("unroll") for (int n = 0; n < 2; ++n) _Pragma("unroll") for (int k = 0; k < 2; ++k) dst[n][k] = *(const LAS bf16x8*)(lds + PG8_SB(b, h) + boff + n * 2048 + k * 1024); } while (0)
; #define PG8_WAIT_V(n) asm volatile("s_waitcnt vmcnt(" #n ")" ::: "memory")
; #define PG8_WAIT_L(n) asm volatile("s_waitcnt lgkmcnt(" #n ")" ::: "memory")
; #define PG8_BAR __builtin_amdgcn_s_barrier()
; #define PG8_SCHED __builtin_amdgcn_sched_barrier(0)
;     ...
;             PG8_LDB(B0, 1, 0); PG8_LDB(B1, 1, 1); PG8_SCHED; PG8_LDA(At, 1, 0); PG8_STAGEX(rsA, PG8_SA(0, 1), a2 + hstepA, voffA);
;             PG8_WAIT_V(8); PG8_WAIT_L(0); PG8_BAR; PG8_MMA(0, 0, At, B0); PG8_MMA(0, 1, At, B1); PG8_BAR; PG8_SCHED;
;             PG8_LDA(At, 1, 1); PG8_STAGEX(rsB, PG8_SB(1, 0), b3, voffB); PG8_STAGEX(rsB, PG8_SB(1, 1), b3 + hstepB, voffB); PG8_STAGEX(rsA, PG8_SA(1, 0), a3, voffA);
;             PG8_WAIT_V(8); PG8_WAIT_L(0); PG8_BAR; PG8_MMA(1, 0, At, B0); PG8_MMA(1, 1, At, B1); PG8_BAR; PG8_SCHED;
;         }
	s_setprio 0
	v_add_u32_e32 v142, 0x18000, v157
	v_add_u32_e32 v159, 0x1c000, v157
	ds_read_b128 v[130:133], v142
	ds_read_b128 v[134:137], v142 offset:1024
	ds_read_b128 v[138:141], v142 offset:2048
	ds_read_b128 v[142:145], v142 offset:3072
	ds_read_b128 v[146:149], v159
	ds_read_b128 v[164:167], v159 offset:1024
	ds_read_b128 v[168:171], v159 offset:2048
	ds_read_b128 v[182:185], v159 offset:3072
	s_add_i32 s70, s70, 0x80000
	s_mov_b32 m0, s21
	ds_read_b128 v[186:189], v158 offset:32768
	ds_read_b128 v[190:193], v158 offset:33792
	ds_read_b128 v[194:197], v158 offset:34816
	ds_read_b128 v[198:201], v158 offset:35840
	ds_read_b128 v[202:205], v158 offset:36864
	ds_read_b128 v[206:209], v158 offset:37888
	ds_read_b128 v[210:213], v158 offset:38912
	ds_read_b128 v[214:217], v158 offset:39936
	buffer_load_dwordx4 v150, s[76:79], s70 offen lds
	s_mov_b32 m0, s22
	s_nop 0
	buffer_load_dwordx4 v152, s[76:79], s70 offen lds
	s_waitcnt vmcnt(8)
	s_waitcnt lgkmcnt(0)
	s_setprio 1
	s_barrier
	v_mfma_f32_16x16x32_bf16 v[126:129], v[130:133], v[186:189], v[126:129]
	v_mfma_f32_16x16x32_bf16 v[126:129], v[134:137], v[190:193], v[126:129]
	v_mfma_f32_16x16x32_bf16 v[122:125], v[138:141], v[186:189], v[122:125]
	v_mfma_f32_16x16x32_bf16 v[122:125], v[142:145], v[190:193], v[122:125]
	v_mfma_f32_16x16x32_bf16 v[118:121], v[130:133], v[194:197], v[118:121]
	v_mfma_f32_16x16x32_bf16 v[118:121], v[134:137], v[198:201], v[118:121]
	v_mfma_f32_16x16x32_bf16 v[114:117], v[138:141], v[194:197], v[114:117]
	v_mfma_f32_16x16x32_bf16 v[114:117], v[142:145], v[198:201], v[114:117]
	v_mfma_f32_16x16x32_bf16 v[110:113], v[130:133], v[202:205], v[110:113]
	v_mfma_f32_16x16x32_bf16 v[110:113], v[134:137], v[206:209], v[110:113]
	v_mfma_f32_16x16x32_bf16 v[106:109], v[138:141], v[202:205], v[106:109]
	v_mfma_f32_16x16x32_bf16 v[106:109], v[142:145], v[206:209], v[106:109]
	v_mfma_f32_16x16x32_bf16 v[102:105], v[130:133], v[210:213], v[102:105]
	v_mfma_f32_16x16x32_bf16 v[102:105], v[134:137], v[214:217], v[102:105]
	v_mfma_f32_16x16x32_bf16 v[98:101], v[138:141], v[210:213], v[98:101]
	v_mfma_f32_16x16x32_bf16 v[98:101], v[142:145], v[214:217], v[98:101]
	v_mfma_f32_16x16x32_bf16 v[62:65], v[146:149], v[186:189], v[62:65]
	v_mfma_f32_16x16x32_bf16 v[62:65], v[164:167], v[190:193], v[62:65]
	v_mfma_f32_16x16x32_bf16 v[58:61], v[168:171], v[186:189], v[58:61]
	v_mfma_f32_16x16x32_bf16 v[58:61], v[182:185], v[190:193], v[58:61]
	v_mfma_f32_16x16x32_bf16 v[54:57], v[146:149], v[194:197], v[54:57]
	v_mfma_f32_16x16x32_bf16 v[54:57], v[164:167], v[198:201], v[54:57]
	v_mfma_f32_16x16x32_bf16 v[50:53], v[168:171], v[194:197], v[50:53]
	v_mfma_f32_16x16x32_bf16 v[50:53], v[182:185], v[198:201], v[50:53]
	v_mfma_f32_16x16x32_bf16 v[46:49], v[146:149], v[202:205], v[46:49]
	v_mfma_f32_16x16x32_bf16 v[46:49], v[164:167], v[206:209], v[46:49]
	v_mfma_f32_16x16x32_bf16 v[42:45], v[168:171], v[202:205], v[42:45]
	v_mfma_f32_16x16x32_bf16 v[42:45], v[182:185], v[206:209], v[42:45]
	v_mfma_f32_16x16x32_bf16 v[38:41], v[146:149], v[210:213], v[38:41]
	v_mfma_f32_16x16x32_bf16 v[38:41], v[164:167], v[214:217], v[38:41]
	v_mfma_f32_16x16x32_bf16 v[34:37], v[168:171], v[210:213], v[34:37]
	v_mfma_f32_16x16x32_bf16 v[34:37], v[182:185], v[214:217], v[34:37]
	s_barrier
	s_setprio 0
	s_mov_b32 m0, s23
	s_or_b32 s70, s69, 0x80
	ds_read_b128 v[186:189], v158 offset:49152
	ds_read_b128 v[190:193], v158 offset:50176
	ds_read_b128 v[194:197], v158 offset:51200
	ds_read_b128 v[198:201], v158 offset:52224
	ds_read_b128 v[202:205], v158 offset:53248
	ds_read_b128 v[206:209], v158 offset:54272
	ds_read_b128 v[210:213], v158 offset:55296
	ds_read_b128 v[214:217], v158 offset:56320
	buffer_load_dwordx4 v151, s[40:43], s70 offen lds
	s_mov_b32 m0, s24
	s_add_i32 s69, s69, 0x80080
	buffer_load_dwordx4 v153, s[40:43], s70 offen lds
	s_mov_b32 m0, s27
	s_nop 0
	buffer_load_dwordx4 v151, s[40:43], s69 offen lds
	s_mov_b32 m0, s28
	s_nop 0
	buffer_load_dwordx4 v153, s[40:43], s69 offen lds
	s_mov_b32 m0, s25
	s_nop 0
	buffer_load_dwordx4 v150, s[76:79], s68 offen lds
	s_mov_b32 m0, s26
	s_nop 0
	buffer_load_dwordx4 v152, s[76:79], s68 offen lds
	s_waitcnt vmcnt(8)
	s_waitcnt lgkmcnt(0)
	s_setprio 1
	s_barrier
	v_mfma_f32_16x16x32_bf16 v[94:97], v[130:133], v[186:189], v[94:97]
	v_mfma_f32_16x16x32_bf16 v[94:97], v[134:137], v[190:193], v[94:97]
	v_mfma_f32_16x16x32_bf16 v[90:93], v[138:141], v[186:189], v[90:93]
	v_mfma_f32_16x16x32_bf16 v[90:93], v[142:145], v[190:193], v[90:93]
	v_mfma_f32_16x16x32_bf16 v[86:89], v[130:133], v[194:197], v[86:89]
	v_mfma_f32_16x16x32_bf16 v[86:89], v[134:137], v[198:201], v[86:89]
	v_mfma_f32_16x16x32_bf16 v[82:85], v[138:141], v[194:197], v[82:85]
	v_mfma_f32_16x16x32_bf16 v[82:85], v[142:145], v[198:201], v[82:85]
	v_mfma_f32_16x16x32_bf16 v[78:81], v[130:133], v[202:205], v[78:81]
	v_mfma_f32_16x16x32_bf16 v[78:81], v[134:137], v[206:209], v[78:81]
	v_mfma_f32_16x16x32_bf16 v[74:77], v[138:141], v[202:205], v[74:77]
	v_mfma_f32_16x16x32_bf16 v[74:77], v[142:145], v[206:209], v[74:77]
	v_mfma_f32_16x16x32_bf16 v[70:73], v[130:133], v[210:213], v[70:73]
	v_mfma_f32_16x16x32_bf16 v[70:73], v[134:137], v[214:217], v[70:73]
	v_mfma_f32_16x16x32_bf16 v[66:69], v[138:141], v[210:213], v[66:69]
	v_mfma_f32_16x16x32_bf16 v[66:69], v[142:145], v[214:217], v[66:69]
	v_mfma_f32_16x16x32_bf16 v[30:33], v[146:149], v[186:189], v[30:33]
	v_mfma_f32_16x16x32_bf16 v[30:33], v[164:167], v[190:193], v[30:33]
	v_mfma_f32_16x16x32_bf16 v[26:29], v[168:171], v[186:189], v[26:29]
	v_mfma_f32_16x16x32_bf16 v[26:29], v[182:185], v[190:193], v[26:29]
	v_mfma_f32_16x16x32_bf16 v[22:25], v[146:149], v[194:197], v[22:25]
	v_mfma_f32_16x16x32_bf16 v[22:25], v[164:167], v[198:201], v[22:25]
	v_mfma_f32_16x16x32_bf16 v[18:21], v[168:171], v[194:197], v[18:21]
	v_mfma_f32_16x16x32_bf16 v[18:21], v[182:185], v[198:201], v[18:21]
	v_mfma_f32_16x16x32_bf16 v[14:17], v[146:149], v[202:205], v[14:17]
	v_mfma_f32_16x16x32_bf16 v[14:17], v[164:167], v[206:209], v[14:17]
	v_mfma_f32_16x16x32_bf16 v[10:13], v[168:171], v[202:205], v[10:13]
	v_mfma_f32_16x16x32_bf16 v[10:13], v[182:185], v[206:209], v[10:13]
	v_mfma_f32_16x16x32_bf16 v[6:9], v[146:149], v[210:213], v[6:9]
	v_mfma_f32_16x16x32_bf16 v[6:9], v[164:167], v[214:217], v[6:9]
	v_mfma_f32_16x16x32_bf16 v[2:5], v[168:171], v[210:213], v[2:5]
	v_mfma_f32_16x16x32_bf16 v[2:5], v[182:185], v[214:217], v[2:5]
	s_barrier
	s_setprio 0
	s_add_i32 s67, s67, 2
	s_addk_i32 s62, 0x100
	s_addk_i32 s63, 0x100
	s_cmp_gt_u32 s67, 29
	s_cbranch_scc0 .LBB0_1274
	s_and_b64 vcc, exec, s[50:51]
	s_cbranch_vccz .LBB0_1277
	s_barrier

; #define PG8_STAGEX(rs, bufoff, soff, voff) do { _Pragma("unroll") for (int _i = 0; _i < 2; ++_i) \
;         __builtin_amdgcn_raw_ptr_buffer_load_lds(rs, (LAS unsigned*)(lds + (bufoff) + ldsw + _i * 8192), 16, (voff)[_i], (soff), 0, 0); } while (0)
; #define PG8_LDA(dst, b, h) do { _Pragma("unroll") for (int m = 0; m < 4; ++m) _Pragma("unroll") for (int k = 0; k < 2; ++k) dst[m][k] = *(const LAS bf16x8*)(lds + PG8_SA(b, h) + aoff + m * 2048 + k * 1024); } while (0)
; #define PG8_LDB(dst, b, h) do { _Pragma("unroll") for (int n = 0; n < 2; ++n) _Pragma("unroll") for (int k = 0; k < 2; ++k) dst[n][k] = *(const LAS bf16x8*)(lds + PG8_SB(b, h) + boff + n * 2048 + k * 1024); } while (0)
; #define PG8_WAIT_V(n) asm volatile("s_waitcnt vmcnt(" #n ")" ::: "memory")
; #define PG8_WAIT_L(n) asm volatile("s_waitcnt lgkmcnt(" #n ")" ::: "memory")
; #define PG8_BAR __builtin_amdgcn_s_barrier()
; #define PG8_SCHED __builtin_amdgcn_sched_barrier(0)
;     ...
;             for (int t = 0; t < nt; t += 2) {
;                 const bool last = (t == nt - 2);
;                 const unsigned a1 = cA + (unsigned)(t + 1) * kstep;
;                 const unsigned a2 = last ? nA : cA + (unsigned)(t + 2) * kstep, b2 = last ? nB : cB + (unsigned)(t + 2) * kstep;
;                 const unsigned a3 = a2 + kstep, b3 = b2 + kstep;
;                 if (w0) { PG8_LDB(B0, 0, 0); PG8_LDB(B1, 0, 1); PG8_SCHED; PG8_LDA(At, 0, 0); }
;                 PG8_WAIT_L(0); PG8_BAR; if (w0) { PG8_MMA(0, 0, At, B0); PG8_MMA(0, 1, At, B1); } PG8_BAR; PG8_SCHED;
;                 PG8_STAGEX(rsB, PG8_SB(0, 0), b2, voffB); PG8_STAGEX(rsB, PG8_SB(0, 1), b2 + hstepB, voffB); PG8_STAGEX(rsA, PG8_SA(0, 0), a2, voffA);
;                 PG8_WAIT_V(6); PG8_BAR; PG8_BAR; PG8_SCHED;
.LBB0_1287:
	v_add_u32_e32 v86, 0x10000, v72
	v_add_u32_e32 v102, 0x14000, v72
	ds_read_b128 v[74:77], v86
	ds_read_b128 v[78:81], v86 offset:1024
	ds_read_b128 v[82:85], v86 offset:2048
	ds_read_b128 v[86:89], v86 offset:3072
	ds_read_b128 v[90:93], v102
	ds_read_b128 v[94:97], v102 offset:1024
	ds_read_b128 v[98:101], v102 offset:2048
	ds_read_b128 v[102:105], v102 offset:3072
	s_cmp_lg_u32 s29, 28
	s_cselect_b32 s30, s28, 0
	s_add_i32 s31, s30, s19
	s_or_b32 s35, s31, 0x80
	s_add_i32 s30, s30, s13
	ds_read_b128 v[106:109], v73
	ds_read_b128 v[110:113], v73 offset:1024
	ds_read_b128 v[114:117], v73 offset:2048
	ds_read_b128 v[118:121], v73 offset:3072
	ds_read_b128 v[122:125], v73 offset:4096
	ds_read_b128 v[126:129], v73 offset:5120
	ds_read_b128 v[130:133], v73 offset:6144
	ds_read_b128 v[134:137], v73 offset:7168
	s_waitcnt lgkmcnt(0)
	s_setprio 1
	s_barrier
	v_mfma_f32_16x16x32_bf16 v[62:65], v[74:77], v[106:109], v[62:65]
	v_mfma_f32_16x16x32_bf16 v[62:65], v[78:81], v[110:113], v[62:65]
	v_mfma_f32_16x16x32_bf16 v[58:61], v[82:85], v[106:109], v[58:61]
	v_mfma_f32_16x16x32_bf16 v[58:61], v[86:89], v[110:113], v[58:61]
	v_mfma_f32_16x16x32_bf16 v[54:57], v[74:77], v[114:117], v[54:57]
	v_mfma_f32_16x16x32_bf16 v[54:57], v[78:81], v[118:121], v[54:57]
	v_mfma_f32_16x16x32_bf16 v[50:53], v[82:85], v[114:117], v[50:53]
	v_mfma_f32_16x16x32_bf16 v[50:53], v[86:89], v[118:121], v[50:53]
	v_mfma_f32_16x16x32_bf16 v[46:49], v[74:77], v[122:125], v[46:49]
	v_mfma_f32_16x16x32_bf16 v[46:49], v[78:81], v[126:129], v[46:49]
	v_mfma_f32_16x16x32_bf16 v[42:45], v[82:85], v[122:125], v[42:45]
	v_mfma_f32_16x16x32_bf16 v[42:45], v[86:89], v[126:129], v[42:45]
	v_mfma_f32_16x16x32_bf16 v[38:41], v[74:77], v[130:133], v[38:41]
	v_mfma_f32_16x16x32_bf16 v[38:41], v[78:81], v[134:137], v[38:41]
	v_mfma_f32_16x16x32_bf16 v[34:37], v[82:85], v[130:133], v[34:37]
	v_mfma_f32_16x16x32_bf16 v[34:37], v[86:89], v[134:137], v[34:37]
	v_mfma_f32_16x16x32_bf16 v[30:33], v[90:93], v[106:109], v[30:33]
	v_mfma_f32_16x16x32_bf16 v[30:33], v[94:97], v[110:113], v[30:33]
	v_mfma_f32_16x16x32_bf16 v[26:29], v[98:101], v[106:109], v[26:29]
	v_mfma_f32_16x16x32_bf16 v[26:29], v[102:105], v[110:113], v[26:29]
	v_mfma_f32_16x16x32_bf16 v[22:25], v[90:93], v[114:117], v[22:25]
	v_mfma_f32_16x16x32_bf16 v[22:25], v[94:97], v[118:121], v[22:25]
	v_mfma_f32_16x16x32_bf16 v[18:21], v[98:101], v[114:117], v[18:21]
	v_mfma_f32_16x16x32_bf16 v[18:21], v[102:105], v[118:121], v[18:21]
	v_mfma_f32_16x16x32_bf16 v[14:17], v[90:93], v[122:125], v[14:17]
	v_mfma_f32_16x16x32_bf16 v[14:17], v[94:97], v[126:129], v[14:17]
	v_mfma_f32_16x16x32_bf16 v[10:13], v[98:101], v[122:125], v[10:13]
	v_mfma_f32_16x16x32_bf16 v[10:13], v[102:105], v[126:129], v[10:13]
	v_mfma_f32_16x16x32_bf16 v[6:9], v[90:93], v[130:133], v[6:9]
	v_mfma_f32_16x16x32_bf16 v[6:9], v[94:97], v[134:137], v[6:9]
	v_mfma_f32_16x16x32_bf16 v[2:5], v[98:101], v[130:133], v[2:5]
	v_mfma_f32_16x16x32_bf16 v[2:5], v[102:105], v[134:137], v[2:5]
	s_barrier
	s_setprio 0
	s_mov_b32 m0, s15
	s_mov_b32 s42, s78
	s_mov_b32 s43, s79
	buffer_load_dwordx4 v67, s[40:43], s30 offen lds
	s_mov_b32 m0, s16
	s_add_i32 s38, s30, 0x80000
	buffer_load_dwordx4 v69, s[40:43], s30 offen lds
	s_mov_b32 m0, s17
	s_nop 0
	buffer_load_dwordx4 v67, s[40:43], s38 offen lds
	s_mov_b32 m0, s18
	s_nop 0
	buffer_load_dwordx4 v69, s[40:43], s38 offen lds
	s_mov_b32 m0, s14
	s_nop 0
	buffer_load_dwordx4 v66, s[76:79], s31 offen lds
	s_mov_b32 m0, s20
	s_nop 0
	buffer_load_dwordx4 v68, s[76:79], s31 offen lds
	s_waitcnt vmcnt(6)
	s_barrier
	s_barrier
; #define PG8_STAGEX(rs, bufoff, soff, voff) do { _Pragma("unroll") for (int _i = 0; _i < 2; ++_i) \
;         __builtin_amdgcn_raw_ptr_buffer_load_lds(rs, (LAS unsigned*)(lds + (bufoff) + ldsw + _i * 8192), 16, (voff)[_i], (soff), 0, 0); } while (0)
; #define PG8_LDA(dst, b, h) do { _Pragma("unroll") for (int m = 0; m < 4; ++m) _Pragma("unroll") for (int k = 0; k < 2; ++k) dst[m][k] = *(const LAS bf16x8*)(lds + PG8_SA(b, h) + aoff + m * 2048 + k * 1024); } while (0)
; #define PG8_LDB(dst, b, h) do { _Pragma("unroll") for (int n = 0; n < 2; ++n) _Pragma("unroll") for (int k = 0; k < 2; ++k) dst[n][k] = *(const LAS bf16x8*)(lds + PG8_SB(b, h) + boff + n * 2048 + k * 1024); } while (0)
; #define PG8_WAIT_V(n) asm volatile("s_waitcnt vmcnt(" #n ")" ::: "memory")
; #define PG8_WAIT_L(n) asm volatile("s_waitcnt lgkmcnt(" #n ")" ::: "memory")
; #define PG8_BAR __builtin_amdgcn_s_barrier()
; #define PG8_SCHED __builtin_amdgcn_sched_barrier(0)
;     ...
;                 if (w0) { PG8_LDB(B0, 1, 0); PG8_LDB(B1, 1, 1); PG8_SCHED; PG8_LDA(At, 1, 0); }
;                 PG8_WAIT_L(0); PG8_BAR; if (w0) { PG8_MMA(0, 0, At, B0); PG8_MMA(0, 1, At, B1); } PG8_BAR; PG8_SCHED;
;                 PG8_STAGEX(rsB, PG8_SB(1, 0), b3, voffB); PG8_STAGEX(rsB, PG8_SB(1, 1), b3 + hstepB, voffB); PG8_STAGEX(rsA, PG8_SA(1, 0), a3, voffA);
;                 PG8_WAIT_V(6); PG8_BAR; PG8_BAR; PG8_SCHED;
;             }
;         }
;         if (wr == 0) PG8_BAR;
	v_add_u32_e32 v86, 0x18000, v72
	v_add_u32_e32 v102, 0x1c000, v72
	ds_read_b128 v[74:77], v86
	ds_read_b128 v[78:81], v86 offset:1024
	ds_read_b128 v[82:85], v86 offset:2048
	ds_read_b128 v[86:89], v86 offset:3072
	ds_read_b128 v[90:93], v102
	ds_read_b128 v[94:97], v102 offset:1024
	ds_read_b128 v[98:101], v102 offset:2048
	ds_read_b128 v[102:105], v102 offset:3072
	ds_read_b128 v[106:109], v73 offset:32768
	ds_read_b128 v[110:113], v73 offset:33792
	ds_read_b128 v[114:117], v73 offset:34816
	ds_read_b128 v[118:121], v73 offset:35840
	ds_read_b128 v[122:125], v73 offset:36864
	ds_read_b128 v[126:129], v73 offset:37888
	ds_read_b128 v[130:133], v73 offset:38912
	ds_read_b128 v[134:137], v73 offset:39936
	s_waitcnt lgkmcnt(0)
	s_setprio 1
	s_barrier
	v_mfma_f32_16x16x32_bf16 v[62:65], v[74:77], v[106:109], v[62:65]
	v_mfma_f32_16x16x32_bf16 v[58:61], v[82:85], v[106:109], v[58:61]
	v_mfma_f32_16x16x32_bf16 v[54:57], v[74:77], v[114:117], v[54:57]
	v_mfma_f32_16x16x32_bf16 v[50:53], v[82:85], v[114:117], v[50:53]
	v_mfma_f32_16x16x32_bf16 v[46:49], v[74:77], v[122:125], v[46:49]
	v_mfma_f32_16x16x32_bf16 v[42:45], v[82:85], v[122:125], v[42:45]
	v_mfma_f32_16x16x32_bf16 v[38:41], v[74:77], v[130:133], v[38:41]
	v_mfma_f32_16x16x32_bf16 v[34:37], v[82:85], v[130:133], v[34:37]
	v_mfma_f32_16x16x32_bf16 v[62:65], v[78:81], v[110:113], v[62:65]
	v_mfma_f32_16x16x32_bf16 v[58:61], v[86:89], v[110:113], v[58:61]
	v_mfma_f32_16x16x32_bf16 v[54:57], v[78:81], v[118:121], v[54:57]
	v_mfma_f32_16x16x32_bf16 v[50:53], v[86:89], v[118:121], v[50:53]
	v_mfma_f32_16x16x32_bf16 v[46:49], v[78:81], v[126:129], v[46:49]
	v_mfma_f32_16x16x32_bf16 v[42:45], v[86:89], v[126:129], v[42:45]
	v_mfma_f32_16x16x32_bf16 v[38:41], v[78:81], v[134:137], v[38:41]
	v_mfma_f32_16x16x32_bf16 v[34:37], v[86:89], v[134:137], v[34:37]
	v_mfma_f32_16x16x32_bf16 v[30:33], v[90:93], v[106:109], v[30:33]
	s_or_b32 s31, s30, 0x80
	v_mfma_f32_16x16x32_bf16 v[26:29], v[98:101], v[106:109], v[26:29]
	v_mfma_f32_16x16x32_bf16 v[22:25], v[90:93], v[114:117], v[22:25]
	v_mfma_f32_16x16x32_bf16 v[18:21], v[98:101], v[114:117], v[18:21]
	v_mfma_f32_16x16x32_bf16 v[14:17], v[90:93], v[122:125], v[14:17]
	v_mfma_f32_16x16x32_bf16 v[10:13], v[98:101], v[122:125], v[10:13]
	v_mfma_f32_16x16x32_bf16 v[6:9], v[90:93], v[130:133], v[6:9]
	v_mfma_f32_16x16x32_bf16 v[2:5], v[98:101], v[130:133], v[2:5]
	v_mfma_f32_16x16x32_bf16 v[30:33], v[94:97], v[110:113], v[30:33]
	v_mfma_f32_16x16x32_bf16 v[26:29], v[102:105], v[110:113], v[26:29]
	v_mfma_f32_16x16x32_bf16 v[22:25], v[94:97], v[118:121], v[22:25]
	v_mfma_f32_16x16x32_bf16 v[18:21], v[102:105], v[118:121], v[18:21]
	v_mfma_f32_16x16x32_bf16 v[14:17], v[94:97], v[126:129], v[14:17]
	v_mfma_f32_16x16x32_bf16 v[10:13], v[102:105], v[126:129], v[10:13]
	v_mfma_f32_16x16x32_bf16 v[6:9], v[94:97], v[134:137], v[6:9]
	v_mfma_f32_16x16x32_bf16 v[2:5], v[102:105], v[134:137], v[2:5]
	s_barrier
	s_setprio 0
	s_mov_b32 m0, s22
	s_add_i32 s30, s30, 0x80080
	buffer_load_dwordx4 v67, s[40:43], s31 offen lds
	s_mov_b32 m0, s23
	s_nop 0
	buffer_load_dwordx4 v69, s[40:43], s31 offen lds
	s_mov_b32 m0, s26
	s_nop 0
	buffer_load_dwordx4 v67, s[40:43], s30 offen lds
	s_mov_b32 m0, s27
	s_nop 0
	buffer_load_dwordx4 v69, s[40:43], s30 offen lds
	s_mov_b32 m0, s24
	s_nop 0
	buffer_load_dwordx4 v66, s[76:79], s35 offen lds
	s_mov_b32 m0, s25
	s_nop 0
	buffer_load_dwordx4 v68, s[76:79], s35 offen lds
	s_waitcnt vmcnt(6)
	s_barrier
	s_barrier
	s_addk_i32 s28, 0x100
	s_add_i32 s29, s29, 2
	s_cmp_gt_u32 s29, 29
	s_cbranch_scc0 .LBB0_1287
	s_cmpk_lt_u32 s12, 0x100
	s_cbranch_scc0 .LBB0_1290
	s_barrier

; #define PG8_STAGEX(rs, bufoff, soff, voff) do { _Pragma("unroll") for (int _i = 0; _i < 2; ++_i) \
;         __builtin_amdgcn_raw_ptr_buffer_load_lds(rs, (LAS unsigned*)(lds + (bufoff) + ldsw + _i * 8192), 16, (voff)[_i], (soff), 0, 0); } while (0)
; #define PG8_LDA(dst, b, h) do { _Pragma("unroll") for (int m = 0; m < 4; ++m) _Pragma("unroll") for (int k = 0; k < 2; ++k) dst[m][k] = *(const LAS bf16x8*)(lds + PG8_SA(b, h) + aoff + m * 2048 + k * 1024); } while (0)
; #define PG8_LDB(dst, b, h) do { _Pragma("unroll") for (int n = 0; n < 2; ++n) _Pragma("unroll") for (int k = 0; k < 2; ++k) dst[n][k] = *(const LAS bf16x8*)(lds + PG8_SB(b, h) + boff + n * 2048 + k * 1024); } while (0)
; #define PG8_WAIT_V(n) asm volatile("s_waitcnt vmcnt(" #n ")" ::: "memory")
; #define PG8_WAIT_L(n) asm volatile("s_waitcnt lgkmcnt(" #n ")" ::: "memory")
; #define PG8_BAR __builtin_amdgcn_s_barrier()
; #define PG8_SCHED __builtin_amdgcn_sched_barrier(0)
;     ...
;         for (int t = 0; t < nt; t += 2) {
;             const bool last = (t == nt - 2);
;             const unsigned a1 = cA + (unsigned)(t + 1) * kstep;
;             const unsigned a2 = last ? nA : cA + (unsigned)(t + 2) * kstep, b2 = last ? nB : cB + (unsigned)(t + 2) * kstep;
;             const unsigned a3 = a2 + kstep, b3 = b2 + kstep;
;             PG8_LDB(B0, 0, 0); PG8_LDB(B1, 0, 1); PG8_SCHED; PG8_LDA(At, 0, 0); PG8_STAGEX(rsA, PG8_SA(1, 1), a1 + hstepA, voffA);
;             PG8_WAIT_V(8); PG8_WAIT_L(0); PG8_BAR; PG8_MMA(0, 0, At, B0); PG8_MMA(0, 1, At, B1); PG8_BAR; PG8_SCHED;
;             PG8_LDA(At, 0, 1); PG8_STAGEX(rsB, PG8_SB(0, 0), b2, voffB); PG8_STAGEX(rsB, PG8_SB(0, 1), b2 + hstepB, voffB); PG8_STAGEX(rsA, PG8_SA(0, 0), a2, voffA);
;             PG8_WAIT_V(8); PG8_WAIT_L(0); PG8_BAR; PG8_MMA(1, 0, At, B0); PG8_MMA(1, 1, At, B1); PG8_BAR; PG8_SCHED;
.LBB0_1377:
	v_add_u32_e32 v142, 0x10000, v185
	v_add_u32_e32 v158, 0x14000, v185
	ds_read_b128 v[130:133], v142
	ds_read_b128 v[134:137], v142 offset:1024
	ds_read_b128 v[138:141], v142 offset:2048
	ds_read_b128 v[142:145], v142 offset:3072
	ds_read_b128 v[146:149], v158
	ds_read_b128 v[150:153], v158 offset:1024
	ds_read_b128 v[154:157], v158 offset:2048
	ds_read_b128 v[158:161], v158 offset:3072
	s_add_i32 s50, s43, 0xfff40080
	s_cmp_eq_u32 s60, 12
	s_cselect_b32 s63, s30, s50
	s_cselect_b32 s62, s31, s59
	s_add_i32 s61, s63, 0x80
	s_mov_b32 m0, s23
	ds_read_b128 v[162:165], v186
	ds_read_b128 v[166:169], v186 offset:1024
	ds_read_b128 v[190:193], v186 offset:2048
	ds_read_b128 v[194:197], v186 offset:3072
	ds_read_b128 v[198:201], v186 offset:4096
	ds_read_b128 v[202:205], v186 offset:5120
	ds_read_b128 v[206:209], v186 offset:6144
	ds_read_b128 v[210:213], v186 offset:7168
	buffer_load_dwordx4 v173, s[76:79], s43 offen lds
	s_mov_b32 m0, s24
	s_nop 0
	buffer_load_dwordx4 v178, s[76:79], s43 offen lds
	s_waitcnt vmcnt(8)
	s_waitcnt lgkmcnt(0)
	s_setprio 1
	s_barrier
	v_mfma_f32_16x16x32_bf16 v[126:129], v[130:133], v[162:165], v[126:129]
	v_mfma_f32_16x16x32_bf16 v[126:129], v[134:137], v[166:169], v[126:129]
	v_mfma_f32_16x16x32_bf16 v[122:125], v[138:141], v[162:165], v[122:125]
	v_mfma_f32_16x16x32_bf16 v[122:125], v[142:145], v[166:169], v[122:125]
	v_mfma_f32_16x16x32_bf16 v[118:121], v[130:133], v[190:193], v[118:121]
	v_mfma_f32_16x16x32_bf16 v[118:121], v[134:137], v[194:197], v[118:121]
	v_mfma_f32_16x16x32_bf16 v[114:117], v[138:141], v[190:193], v[114:117]
	v_mfma_f32_16x16x32_bf16 v[114:117], v[142:145], v[194:197], v[114:117]
	v_mfma_f32_16x16x32_bf16 v[110:113], v[130:133], v[198:201], v[110:113]
	v_mfma_f32_16x16x32_bf16 v[110:113], v[134:137], v[202:205], v[110:113]
	v_mfma_f32_16x16x32_bf16 v[106:109], v[138:141], v[198:201], v[106:109]
	v_mfma_f32_16x16x32_bf16 v[106:109], v[142:145], v[202:205], v[106:109]
	v_mfma_f32_16x16x32_bf16 v[102:105], v[130:133], v[206:209], v[102:105]
	v_mfma_f32_16x16x32_bf16 v[102:105], v[134:137], v[210:213], v[102:105]
	v_mfma_f32_16x16x32_bf16 v[98:101], v[138:141], v[206:209], v[98:101]
	v_mfma_f32_16x16x32_bf16 v[98:101], v[142:145], v[210:213], v[98:101]
	v_mfma_f32_16x16x32_bf16 v[94:97], v[146:149], v[162:165], v[94:97]
	v_mfma_f32_16x16x32_bf16 v[94:97], v[150:153], v[166:169], v[94:97]
	v_mfma_f32_16x16x32_bf16 v[90:93], v[154:157], v[162:165], v[90:93]
	v_mfma_f32_16x16x32_bf16 v[90:93], v[158:161], v[166:169], v[90:93]
	v_mfma_f32_16x16x32_bf16 v[86:89], v[146:149], v[190:193], v[86:89]
	v_mfma_f32_16x16x32_bf16 v[86:89], v[150:153], v[194:197], v[86:89]
	v_mfma_f32_16x16x32_bf16 v[82:85], v[154:157], v[190:193], v[82:85]
	v_mfma_f32_16x16x32_bf16 v[82:85], v[158:161], v[194:197], v[82:85]
	v_mfma_f32_16x16x32_bf16 v[78:81], v[146:149], v[198:201], v[78:81]
	v_mfma_f32_16x16x32_bf16 v[78:81], v[150:153], v[202:205], v[78:81]
	v_mfma_f32_16x16x32_bf16 v[74:77], v[154:157], v[198:201], v[74:77]
	v_mfma_f32_16x16x32_bf16 v[74:77], v[158:161], v[202:205], v[74:77]
	v_mfma_f32_16x16x32_bf16 v[70:73], v[146:149], v[206:209], v[70:73]
	v_mfma_f32_16x16x32_bf16 v[70:73], v[150:153], v[210:213], v[70:73]
	v_mfma_f32_16x16x32_bf16 v[66:69], v[154:157], v[206:209], v[66:69]
	v_mfma_f32_16x16x32_bf16 v[66:69], v[158:161], v[210:213], v[66:69]
	s_barrier
	s_setprio 0
	s_mov_b32 m0, s7
	s_mov_b32 s50, s78
	s_mov_b32 s51, s79
	ds_read_b128 v[162:165], v186 offset:16384
	ds_read_b128 v[166:169], v186 offset:17408
	ds_read_b128 v[190:193], v186 offset:18432
	ds_read_b128 v[194:197], v186 offset:19456
	ds_read_b128 v[198:201], v186 offset:20480
	ds_read_b128 v[202:205], v186 offset:21504
	ds_read_b128 v[206:209], v186 offset:22528
	ds_read_b128 v[210:213], v186 offset:23552
	buffer_load_dwordx4 v177, s[48:51], s62 offen lds
	s_mov_b32 m0, s11
	s_add_i32 s64, s62, 0x40000
	buffer_load_dwordx4 v179, s[48:51], s62 offen lds
	s_mov_b32 m0, s12
	s_nop 0
	buffer_load_dwordx4 v177, s[48:51], s64 offen lds
	s_mov_b32 m0, s13
	s_nop 0
	buffer_load_dwordx4 v179, s[48:51], s64 offen lds
	s_mov_b32 m0, s5
	s_nop 0
	buffer_load_dwordx4 v173, s[76:79], s63 offen lds
	s_mov_b32 m0, s14
	s_nop 0
	buffer_load_dwordx4 v178, s[76:79], s63 offen lds
	s_waitcnt vmcnt(8)
	s_waitcnt lgkmcnt(0)
	s_setprio 1
	s_barrier
	v_mfma_f32_16x16x32_bf16 v[62:65], v[130:133], v[162:165], v[62:65]
	v_mfma_f32_16x16x32_bf16 v[62:65], v[134:137], v[166:169], v[62:65]
	v_mfma_f32_16x16x32_bf16 v[58:61], v[138:141], v[162:165], v[58:61]
	v_mfma_f32_16x16x32_bf16 v[58:61], v[142:145], v[166:169], v[58:61]
	v_mfma_f32_16x16x32_bf16 v[54:57], v[130:133], v[190:193], v[54:57]
	v_mfma_f32_16x16x32_bf16 v[54:57], v[134:137], v[194:197], v[54:57]
	v_mfma_f32_16x16x32_bf16 v[50:53], v[138:141], v[190:193], v[50:53]
	v_mfma_f32_16x16x32_bf16 v[50:53], v[142:145], v[194:197], v[50:53]
	v_mfma_f32_16x16x32_bf16 v[46:49], v[130:133], v[198:201], v[46:49]
	v_mfma_f32_16x16x32_bf16 v[46:49], v[134:137], v[202:205], v[46:49]
	v_mfma_f32_16x16x32_bf16 v[42:45], v[138:141], v[198:201], v[42:45]
	v_mfma_f32_16x16x32_bf16 v[42:45], v[142:145], v[202:205], v[42:45]
	v_mfma_f32_16x16x32_bf16 v[38:41], v[130:133], v[206:209], v[38:41]
	v_mfma_f32_16x16x32_bf16 v[38:41], v[134:137], v[210:213], v[38:41]
	v_mfma_f32_16x16x32_bf16 v[34:37], v[138:141], v[206:209], v[34:37]
	v_mfma_f32_16x16x32_bf16 v[34:37], v[142:145], v[210:213], v[34:37]
	v_mfma_f32_16x16x32_bf16 v[30:33], v[146:149], v[162:165], v[30:33]
	v_mfma_f32_16x16x32_bf16 v[30:33], v[150:153], v[166:169], v[30:33]
	v_mfma_f32_16x16x32_bf16 v[26:29], v[154:157], v[162:165], v[26:29]
	v_mfma_f32_16x16x32_bf16 v[26:29], v[158:161], v[166:169], v[26:29]
	v_mfma_f32_16x16x32_bf16 v[22:25], v[146:149], v[190:193], v[22:25]
	v_mfma_f32_16x16x32_bf16 v[22:25], v[150:153], v[194:197], v[22:25]
	v_mfma_f32_16x16x32_bf16 v[18:21], v[154:157], v[190:193], v[18:21]
	v_mfma_f32_16x16x32_bf16 v[18:21], v[158:161], v[194:197], v[18:21]
	v_mfma_f32_16x16x32_bf16 v[14:17], v[146:149], v[198:201], v[14:17]
	v_mfma_f32_16x16x32_bf16 v[14:17], v[150:153], v[202:205], v[14:17]
	v_mfma_f32_16x16x32_bf16 v[10:13], v[154:157], v[198:201], v[10:13]
	v_mfma_f32_16x16x32_bf16 v[10:13], v[158:161], v[202:205], v[10:13]
	v_mfma_f32_16x16x32_bf16 v[6:9], v[146:149], v[206:209], v[6:9]
	v_mfma_f32_16x16x32_bf16 v[6:9], v[150:153], v[210:213], v[6:9]
	v_mfma_f32_16x16x32_bf16 v[2:5], v[154:157], v[206:209], v[2:5]
	v_mfma_f32_16x16x32_bf16 v[2:5], v[158:161], v[210:213], v[2:5]
	s_barrier
; #define PG8_STAGEX(rs, bufoff, soff, voff) do { _Pragma("unroll") for (int _i = 0; _i < 2; ++_i) \
;         __builtin_amdgcn_raw_ptr_buffer_load_lds(rs, (LAS unsigned*)(lds + (bufoff) + ldsw + _i * 8192), 16, (voff)[_i], (soff), 0, 0); } while (0)
; #define PG8_LDA(dst, b, h) do { _Pragma("unroll") for (int m = 0; m < 4; ++m) _Pragma("unroll") for (int k = 0; k < 2; ++k) dst[m][k] = *(const LAS bf16x8*)(lds + PG8_SA(b, h) + aoff + m * 2048 + k * 1024); } while (0)
; #define PG8_LDB(dst, b, h) do { _Pragma("unroll") for (int n = 0; n < 2; ++n) _Pragma("unroll") for (int k = 0; k < 2; ++k) dst[n][k] = *(const LAS bf16x8*)(lds + PG8_SB(b, h) + boff + n * 2048 + k * 1024); } while (0)
; #define PG8_WAIT_V(n) asm volatile("s_waitcnt vmcnt(" #n ")" ::: "memory")
; #define PG8_WAIT_L(n) asm volatile("s_waitcnt lgkmcnt(" #n ")" ::: "memory")
; #define PG8_BAR __builtin_amdgcn_s_barrier()
; #define PG8_SCHED __builtin_amdgcn_sched_barrier(0)
;     ...
;             PG8_LDB(B0, 1, 0); PG8_LDB(B1, 1, 1); PG8_SCHED; PG8_LDA(At, 1, 0); PG8_STAGEX(rsA, PG8_SA(0, 1), a2 + hstepA, voffA);
;             PG8_WAIT_V(8); PG8_WAIT_L(0); PG8_BAR; PG8_MMA(0, 0, At, B0); PG8_MMA(0, 1, At, B1); PG8_BAR; PG8_SCHED;
;             PG8_LDA(At, 1, 1); PG8_STAGEX(rsB, PG8_SB(1, 0), b3, voffB); PG8_STAGEX(rsB, PG8_SB(1, 1), b3 + hstepB, voffB); PG8_STAGEX(rsA, PG8_SA(1, 0), a3, voffA);
;             PG8_WAIT_V(8); PG8_WAIT_L(0); PG8_BAR; PG8_MMA(1, 0, At, B0); PG8_MMA(1, 1, At, B1); PG8_BAR; PG8_SCHED;
;         }
;     ...
;         if (wr == 0) PG8_BAR;
	s_setprio 0
	v_add_u32_e32 v142, 0x18000, v185
	v_add_u32_e32 v158, 0x1c000, v185
	ds_read_b128 v[130:133], v142
	ds_read_b128 v[134:137], v142 offset:1024
	ds_read_b128 v[138:141], v142 offset:2048
	ds_read_b128 v[142:145], v142 offset:3072
	ds_read_b128 v[146:149], v158
	ds_read_b128 v[150:153], v158 offset:1024
	ds_read_b128 v[154:157], v158 offset:2048
	ds_read_b128 v[158:161], v158 offset:3072
	s_add_i32 s63, s63, 0xc0000
	s_mov_b32 m0, s15
	ds_read_b128 v[162:165], v186 offset:32768
	ds_read_b128 v[166:169], v186 offset:33792
	ds_read_b128 v[190:193], v186 offset:34816
	ds_read_b128 v[194:197], v186 offset:35840
	ds_read_b128 v[198:201], v186 offset:36864
	ds_read_b128 v[202:205], v186 offset:37888
	ds_read_b128 v[206:209], v186 offset:38912
	ds_read_b128 v[210:213], v186 offset:39936
	buffer_load_dwordx4 v173, s[76:79], s63 offen lds
	s_mov_b32 m0, s16
	s_nop 0
	buffer_load_dwordx4 v178, s[76:79], s63 offen lds
	s_waitcnt vmcnt(8)
	s_waitcnt lgkmcnt(0)
	s_setprio 1
	s_barrier
	v_mfma_f32_16x16x32_bf16 v[126:129], v[130:133], v[162:165], v[126:129]
	v_mfma_f32_16x16x32_bf16 v[126:129], v[134:137], v[166:169], v[126:129]
	v_mfma_f32_16x16x32_bf16 v[122:125], v[138:141], v[162:165], v[122:125]
	v_mfma_f32_16x16x32_bf16 v[122:125], v[142:145], v[166:169], v[122:125]
	v_mfma_f32_16x16x32_bf16 v[118:121], v[130:133], v[190:193], v[118:121]
	v_mfma_f32_16x16x32_bf16 v[118:121], v[134:137], v[194:197], v[118:121]
	v_mfma_f32_16x16x32_bf16 v[114:117], v[138:141], v[190:193], v[114:117]
	v_mfma_f32_16x16x32_bf16 v[114:117], v[142:145], v[194:197], v[114:117]
	v_mfma_f32_16x16x32_bf16 v[110:113], v[130:133], v[198:201], v[110:113]
	v_mfma_f32_16x16x32_bf16 v[110:113], v[134:137], v[202:205], v[110:113]
	v_mfma_f32_16x16x32_bf16 v[106:109], v[138:141], v[198:201], v[106:109]
	v_mfma_f32_16x16x32_bf16 v[106:109], v[142:145], v[202:205], v[106:109]
	v_mfma_f32_16x16x32_bf16 v[102:105], v[130:133], v[206:209], v[102:105]
	v_mfma_f32_16x16x32_bf16 v[102:105], v[134:137], v[210:213], v[102:105]
	v_mfma_f32_16x16x32_bf16 v[98:101], v[138:141], v[206:209], v[98:101]
	v_mfma_f32_16x16x32_bf16 v[98:101], v[142:145], v[210:213], v[98:101]
	v_mfma_f32_16x16x32_bf16 v[94:97], v[146:149], v[162:165], v[94:97]
	v_mfma_f32_16x16x32_bf16 v[94:97], v[150:153], v[166:169], v[94:97]
	v_mfma_f32_16x16x32_bf16 v[90:93], v[154:157], v[162:165], v[90:93]
	v_mfma_f32_16x16x32_bf16 v[90:93], v[158:161], v[166:169], v[90:93]
	v_mfma_f32_16x16x32_bf16 v[86:89], v[146:149], v[190:193], v[86:89]
	v_mfma_f32_16x16x32_bf16 v[86:89], v[150:153], v[194:197], v[86:89]
	v_mfma_f32_16x16x32_bf16 v[82:85], v[154:157], v[190:193], v[82:85]
	v_mfma_f32_16x16x32_bf16 v[82:85], v[158:161], v[194:197], v[82:85]
	v_mfma_f32_16x16x32_bf16 v[78:81], v[146:149], v[198:201], v[78:81]
	v_mfma_f32_16x16x32_bf16 v[78:81], v[150:153], v[202:205], v[78:81]
	v_mfma_f32_16x16x32_bf16 v[74:77], v[154:157], v[198:201], v[74:77]
	v_mfma_f32_16x16x32_bf16 v[74:77], v[158:161], v[202:205], v[74:77]
	v_mfma_f32_16x16x32_bf16 v[70:73], v[146:149], v[206:209], v[70:73]
	v_mfma_f32_16x16x32_bf16 v[70:73], v[150:153], v[210:213], v[70:73]
	v_mfma_f32_16x16x32_bf16 v[66:69], v[154:157], v[206:209], v[66:69]
	v_mfma_f32_16x16x32_bf16 v[66:69], v[158:161], v[210:213], v[66:69]
	s_barrier
	s_setprio 0
	s_mov_b32 m0, s17
	s_add_i32 s63, s62, 0x80
	ds_read_b128 v[162:165], v186 offset:49152
	ds_read_b128 v[166:169], v186 offset:50176
	ds_read_b128 v[190:193], v186 offset:51200
	ds_read_b128 v[194:197], v186 offset:52224
	ds_read_b128 v[198:201], v186 offset:53248
	ds_read_b128 v[202:205], v186 offset:54272
	ds_read_b128 v[206:209], v186 offset:55296
	ds_read_b128 v[210:213], v186 offset:56320
	buffer_load_dwordx4 v177, s[48:51], s63 offen lds
	s_mov_b32 m0, s18
	s_add_i32 s62, s62, 0x40080
	buffer_load_dwordx4 v179, s[48:51], s63 offen lds
	s_mov_b32 m0, s21
	s_nop 0
	buffer_load_dwordx4 v177, s[48:51], s62 offen lds
	s_mov_b32 m0, s22
	s_nop 0
	buffer_load_dwordx4 v179, s[48:51], s62 offen lds
	s_mov_b32 m0, s19
	s_nop 0
	buffer_load_dwordx4 v173, s[76:79], s61 offen lds
	s_mov_b32 m0, s20
	s_nop 0
	buffer_load_dwordx4 v178, s[76:79], s61 offen lds
	s_waitcnt vmcnt(8)
	s_waitcnt lgkmcnt(0)
	s_setprio 1
	s_barrier
	v_mfma_f32_16x16x32_bf16 v[62:65], v[130:133], v[162:165], v[62:65]
	v_mfma_f32_16x16x32_bf16 v[62:65], v[134:137], v[166:169], v[62:65]
	v_mfma_f32_16x16x32_bf16 v[58:61], v[138:141], v[162:165], v[58:61]
	v_mfma_f32_16x16x32_bf16 v[58:61], v[142:145], v[166:169], v[58:61]
	v_mfma_f32_16x16x32_bf16 v[54:57], v[130:133], v[190:193], v[54:57]
	v_mfma_f32_16x16x32_bf16 v[54:57], v[134:137], v[194:197], v[54:57]
	v_mfma_f32_16x16x32_bf16 v[50:53], v[138:141], v[190:193], v[50:53]
	v_mfma_f32_16x16x32_bf16 v[50:53], v[142:145], v[194:197], v[50:53]
	v_mfma_f32_16x16x32_bf16 v[46:49], v[130:133], v[198:201], v[46:49]
	v_mfma_f32_16x16x32_bf16 v[46:49], v[134:137], v[202:205], v[46:49]
	v_mfma_f32_16x16x32_bf16 v[42:45], v[138:141], v[198:201], v[42:45]
	v_mfma_f32_16x16x32_bf16 v[42:45], v[142:145], v[202:205], v[42:45]
	v_mfma_f32_16x16x32_bf16 v[38:41], v[130:133], v[206:209], v[38:41]
	v_mfma_f32_16x16x32_bf16 v[38:41], v[134:137], v[210:213], v[38:41]
	v_mfma_f32_16x16x32_bf16 v[34:37], v[138:141], v[206:209], v[34:37]
	v_mfma_f32_16x16x32_bf16 v[34:37], v[142:145], v[210:213], v[34:37]
	v_mfma_f32_16x16x32_bf16 v[30:33], v[146:149], v[162:165], v[30:33]
	v_mfma_f32_16x16x32_bf16 v[30:33], v[150:153], v[166:169], v[30:33]
	v_mfma_f32_16x16x32_bf16 v[26:29], v[154:157], v[162:165], v[26:29]
	v_mfma_f32_16x16x32_bf16 v[26:29], v[158:161], v[166:169], v[26:29]
	v_mfma_f32_16x16x32_bf16 v[22:25], v[146:149], v[190:193], v[22:25]
	v_mfma_f32_16x16x32_bf16 v[22:25], v[150:153], v[194:197], v[22:25]
	v_mfma_f32_16x16x32_bf16 v[18:21], v[154:157], v[190:193], v[18:21]
	v_mfma_f32_16x16x32_bf16 v[18:21], v[158:161], v[194:197], v[18:21]
	v_mfma_f32_16x16x32_bf16 v[14:17], v[146:149], v[198:201], v[14:17]
	v_mfma_f32_16x16x32_bf16 v[14:17], v[150:153], v[202:205], v[14:17]
	v_mfma_f32_16x16x32_bf16 v[10:13], v[154:157], v[198:201], v[10:13]
	v_mfma_f32_16x16x32_bf16 v[10:13], v[158:161], v[202:205], v[10:13]
	v_mfma_f32_16x16x32_bf16 v[6:9], v[146:149], v[206:209], v[6:9]
	v_mfma_f32_16x16x32_bf16 v[6:9], v[150:153], v[210:213], v[6:9]
	v_mfma_f32_16x16x32_bf16 v[2:5], v[154:157], v[206:209], v[2:5]
	v_mfma_f32_16x16x32_bf16 v[2:5], v[158:161], v[210:213], v[2:5]
	s_barrier
	s_setprio 0
	s_add_i32 s60, s60, 2
	s_addk_i32 s43, 0x100
	s_addk_i32 s59, 0x100
	s_cmp_gt_u32 s60, 13
	s_cbranch_scc0 .LBB0_1377
	s_and_b64 vcc, exec, s[52:53]
	s_cbranch_vccz .LBB0_1380
	s_barrier

; #define PG8_STAGEX(rs, bufoff, soff, voff) do { _Pragma("unroll") for (int _i = 0; _i < 2; ++_i) \
;         __builtin_amdgcn_raw_ptr_buffer_load_lds(rs, (LAS unsigned*)(lds + (bufoff) + ldsw + _i * 8192), 16, (voff)[_i], (soff), 0, 0); } while (0)
; #define PG8_LDA(dst, b, h) do { _Pragma("unroll") for (int m = 0; m < 4; ++m) _Pragma("unroll") for (int k = 0; k < 2; ++k) dst[m][k] = *(const LAS bf16x8*)(lds + PG8_SA(b, h) + aoff + m * 2048 + k * 1024); } while (0)
; #define PG8_LDB(dst, b, h) do { _Pragma("unroll") for (int n = 0; n < 2; ++n) _Pragma("unroll") for (int k = 0; k < 2; ++k) dst[n][k] = *(const LAS bf16x8*)(lds + PG8_SB(b, h) + boff + n * 2048 + k * 1024); } while (0)
; #define PG8_WAIT_V(n) asm volatile("s_waitcnt vmcnt(" #n ")" ::: "memory")
; #define PG8_WAIT_L(n) asm volatile("s_waitcnt lgkmcnt(" #n ")" ::: "memory")
; #define PG8_BAR __builtin_amdgcn_s_barrier()
; #define PG8_SCHED __builtin_amdgcn_sched_barrier(0)
;     ...
;             for (int t = 0; t < nt; t += 2) {
;                 const bool last = (t == nt - 2);
;                 const unsigned a1 = cA + (unsigned)(t + 1) * kstep;
;                 const unsigned a2 = last ? nA : cA + (unsigned)(t + 2) * kstep, b2 = last ? nB : cB + (unsigned)(t + 2) * kstep;
;                 const unsigned a3 = a2 + kstep, b3 = b2 + kstep;
;                 if (w0) { PG8_LDB(B0, 0, 0); PG8_LDB(B1, 0, 1); PG8_SCHED; PG8_LDA(At, 0, 0); }
;                 PG8_WAIT_L(0); PG8_BAR; if (w0) { PG8_MMA(0, 0, At, B0); PG8_MMA(0, 1, At, B1); } PG8_BAR; PG8_SCHED;
;                 PG8_STAGEX(rsB, PG8_SB(0, 0), b2, voffB); PG8_STAGEX(rsB, PG8_SB(0, 1), b2 + hstepB, voffB); PG8_STAGEX(rsA, PG8_SA(0, 0), a2, voffA);
;                 PG8_WAIT_V(6); PG8_BAR; PG8_BAR; PG8_SCHED;
.LBB0_1429:
	v_add_u32_e32 v78, 0x10000, v95
	v_add_u32_e32 v86, 0x14000, v95
	ds_read_b128 v[66:69], v78
	ds_read_b128 v[70:73], v78 offset:1024
	ds_read_b128 v[74:77], v78 offset:2048
	ds_read_b128 v[78:81], v78 offset:3072
	ds_read_b128 v[82:85], v86
	ds_read_b128 v[100:103], v86 offset:1024
	ds_read_b128 v[104:107], v86 offset:2048
	ds_read_b128 v[108:111], v86 offset:3072
	s_cmp_eq_u32 s40, 12
	s_cselect_b32 s41, s38, s39
	s_cselect_b32 s46, s30, s31
	s_add_i32 s47, s41, 0x80
	ds_read_b128 v[112:115], v96
	ds_read_b128 v[116:119], v96 offset:1024
	ds_read_b128 v[120:123], v96 offset:2048
	ds_read_b128 v[124:127], v96 offset:3072
	ds_read_b128 v[128:131], v96 offset:4096
	ds_read_b128 v[132:135], v96 offset:5120
	ds_read_b128 v[136:139], v96 offset:6144
	ds_read_b128 v[140:143], v96 offset:7168
	s_waitcnt lgkmcnt(0)
	s_setprio 1
	s_barrier
	v_mfma_f32_16x16x32_bf16 v[62:65], v[66:69], v[112:115], v[62:65]
	v_mfma_f32_16x16x32_bf16 v[62:65], v[70:73], v[116:119], v[62:65]
	v_mfma_f32_16x16x32_bf16 v[58:61], v[74:77], v[112:115], v[58:61]
	v_mfma_f32_16x16x32_bf16 v[58:61], v[78:81], v[116:119], v[58:61]
	v_mfma_f32_16x16x32_bf16 v[54:57], v[66:69], v[120:123], v[54:57]
	v_mfma_f32_16x16x32_bf16 v[54:57], v[70:73], v[124:127], v[54:57]
	v_mfma_f32_16x16x32_bf16 v[50:53], v[74:77], v[120:123], v[50:53]
	v_mfma_f32_16x16x32_bf16 v[50:53], v[78:81], v[124:127], v[50:53]
	v_mfma_f32_16x16x32_bf16 v[46:49], v[66:69], v[128:131], v[46:49]
	v_mfma_f32_16x16x32_bf16 v[46:49], v[70:73], v[132:135], v[46:49]
	v_mfma_f32_16x16x32_bf16 v[42:45], v[74:77], v[128:131], v[42:45]
	v_mfma_f32_16x16x32_bf16 v[42:45], v[78:81], v[132:135], v[42:45]
	v_mfma_f32_16x16x32_bf16 v[38:41], v[66:69], v[136:139], v[38:41]
	v_mfma_f32_16x16x32_bf16 v[38:41], v[70:73], v[140:143], v[38:41]
	v_mfma_f32_16x16x32_bf16 v[34:37], v[74:77], v[136:139], v[34:37]
	v_mfma_f32_16x16x32_bf16 v[34:37], v[78:81], v[140:143], v[34:37]
	v_mfma_f32_16x16x32_bf16 v[30:33], v[82:85], v[112:115], v[30:33]
	v_mfma_f32_16x16x32_bf16 v[30:33], v[100:103], v[116:119], v[30:33]
	v_mfma_f32_16x16x32_bf16 v[26:29], v[104:107], v[112:115], v[26:29]
	v_mfma_f32_16x16x32_bf16 v[26:29], v[108:111], v[116:119], v[26:29]
	v_mfma_f32_16x16x32_bf16 v[22:25], v[82:85], v[120:123], v[22:25]
	v_mfma_f32_16x16x32_bf16 v[22:25], v[100:103], v[124:127], v[22:25]
	v_mfma_f32_16x16x32_bf16 v[18:21], v[104:107], v[120:123], v[18:21]
	v_mfma_f32_16x16x32_bf16 v[18:21], v[108:111], v[124:127], v[18:21]
	v_mfma_f32_16x16x32_bf16 v[14:17], v[82:85], v[128:131], v[14:17]
	v_mfma_f32_16x16x32_bf16 v[14:17], v[100:103], v[132:135], v[14:17]
	v_mfma_f32_16x16x32_bf16 v[10:13], v[104:107], v[128:131], v[10:13]
	v_mfma_f32_16x16x32_bf16 v[10:13], v[108:111], v[132:135], v[10:13]
	v_mfma_f32_16x16x32_bf16 v[6:9], v[82:85], v[136:139], v[6:9]
	v_mfma_f32_16x16x32_bf16 v[6:9], v[100:103], v[140:143], v[6:9]
	v_mfma_f32_16x16x32_bf16 v[2:5], v[104:107], v[136:139], v[2:5]
	v_mfma_f32_16x16x32_bf16 v[2:5], v[108:111], v[140:143], v[2:5]
	s_barrier
	s_setprio 0
	s_mov_b32 m0, s5
	s_mov_b32 s50, s78
	s_mov_b32 s51, s79
	buffer_load_dwordx4 v89, s[48:51], s46 offen lds
	s_mov_b32 m0, s7
	s_add_i32 s52, s46, 0x40000
	buffer_load_dwordx4 v91, s[48:51], s46 offen lds
	s_mov_b32 m0, s11
	s_nop 0
	buffer_load_dwordx4 v89, s[48:51], s52 offen lds
	s_mov_b32 m0, s12
	s_nop 0
	buffer_load_dwordx4 v91, s[48:51], s52 offen lds
	s_mov_b32 m0, s3
	s_nop 0
	buffer_load_dwordx4 v88, s[76:79], s41 offen lds
	s_mov_b32 m0, s13
	s_nop 0
	buffer_load_dwordx4 v90, s[76:79], s41 offen lds
	s_waitcnt vmcnt(6)
	s_barrier
	s_barrier
; #define PG8_STAGEX(rs, bufoff, soff, voff) do { _Pragma("unroll") for (int _i = 0; _i < 2; ++_i) \
;         __builtin_amdgcn_raw_ptr_buffer_load_lds(rs, (LAS unsigned*)(lds + (bufoff) + ldsw + _i * 8192), 16, (voff)[_i], (soff), 0, 0); } while (0)
; #define PG8_LDA(dst, b, h) do { _Pragma("unroll") for (int m = 0; m < 4; ++m) _Pragma("unroll") for (int k = 0; k < 2; ++k) dst[m][k] = *(const LAS bf16x8*)(lds + PG8_SA(b, h) + aoff + m * 2048 + k * 1024); } while (0)
; #define PG8_LDB(dst, b, h) do { _Pragma("unroll") for (int n = 0; n < 2; ++n) _Pragma("unroll") for (int k = 0; k < 2; ++k) dst[n][k] = *(const LAS bf16x8*)(lds + PG8_SB(b, h) + boff + n * 2048 + k * 1024); } while (0)
; #define PG8_WAIT_V(n) asm volatile("s_waitcnt vmcnt(" #n ")" ::: "memory")
; #define PG8_WAIT_L(n) asm volatile("s_waitcnt lgkmcnt(" #n ")" ::: "memory")
; #define PG8_BAR __builtin_amdgcn_s_barrier()
; #define PG8_SCHED __builtin_amdgcn_sched_barrier(0)
;     ...
;                 if (w0) { PG8_LDB(B0, 1, 0); PG8_LDB(B1, 1, 1); PG8_SCHED; PG8_LDA(At, 1, 0); }
;                 PG8_WAIT_L(0); PG8_BAR; if (w0) { PG8_MMA(0, 0, At, B0); PG8_MMA(0, 1, At, B1); } PG8_BAR; PG8_SCHED;
;                 PG8_STAGEX(rsB, PG8_SB(1, 0), b3, voffB); PG8_STAGEX(rsB, PG8_SB(1, 1), b3 + hstepB, voffB); PG8_STAGEX(rsA, PG8_SA(1, 0), a3, voffA);
;                 PG8_WAIT_V(6); PG8_BAR; PG8_BAR; PG8_SCHED;
;             }
;         }
;         if (wr == 0) PG8_BAR;
	v_add_u32_e32 v78, 0x18000, v95
	v_add_u32_e32 v86, 0x1c000, v95
	ds_read_b128 v[66:69], v78
	ds_read_b128 v[70:73], v78 offset:1024
	ds_read_b128 v[74:77], v78 offset:2048
	ds_read_b128 v[78:81], v78 offset:3072
	ds_read_b128 v[82:85], v86
	ds_read_b128 v[100:103], v86 offset:1024
	ds_read_b128 v[104:107], v86 offset:2048
	ds_read_b128 v[108:111], v86 offset:3072
	ds_read_b128 v[112:115], v96 offset:32768
	ds_read_b128 v[116:119], v96 offset:33792
	ds_read_b128 v[120:123], v96 offset:34816
	ds_read_b128 v[124:127], v96 offset:35840
	ds_read_b128 v[128:131], v96 offset:36864
	ds_read_b128 v[132:135], v96 offset:37888
	ds_read_b128 v[136:139], v96 offset:38912
	ds_read_b128 v[140:143], v96 offset:39936
	s_waitcnt lgkmcnt(0)
	s_setprio 1
	s_barrier
	v_mfma_f32_16x16x32_bf16 v[62:65], v[66:69], v[112:115], v[62:65]
	v_mfma_f32_16x16x32_bf16 v[58:61], v[74:77], v[112:115], v[58:61]
	v_mfma_f32_16x16x32_bf16 v[54:57], v[66:69], v[120:123], v[54:57]
	v_mfma_f32_16x16x32_bf16 v[50:53], v[74:77], v[120:123], v[50:53]
	v_mfma_f32_16x16x32_bf16 v[46:49], v[66:69], v[128:131], v[46:49]
	v_mfma_f32_16x16x32_bf16 v[42:45], v[74:77], v[128:131], v[42:45]
	v_mfma_f32_16x16x32_bf16 v[38:41], v[66:69], v[136:139], v[38:41]
	v_mfma_f32_16x16x32_bf16 v[34:37], v[74:77], v[136:139], v[34:37]
	v_mfma_f32_16x16x32_bf16 v[62:65], v[70:73], v[116:119], v[62:65]
	v_mfma_f32_16x16x32_bf16 v[58:61], v[78:81], v[116:119], v[58:61]
	v_mfma_f32_16x16x32_bf16 v[54:57], v[70:73], v[124:127], v[54:57]
	v_mfma_f32_16x16x32_bf16 v[50:53], v[78:81], v[124:127], v[50:53]
	v_mfma_f32_16x16x32_bf16 v[46:49], v[70:73], v[132:135], v[46:49]
	v_mfma_f32_16x16x32_bf16 v[42:45], v[78:81], v[132:135], v[42:45]
	v_mfma_f32_16x16x32_bf16 v[38:41], v[70:73], v[140:143], v[38:41]
	v_mfma_f32_16x16x32_bf16 v[34:37], v[78:81], v[140:143], v[34:37]
	v_mfma_f32_16x16x32_bf16 v[30:33], v[82:85], v[112:115], v[30:33]
	s_add_i32 s41, s46, 0x80
	v_mfma_f32_16x16x32_bf16 v[26:29], v[104:107], v[112:115], v[26:29]
	v_mfma_f32_16x16x32_bf16 v[22:25], v[82:85], v[120:123], v[22:25]
	v_mfma_f32_16x16x32_bf16 v[18:21], v[104:107], v[120:123], v[18:21]
	v_mfma_f32_16x16x32_bf16 v[14:17], v[82:85], v[128:131], v[14:17]
	v_mfma_f32_16x16x32_bf16 v[10:13], v[104:107], v[128:131], v[10:13]
	v_mfma_f32_16x16x32_bf16 v[6:9], v[82:85], v[136:139], v[6:9]
	v_mfma_f32_16x16x32_bf16 v[2:5], v[104:107], v[136:139], v[2:5]
	v_mfma_f32_16x16x32_bf16 v[30:33], v[100:103], v[116:119], v[30:33]
	v_mfma_f32_16x16x32_bf16 v[26:29], v[108:111], v[116:119], v[26:29]
	v_mfma_f32_16x16x32_bf16 v[22:25], v[100:103], v[124:127], v[22:25]
	v_mfma_f32_16x16x32_bf16 v[18:21], v[108:111], v[124:127], v[18:21]
	v_mfma_f32_16x16x32_bf16 v[14:17], v[100:103], v[132:135], v[14:17]
	v_mfma_f32_16x16x32_bf16 v[10:13], v[108:111], v[132:135], v[10:13]
	v_mfma_f32_16x16x32_bf16 v[6:9], v[100:103], v[140:143], v[6:9]
	v_mfma_f32_16x16x32_bf16 v[2:5], v[108:111], v[140:143], v[2:5]
	s_barrier
	s_setprio 0
	s_mov_b32 m0, s14
	s_add_i32 s46, s46, 0x40080
	buffer_load_dwordx4 v89, s[48:51], s41 offen lds
	s_mov_b32 m0, s15
	s_nop 0
	buffer_load_dwordx4 v91, s[48:51], s41 offen lds
	s_mov_b32 m0, s18
	s_nop 0
	buffer_load_dwordx4 v89, s[48:51], s46 offen lds
	s_mov_b32 m0, s19
	s_nop 0
	buffer_load_dwordx4 v91, s[48:51], s46 offen lds
	s_mov_b32 m0, s16
	s_nop 0
	buffer_load_dwordx4 v88, s[76:79], s47 offen lds
	s_mov_b32 m0, s17
	s_nop 0
	buffer_load_dwordx4 v90, s[76:79], s47 offen lds
	s_waitcnt vmcnt(6)
	s_barrier
	s_barrier
	s_add_i32 s40, s40, 2
	s_addk_i32 s31, 0x100
	s_addk_i32 s39, 0x100
	s_cmp_gt_u32 s40, 13
	s_cbranch_scc0 .LBB0_1429
	s_and_b64 vcc, exec, s[42:43]
	s_cbranch_vccz .LBB0_1432
	s_barrier

; #define PG8_STAGEX(rs, bufoff, soff, voff) do { _Pragma("unroll") for (int _i = 0; _i < 2; ++_i) \
;         __builtin_amdgcn_raw_ptr_buffer_load_lds(rs, (LAS unsigned*)(lds + (bufoff) + ldsw + _i * 8192), 16, (voff)[_i], (soff), 0, 0); } while (0)
; #define PG8_LDA(dst, b, h) do { _Pragma("unroll") for (int m = 0; m < 4; ++m) _Pragma("unroll") for (int k = 0; k < 2; ++k) dst[m][k] = *(const LAS bf16x8*)(lds + PG8_SA(b, h) + aoff + m * 2048 + k * 1024); } while (0)
; #define PG8_LDB(dst, b, h) do { _Pragma("unroll") for (int n = 0; n < 2; ++n) _Pragma("unroll") for (int k = 0; k < 2; ++k) dst[n][k] = *(const LAS bf16x8*)(lds + PG8_SB(b, h) + boff + n * 2048 + k * 1024); } while (0)
; #define PG8_WAIT_V(n) asm volatile("s_waitcnt vmcnt(" #n ")" ::: "memory")
; #define PG8_WAIT_L(n) asm volatile("s_waitcnt lgkmcnt(" #n ")" ::: "memory")
; #define PG8_BAR __builtin_amdgcn_s_barrier()
; #define PG8_SCHED __builtin_amdgcn_sched_barrier(0)
;     ...
;         for (int t = 0; t < nt; t += 2) {
;             const bool last = (t == nt - 2);
;             const unsigned a1 = cA + (unsigned)(t + 1) * kstep;
;             const unsigned a2 = last ? nA : cA + (unsigned)(t + 2) * kstep, b2 = last ? nB : cB + (unsigned)(t + 2) * kstep;
;             const unsigned a3 = a2 + kstep, b3 = b2 + kstep;
;             PG8_LDB(B0, 0, 0); PG8_LDB(B1, 0, 1); PG8_SCHED; PG8_LDA(At, 0, 0); PG8_STAGEX(rsA, PG8_SA(1, 1), a1 + hstepA, voffA);
;             PG8_WAIT_V(8); PG8_WAIT_L(0); PG8_BAR; PG8_MMA(0, 0, At, B0); PG8_MMA(0, 1, At, B1); PG8_BAR; PG8_SCHED;
;             PG8_LDA(At, 0, 1); PG8_STAGEX(rsB, PG8_SB(0, 0), b2, voffB); PG8_STAGEX(rsB, PG8_SB(0, 1), b2 + hstepB, voffB); PG8_STAGEX(rsA, PG8_SA(0, 0), a2, voffA);
;             PG8_WAIT_V(8); PG8_WAIT_L(0); PG8_BAR; PG8_MMA(1, 0, At, B0); PG8_MMA(1, 1, At, B1); PG8_BAR; PG8_SCHED;
.LBB0_1529:
	v_add_u32_e32 v118, 0x10000, v210
	v_add_u32_e32 v142, 0x14000, v210
	ds_read_b128 v[106:109], v118
	ds_read_b128 v[110:113], v118 offset:1024
	ds_read_b128 v[114:117], v118 offset:2048
	ds_read_b128 v[118:121], v118 offset:3072
	ds_read_b128 v[122:125], v142
	ds_read_b128 v[126:129], v142 offset:1024
	ds_read_b128 v[130:133], v142 offset:2048
	ds_read_b128 v[142:145], v142 offset:3072
	s_add_i32 s46, s59, 0xfff80080
	s_cmp_eq_u32 s64, 28
	s_cselect_b32 s67, s30, s46
	s_cselect_b32 s66, s31, s63
	s_or_b32 s65, s67, 0x80
	s_mov_b32 m0, s76
	ds_read_b128 v[164:167], v211
	ds_read_b128 v[168:171], v211 offset:1024
	ds_read_b128 v[182:185], v211 offset:2048
	ds_read_b128 v[186:189], v211 offset:3072
	ds_read_b128 v[190:193], v211 offset:4096
	ds_read_b128 v[194:197], v211 offset:5120
	ds_read_b128 v[198:201], v211 offset:6144
	ds_read_b128 v[202:205], v211 offset:7168
	buffer_load_dwordx4 v178, s[40:43], s59 offen lds
	s_mov_b32 m0, s77
	s_nop 0
	buffer_load_dwordx4 v206, s[40:43], s59 offen lds
	s_waitcnt vmcnt(8)
	s_waitcnt lgkmcnt(0)
	s_setprio 1
	s_barrier
	v_mfma_f32_16x16x32_bf16 v[158:161], v[106:109], v[164:167], v[158:161]
	v_mfma_f32_16x16x32_bf16 v[158:161], v[110:113], v[168:171], v[158:161]
	v_mfma_f32_16x16x32_bf16 v[154:157], v[114:117], v[164:167], v[154:157]
	v_mfma_f32_16x16x32_bf16 v[154:157], v[118:121], v[168:171], v[154:157]
	v_mfma_f32_16x16x32_bf16 v[150:153], v[106:109], v[182:185], v[150:153]
	v_mfma_f32_16x16x32_bf16 v[150:153], v[110:113], v[186:189], v[150:153]
	v_mfma_f32_16x16x32_bf16 v[146:149], v[114:117], v[182:185], v[146:149]
	v_mfma_f32_16x16x32_bf16 v[146:149], v[118:121], v[186:189], v[146:149]
	v_mfma_f32_16x16x32_bf16 v[138:141], v[106:109], v[190:193], v[138:141]
	v_mfma_f32_16x16x32_bf16 v[138:141], v[110:113], v[194:197], v[138:141]
	v_mfma_f32_16x16x32_bf16 v[134:137], v[114:117], v[190:193], v[134:137]
	v_mfma_f32_16x16x32_bf16 v[134:137], v[118:121], v[194:197], v[134:137]
	v_mfma_f32_16x16x32_bf16 v[102:105], v[106:109], v[198:201], v[102:105]
	v_mfma_f32_16x16x32_bf16 v[102:105], v[110:113], v[202:205], v[102:105]
	v_mfma_f32_16x16x32_bf16 v[98:101], v[114:117], v[198:201], v[98:101]
	v_mfma_f32_16x16x32_bf16 v[98:101], v[118:121], v[202:205], v[98:101]
	v_mfma_f32_16x16x32_bf16 v[62:65], v[122:125], v[164:167], v[62:65]
	v_mfma_f32_16x16x32_bf16 v[62:65], v[126:129], v[168:171], v[62:65]
	v_mfma_f32_16x16x32_bf16 v[58:61], v[130:133], v[164:167], v[58:61]
	v_mfma_f32_16x16x32_bf16 v[58:61], v[142:145], v[168:171], v[58:61]
	v_mfma_f32_16x16x32_bf16 v[54:57], v[122:125], v[182:185], v[54:57]
	v_mfma_f32_16x16x32_bf16 v[54:57], v[126:129], v[186:189], v[54:57]
	v_mfma_f32_16x16x32_bf16 v[50:53], v[130:133], v[182:185], v[50:53]
	v_mfma_f32_16x16x32_bf16 v[50:53], v[142:145], v[186:189], v[50:53]
	v_mfma_f32_16x16x32_bf16 v[46:49], v[122:125], v[190:193], v[46:49]
	v_mfma_f32_16x16x32_bf16 v[46:49], v[126:129], v[194:197], v[46:49]
	v_mfma_f32_16x16x32_bf16 v[42:45], v[130:133], v[190:193], v[42:45]
	v_mfma_f32_16x16x32_bf16 v[42:45], v[142:145], v[194:197], v[42:45]
	v_mfma_f32_16x16x32_bf16 v[38:41], v[122:125], v[198:201], v[38:41]
	v_mfma_f32_16x16x32_bf16 v[38:41], v[126:129], v[202:205], v[38:41]
	v_mfma_f32_16x16x32_bf16 v[34:37], v[130:133], v[198:201], v[34:37]
	v_mfma_f32_16x16x32_bf16 v[34:37], v[142:145], v[202:205], v[34:37]
	s_barrier
	s_setprio 0
	s_mov_b32 m0, s17
	s_mov_b32 s46, s42
	s_mov_b32 s47, s43
	ds_read_b128 v[164:167], v211 offset:16384
	ds_read_b128 v[168:171], v211 offset:17408
	ds_read_b128 v[182:185], v211 offset:18432
	ds_read_b128 v[186:189], v211 offset:19456
	ds_read_b128 v[190:193], v211 offset:20480
	ds_read_b128 v[194:197], v211 offset:21504
	ds_read_b128 v[198:201], v211 offset:22528
	ds_read_b128 v[202:205], v211 offset:23552
	buffer_load_dwordx4 v179, s[44:47], s66 offen lds
	s_mov_b32 m0, s18
	s_add_i32 s68, s66, 0x80000
	buffer_load_dwordx4 v207, s[44:47], s66 offen lds
	s_mov_b32 m0, s19
	s_nop 0
	buffer_load_dwordx4 v179, s[44:47], s68 offen lds
	s_mov_b32 m0, s20
	s_nop 0
	buffer_load_dwordx4 v207, s[44:47], s68 offen lds
	s_mov_b32 m0, s16
	s_nop 0
	buffer_load_dwordx4 v178, s[40:43], s67 offen lds
	s_mov_b32 m0, s21
	s_nop 0
	buffer_load_dwordx4 v206, s[40:43], s67 offen lds
	s_waitcnt vmcnt(8)
	s_waitcnt lgkmcnt(0)
	s_setprio 1
	s_barrier
	v_mfma_f32_16x16x32_bf16 v[94:97], v[106:109], v[164:167], v[94:97]
	v_mfma_f32_16x16x32_bf16 v[94:97], v[110:113], v[168:171], v[94:97]
	v_mfma_f32_16x16x32_bf16 v[90:93], v[114:117], v[164:167], v[90:93]
	v_mfma_f32_16x16x32_bf16 v[90:93], v[118:121], v[168:171], v[90:93]
	v_mfma_f32_16x16x32_bf16 v[86:89], v[106:109], v[182:185], v[86:89]
	v_mfma_f32_16x16x32_bf16 v[86:89], v[110:113], v[186:189], v[86:89]
	v_mfma_f32_16x16x32_bf16 v[82:85], v[114:117], v[182:185], v[82:85]
	v_mfma_f32_16x16x32_bf16 v[82:85], v[118:121], v[186:189], v[82:85]
	v_mfma_f32_16x16x32_bf16 v[78:81], v[106:109], v[190:193], v[78:81]
	v_mfma_f32_16x16x32_bf16 v[78:81], v[110:113], v[194:197], v[78:81]
	v_mfma_f32_16x16x32_bf16 v[74:77], v[114:117], v[190:193], v[74:77]
	v_mfma_f32_16x16x32_bf16 v[74:77], v[118:121], v[194:197], v[74:77]
	v_mfma_f32_16x16x32_bf16 v[70:73], v[106:109], v[198:201], v[70:73]
	v_mfma_f32_16x16x32_bf16 v[70:73], v[110:113], v[202:205], v[70:73]
	v_mfma_f32_16x16x32_bf16 v[66:69], v[114:117], v[198:201], v[66:69]
	v_mfma_f32_16x16x32_bf16 v[66:69], v[118:121], v[202:205], v[66:69]
	v_mfma_f32_16x16x32_bf16 v[30:33], v[122:125], v[164:167], v[30:33]
	v_mfma_f32_16x16x32_bf16 v[30:33], v[126:129], v[168:171], v[30:33]
	v_mfma_f32_16x16x32_bf16 v[26:29], v[130:133], v[164:167], v[26:29]
	v_mfma_f32_16x16x32_bf16 v[26:29], v[142:145], v[168:171], v[26:29]
	v_mfma_f32_16x16x32_bf16 v[22:25], v[122:125], v[182:185], v[22:25]
	v_mfma_f32_16x16x32_bf16 v[22:25], v[126:129], v[186:189], v[22:25]
	v_mfma_f32_16x16x32_bf16 v[18:21], v[130:133], v[182:185], v[18:21]
	v_mfma_f32_16x16x32_bf16 v[18:21], v[142:145], v[186:189], v[18:21]
	v_mfma_f32_16x16x32_bf16 v[14:17], v[122:125], v[190:193], v[14:17]
	v_mfma_f32_16x16x32_bf16 v[14:17], v[126:129], v[194:197], v[14:17]
	v_mfma_f32_16x16x32_bf16 v[10:13], v[130:133], v[190:193], v[10:13]
	v_mfma_f32_16x16x32_bf16 v[10:13], v[142:145], v[194:197], v[10:13]
	v_mfma_f32_16x16x32_bf16 v[6:9], v[122:125], v[198:201], v[6:9]
	v_mfma_f32_16x16x32_bf16 v[6:9], v[126:129], v[202:205], v[6:9]
	v_mfma_f32_16x16x32_bf16 v[2:5], v[130:133], v[198:201], v[2:5]
	v_mfma_f32_16x16x32_bf16 v[2:5], v[142:145], v[202:205], v[2:5]
	s_barrier
; #define PG8_STAGEX(rs, bufoff, soff, voff) do { _Pragma("unroll") for (int _i = 0; _i < 2; ++_i) \
;         __builtin_amdgcn_raw_ptr_buffer_load_lds(rs, (LAS unsigned*)(lds + (bufoff) + ldsw + _i * 8192), 16, (voff)[_i], (soff), 0, 0); } while (0)
; #define PG8_LDA(dst, b, h) do { _Pragma("unroll") for (int m = 0; m < 4; ++m) _Pragma("unroll") for (int k = 0; k < 2; ++k) dst[m][k] = *(const LAS bf16x8*)(lds + PG8_SA(b, h) + aoff + m * 2048 + k * 1024); } while (0)
; #define PG8_LDB(dst, b, h) do { _Pragma("unroll") for (int n = 0; n < 2; ++n) _Pragma("unroll") for (int k = 0; k < 2; ++k) dst[n][k] = *(const LAS bf16x8*)(lds + PG8_SB(b, h) + boff + n * 2048 + k * 1024); } while (0)
; #define PG8_WAIT_V(n) asm volatile("s_waitcnt vmcnt(" #n ")" ::: "memory")
; #define PG8_WAIT_L(n) asm volatile("s_waitcnt lgkmcnt(" #n ")" ::: "memory")
; #define PG8_BAR __builtin_amdgcn_s_barrier()
; #define PG8_SCHED __builtin_amdgcn_sched_barrier(0)
;     ...
;             PG8_LDB(B0, 1, 0); PG8_LDB(B1, 1, 1); PG8_SCHED; PG8_LDA(At, 1, 0); PG8_STAGEX(rsA, PG8_SA(0, 1), a2 + hstepA, voffA);
;             PG8_WAIT_V(8); PG8_WAIT_L(0); PG8_BAR; PG8_MMA(0, 0, At, B0); PG8_MMA(0, 1, At, B1); PG8_BAR; PG8_SCHED;
;             PG8_LDA(At, 1, 1); PG8_STAGEX(rsB, PG8_SB(1, 0), b3, voffB); PG8_STAGEX(rsB, PG8_SB(1, 1), b3 + hstepB, voffB); PG8_STAGEX(rsA, PG8_SA(1, 0), a3, voffA);
;             PG8_WAIT_V(8); PG8_WAIT_L(0); PG8_BAR; PG8_MMA(1, 0, At, B0); PG8_MMA(1, 1, At, B1); PG8_BAR; PG8_SCHED;
;         }
;     ...
;         if (wr == 0) PG8_BAR;
	s_setprio 0
	v_add_u32_e32 v118, 0x18000, v210
	v_add_u32_e32 v142, 0x1c000, v210
	ds_read_b128 v[106:109], v118
	ds_read_b128 v[110:113], v118 offset:1024
	ds_read_b128 v[114:117], v118 offset:2048
	ds_read_b128 v[118:121], v118 offset:3072
	ds_read_b128 v[122:125], v142
	ds_read_b128 v[126:129], v142 offset:1024
	ds_read_b128 v[130:133], v142 offset:2048
	ds_read_b128 v[142:145], v142 offset:3072
	s_add_i32 s67, s67, 0x80000
	s_mov_b32 m0, s22
	ds_read_b128 v[164:167], v211 offset:32768
	ds_read_b128 v[168:171], v211 offset:33792
	ds_read_b128 v[182:185], v211 offset:34816
	ds_read_b128 v[186:189], v211 offset:35840
	ds_read_b128 v[190:193], v211 offset:36864
	ds_read_b128 v[194:197], v211 offset:37888
	ds_read_b128 v[198:201], v211 offset:38912
	ds_read_b128 v[202:205], v211 offset:39936
	buffer_load_dwordx4 v178, s[40:43], s67 offen lds
	s_mov_b32 m0, s23
	s_nop 0
	buffer_load_dwordx4 v206, s[40:43], s67 offen lds
	s_waitcnt vmcnt(8)
	s_waitcnt lgkmcnt(0)
	s_setprio 1
	s_barrier
	v_mfma_f32_16x16x32_bf16 v[158:161], v[106:109], v[164:167], v[158:161]
	v_mfma_f32_16x16x32_bf16 v[158:161], v[110:113], v[168:171], v[158:161]
	v_mfma_f32_16x16x32_bf16 v[154:157], v[114:117], v[164:167], v[154:157]
	v_mfma_f32_16x16x32_bf16 v[154:157], v[118:121], v[168:171], v[154:157]
	v_mfma_f32_16x16x32_bf16 v[150:153], v[106:109], v[182:185], v[150:153]
	v_mfma_f32_16x16x32_bf16 v[150:153], v[110:113], v[186:189], v[150:153]
	v_mfma_f32_16x16x32_bf16 v[146:149], v[114:117], v[182:185], v[146:149]
	v_mfma_f32_16x16x32_bf16 v[146:149], v[118:121], v[186:189], v[146:149]
	v_mfma_f32_16x16x32_bf16 v[138:141], v[106:109], v[190:193], v[138:141]
	v_mfma_f32_16x16x32_bf16 v[138:141], v[110:113], v[194:197], v[138:141]
	v_mfma_f32_16x16x32_bf16 v[134:137], v[114:117], v[190:193], v[134:137]
	v_mfma_f32_16x16x32_bf16 v[134:137], v[118:121], v[194:197], v[134:137]
	v_mfma_f32_16x16x32_bf16 v[102:105], v[106:109], v[198:201], v[102:105]
	v_mfma_f32_16x16x32_bf16 v[102:105], v[110:113], v[202:205], v[102:105]
	v_mfma_f32_16x16x32_bf16 v[98:101], v[114:117], v[198:201], v[98:101]
	v_mfma_f32_16x16x32_bf16 v[98:101], v[118:121], v[202:205], v[98:101]
	v_mfma_f32_16x16x32_bf16 v[62:65], v[122:125], v[164:167], v[62:65]
	v_mfma_f32_16x16x32_bf16 v[62:65], v[126:129], v[168:171], v[62:65]
	v_mfma_f32_16x16x32_bf16 v[58:61], v[130:133], v[164:167], v[58:61]
	v_mfma_f32_16x16x32_bf16 v[58:61], v[142:145], v[168:171], v[58:61]
	v_mfma_f32_16x16x32_bf16 v[54:57], v[122:125], v[182:185], v[54:57]
	v_mfma_f32_16x16x32_bf16 v[54:57], v[126:129], v[186:189], v[54:57]
	v_mfma_f32_16x16x32_bf16 v[50:53], v[130:133], v[182:185], v[50:53]
	v_mfma_f32_16x16x32_bf16 v[50:53], v[142:145], v[186:189], v[50:53]
	v_mfma_f32_16x16x32_bf16 v[46:49], v[122:125], v[190:193], v[46:49]
	v_mfma_f32_16x16x32_bf16 v[46:49], v[126:129], v[194:197], v[46:49]
	v_mfma_f32_16x16x32_bf16 v[42:45], v[130:133], v[190:193], v[42:45]
	v_mfma_f32_16x16x32_bf16 v[42:45], v[142:145], v[194:197], v[42:45]
	v_mfma_f32_16x16x32_bf16 v[38:41], v[122:125], v[198:201], v[38:41]
	v_mfma_f32_16x16x32_bf16 v[38:41], v[126:129], v[202:205], v[38:41]
	v_mfma_f32_16x16x32_bf16 v[34:37], v[130:133], v[198:201], v[34:37]
	v_mfma_f32_16x16x32_bf16 v[34:37], v[142:145], v[202:205], v[34:37]
	s_barrier
	s_setprio 0
	s_mov_b32 m0, s54
	s_or_b32 s67, s66, 0x80
	ds_read_b128 v[164:167], v211 offset:49152
	ds_read_b128 v[168:171], v211 offset:50176
	ds_read_b128 v[182:185], v211 offset:51200
	ds_read_b128 v[186:189], v211 offset:52224
	ds_read_b128 v[190:193], v211 offset:53248
	ds_read_b128 v[194:197], v211 offset:54272
	ds_read_b128 v[198:201], v211 offset:55296
	ds_read_b128 v[202:205], v211 offset:56320
	buffer_load_dwordx4 v179, s[44:47], s67 offen lds
	s_mov_b32 m0, s55
	s_add_i32 s66, s66, 0x80080
	buffer_load_dwordx4 v207, s[44:47], s67 offen lds
	s_mov_b32 m0, s74
	s_nop 0
	buffer_load_dwordx4 v179, s[44:47], s66 offen lds
	s_mov_b32 m0, s75
	s_nop 0
	buffer_load_dwordx4 v207, s[44:47], s66 offen lds
	s_mov_b32 m0, s72
	s_nop 0
	buffer_load_dwordx4 v178, s[40:43], s65 offen lds
	s_mov_b32 m0, s73
	s_nop 0
	buffer_load_dwordx4 v206, s[40:43], s65 offen lds
	s_waitcnt vmcnt(8)
	s_waitcnt lgkmcnt(0)
	s_setprio 1
	s_barrier
	v_mfma_f32_16x16x32_bf16 v[94:97], v[106:109], v[164:167], v[94:97]
	v_mfma_f32_16x16x32_bf16 v[94:97], v[110:113], v[168:171], v[94:97]
	v_mfma_f32_16x16x32_bf16 v[90:93], v[114:117], v[164:167], v[90:93]
	v_mfma_f32_16x16x32_bf16 v[90:93], v[118:121], v[168:171], v[90:93]
	v_mfma_f32_16x16x32_bf16 v[86:89], v[106:109], v[182:185], v[86:89]
	v_mfma_f32_16x16x32_bf16 v[86:89], v[110:113], v[186:189], v[86:89]
	v_mfma_f32_16x16x32_bf16 v[82:85], v[114:117], v[182:185], v[82:85]
	v_mfma_f32_16x16x32_bf16 v[82:85], v[118:121], v[186:189], v[82:85]
	v_mfma_f32_16x16x32_bf16 v[78:81], v[106:109], v[190:193], v[78:81]
	v_mfma_f32_16x16x32_bf16 v[78:81], v[110:113], v[194:197], v[78:81]
	v_mfma_f32_16x16x32_bf16 v[74:77], v[114:117], v[190:193], v[74:77]
	v_mfma_f32_16x16x32_bf16 v[74:77], v[118:121], v[194:197], v[74:77]
	v_mfma_f32_16x16x32_bf16 v[70:73], v[106:109], v[198:201], v[70:73]
	v_mfma_f32_16x16x32_bf16 v[70:73], v[110:113], v[202:205], v[70:73]
	v_mfma_f32_16x16x32_bf16 v[66:69], v[114:117], v[198:201], v[66:69]
	v_mfma_f32_16x16x32_bf16 v[66:69], v[118:121], v[202:205], v[66:69]
	v_mfma_f32_16x16x32_bf16 v[30:33], v[122:125], v[164:167], v[30:33]
	v_mfma_f32_16x16x32_bf16 v[30:33], v[126:129], v[168:171], v[30:33]
	v_mfma_f32_16x16x32_bf16 v[26:29], v[130:133], v[164:167], v[26:29]
	v_mfma_f32_16x16x32_bf16 v[26:29], v[142:145], v[168:171], v[26:29]
	v_mfma_f32_16x16x32_bf16 v[22:25], v[122:125], v[182:185], v[22:25]
	v_mfma_f32_16x16x32_bf16 v[22:25], v[126:129], v[186:189], v[22:25]
	v_mfma_f32_16x16x32_bf16 v[18:21], v[130:133], v[182:185], v[18:21]
	v_mfma_f32_16x16x32_bf16 v[18:21], v[142:145], v[186:189], v[18:21]
	v_mfma_f32_16x16x32_bf16 v[14:17], v[122:125], v[190:193], v[14:17]
	v_mfma_f32_16x16x32_bf16 v[14:17], v[126:129], v[194:197], v[14:17]
	v_mfma_f32_16x16x32_bf16 v[10:13], v[130:133], v[190:193], v[10:13]
	v_mfma_f32_16x16x32_bf16 v[10:13], v[142:145], v[194:197], v[10:13]
	v_mfma_f32_16x16x32_bf16 v[6:9], v[122:125], v[198:201], v[6:9]
	v_mfma_f32_16x16x32_bf16 v[6:9], v[126:129], v[202:205], v[6:9]
	v_mfma_f32_16x16x32_bf16 v[2:5], v[130:133], v[198:201], v[2:5]
	v_mfma_f32_16x16x32_bf16 v[2:5], v[142:145], v[202:205], v[2:5]
	s_barrier
	s_setprio 0
	s_add_i32 s64, s64, 2
	s_addk_i32 s59, 0x100
	s_addk_i32 s63, 0x100
	s_cmp_gt_u32 s64, 29
	s_cbranch_scc0 .LBB0_1529
	s_and_b64 vcc, exec, s[52:53]
	s_cbranch_vccz .LBB0_1532
	s_barrier

; #define PG8_STAGEX(rs, bufoff, soff, voff) do { _Pragma("unroll") for (int _i = 0; _i < 2; ++_i) \
;         __builtin_amdgcn_raw_ptr_buffer_load_lds(rs, (LAS unsigned*)(lds + (bufoff) + ldsw + _i * 8192), 16, (voff)[_i], (soff), 0, 0); } while (0)
; #define PG8_LDA(dst, b, h) do { _Pragma("unroll") for (int m = 0; m < 4; ++m) _Pragma("unroll") for (int k = 0; k < 2; ++k) dst[m][k] = *(const LAS bf16x8*)(lds + PG8_SA(b, h) + aoff + m * 2048 + k * 1024); } while (0)
; #define PG8_LDB(dst, b, h) do { _Pragma("unroll") for (int n = 0; n < 2; ++n) _Pragma("unroll") for (int k = 0; k < 2; ++k) dst[n][k] = *(const LAS bf16x8*)(lds + PG8_SB(b, h) + boff + n * 2048 + k * 1024); } while (0)
; #define PG8_WAIT_V(n) asm volatile("s_waitcnt vmcnt(" #n ")" ::: "memory")
; #define PG8_WAIT_L(n) asm volatile("s_waitcnt lgkmcnt(" #n ")" ::: "memory")
; #define PG8_BAR __builtin_amdgcn_s_barrier()
; #define PG8_SCHED __builtin_amdgcn_sched_barrier(0)
;     ...
;         for (int t = 0; t < nt; t += 2) {
;             const bool last = (t == nt - 2);
;             const unsigned a1 = cA + (unsigned)(t + 1) * kstep;
;             const unsigned a2 = last ? nA : cA + (unsigned)(t + 2) * kstep, b2 = last ? nB : cB + (unsigned)(t + 2) * kstep;
;             const unsigned a3 = a2 + kstep, b3 = b2 + kstep;
;             PG8_LDB(B0, 0, 0); PG8_LDB(B1, 0, 1); PG8_SCHED; PG8_LDA(At, 0, 0); PG8_STAGEX(rsA, PG8_SA(1, 1), a1 + hstepA, voffA);
;             PG8_WAIT_V(8); PG8_WAIT_L(0); PG8_BAR; PG8_MMA(0, 0, At, B0); PG8_MMA(0, 1, At, B1); PG8_BAR; PG8_SCHED;
;             PG8_LDA(At, 0, 1); PG8_STAGEX(rsB, PG8_SB(0, 0), b2, voffB); PG8_STAGEX(rsB, PG8_SB(0, 1), b2 + hstepB, voffB); PG8_STAGEX(rsA, PG8_SA(0, 0), a2, voffA);
;             PG8_WAIT_V(8); PG8_WAIT_L(0); PG8_BAR; PG8_MMA(1, 0, At, B0); PG8_MMA(1, 1, At, B1); PG8_BAR; PG8_SCHED;
.LBB0_1651:
	v_add_u32_e32 v102, 0x10000, v172
	v_add_u32_e32 v146, 0x14000, v172
	ds_read_b128 v[82:85], v102
	ds_read_b128 v[86:89], v102 offset:1024
	ds_read_b128 v[98:101], v102 offset:2048
	ds_read_b128 v[102:105], v102 offset:3072
	ds_read_b128 v[150:153], v146
	ds_read_b128 v[154:157], v146 offset:1024
	ds_read_b128 v[182:185], v146 offset:2048
	ds_read_b128 v[186:189], v146 offset:3072
	s_add_i32 s42, s61, 0xfff80080
	s_cmp_eq_u32 s63, 28
	s_cselect_b32 s66, s30, s42
	s_cselect_b32 s65, s31, s62
	s_or_b32 s64, s66, 0x80
	s_mov_b32 m0, s29
	ds_read_b128 v[190:193], v173
	ds_read_b128 v[194:197], v173 offset:1024
	ds_read_b128 v[198:201], v173 offset:2048
	ds_read_b128 v[202:205], v173 offset:3072
	ds_read_b128 v[206:209], v173 offset:4096
	ds_read_b128 v[210:213], v173 offset:5120
	ds_read_b128 v[214:217], v173 offset:6144
	ds_read_b128 v[218:221], v173 offset:7168
	buffer_load_dwordx4 v159, s[76:79], s61 offen lds
	s_mov_b32 m0, s50
	s_nop 0
	buffer_load_dwordx4 v163, s[76:79], s61 offen lds
	s_waitcnt vmcnt(8)
	s_waitcnt lgkmcnt(0)
	s_setprio 1
	s_barrier
	v_mfma_f32_16x16x32_bf16 v[142:145], v[82:85], v[190:193], v[142:145]
	v_mfma_f32_16x16x32_bf16 v[142:145], v[86:89], v[194:197], v[142:145]
	v_mfma_f32_16x16x32_bf16 v[134:137], v[98:101], v[190:193], v[134:137]
	v_mfma_f32_16x16x32_bf16 v[134:137], v[102:105], v[194:197], v[134:137]
	v_mfma_f32_16x16x32_bf16 v[126:129], v[82:85], v[198:201], v[126:129]
	v_mfma_f32_16x16x32_bf16 v[126:129], v[86:89], v[202:205], v[126:129]
	v_mfma_f32_16x16x32_bf16 v[118:121], v[98:101], v[198:201], v[118:121]
	v_mfma_f32_16x16x32_bf16 v[118:121], v[102:105], v[202:205], v[118:121]
	v_mfma_f32_16x16x32_bf16 v[110:113], v[82:85], v[206:209], v[110:113]
	v_mfma_f32_16x16x32_bf16 v[110:113], v[86:89], v[210:213], v[110:113]
	v_mfma_f32_16x16x32_bf16 v[94:97], v[98:101], v[206:209], v[94:97]
	v_mfma_f32_16x16x32_bf16 v[94:97], v[102:105], v[210:213], v[94:97]
	v_mfma_f32_16x16x32_bf16 v[78:81], v[82:85], v[214:217], v[78:81]
	v_mfma_f32_16x16x32_bf16 v[78:81], v[86:89], v[218:221], v[78:81]
	v_mfma_f32_16x16x32_bf16 v[70:73], v[98:101], v[214:217], v[70:73]
	v_mfma_f32_16x16x32_bf16 v[70:73], v[102:105], v[218:221], v[70:73]
	v_mfma_f32_16x16x32_bf16 v[138:141], v[150:153], v[190:193], v[138:141]
	v_mfma_f32_16x16x32_bf16 v[138:141], v[154:157], v[194:197], v[138:141]
	v_mfma_f32_16x16x32_bf16 v[130:133], v[182:185], v[190:193], v[130:133]
	v_mfma_f32_16x16x32_bf16 v[130:133], v[186:189], v[194:197], v[130:133]
	v_mfma_f32_16x16x32_bf16 v[122:125], v[150:153], v[198:201], v[122:125]
	v_mfma_f32_16x16x32_bf16 v[122:125], v[154:157], v[202:205], v[122:125]
	v_mfma_f32_16x16x32_bf16 v[114:117], v[182:185], v[198:201], v[114:117]
	v_mfma_f32_16x16x32_bf16 v[114:117], v[186:189], v[202:205], v[114:117]
	v_mfma_f32_16x16x32_bf16 v[106:109], v[150:153], v[206:209], v[106:109]
	v_mfma_f32_16x16x32_bf16 v[106:109], v[154:157], v[210:213], v[106:109]
	v_mfma_f32_16x16x32_bf16 v[90:93], v[182:185], v[206:209], v[90:93]
	v_mfma_f32_16x16x32_bf16 v[90:93], v[186:189], v[210:213], v[90:93]
	v_mfma_f32_16x16x32_bf16 v[74:77], v[150:153], v[214:217], v[74:77]
	v_mfma_f32_16x16x32_bf16 v[74:77], v[154:157], v[218:221], v[74:77]
	v_mfma_f32_16x16x32_bf16 v[66:69], v[182:185], v[214:217], v[66:69]
	v_mfma_f32_16x16x32_bf16 v[66:69], v[186:189], v[218:221], v[66:69]
	s_barrier
	s_setprio 0
	s_mov_b32 m0, s16
	s_mov_b32 s42, s78
	s_mov_b32 s43, s79
	ds_read_b128 v[190:193], v173 offset:16384
	ds_read_b128 v[194:197], v173 offset:17408
	ds_read_b128 v[198:201], v173 offset:18432
	ds_read_b128 v[202:205], v173 offset:19456
	ds_read_b128 v[206:209], v173 offset:20480
	ds_read_b128 v[210:213], v173 offset:21504
	ds_read_b128 v[214:217], v173 offset:22528
	ds_read_b128 v[218:221], v173 offset:23552
	buffer_load_dwordx4 v161, s[40:43], s65 offen lds
	s_mov_b32 m0, s17
	s_add_i32 s67, s65, 0x80000
	buffer_load_dwordx4 v165, s[40:43], s65 offen lds
	s_mov_b32 m0, s18
	s_nop 0
	buffer_load_dwordx4 v161, s[40:43], s67 offen lds
	s_mov_b32 m0, s19
	s_nop 0
	buffer_load_dwordx4 v165, s[40:43], s67 offen lds
	s_mov_b32 m0, s15
	s_nop 0
	buffer_load_dwordx4 v159, s[76:79], s66 offen lds
	s_mov_b32 m0, s20
	s_nop 0
	buffer_load_dwordx4 v163, s[76:79], s66 offen lds
	s_waitcnt vmcnt(8)
	s_waitcnt lgkmcnt(0)
	s_setprio 1
	s_barrier
	v_mfma_f32_16x16x32_bf16 v[62:65], v[82:85], v[190:193], v[62:65]
	v_mfma_f32_16x16x32_bf16 v[62:65], v[86:89], v[194:197], v[62:65]
	v_mfma_f32_16x16x32_bf16 v[54:57], v[98:101], v[190:193], v[54:57]
	v_mfma_f32_16x16x32_bf16 v[54:57], v[102:105], v[194:197], v[54:57]
	v_mfma_f32_16x16x32_bf16 v[46:49], v[82:85], v[198:201], v[46:49]
	v_mfma_f32_16x16x32_bf16 v[46:49], v[86:89], v[202:205], v[46:49]
	v_mfma_f32_16x16x32_bf16 v[38:41], v[98:101], v[198:201], v[38:41]
	v_mfma_f32_16x16x32_bf16 v[38:41], v[102:105], v[202:205], v[38:41]
	v_mfma_f32_16x16x32_bf16 v[30:33], v[82:85], v[206:209], v[30:33]
	v_mfma_f32_16x16x32_bf16 v[30:33], v[86:89], v[210:213], v[30:33]
	v_mfma_f32_16x16x32_bf16 v[22:25], v[98:101], v[206:209], v[22:25]
	v_mfma_f32_16x16x32_bf16 v[22:25], v[102:105], v[210:213], v[22:25]
	v_mfma_f32_16x16x32_bf16 v[14:17], v[82:85], v[214:217], v[14:17]
	v_mfma_f32_16x16x32_bf16 v[14:17], v[86:89], v[218:221], v[14:17]
	v_mfma_f32_16x16x32_bf16 v[6:9], v[98:101], v[214:217], v[6:9]
	v_mfma_f32_16x16x32_bf16 v[6:9], v[102:105], v[218:221], v[6:9]
	v_mfma_f32_16x16x32_bf16 v[58:61], v[150:153], v[190:193], v[58:61]
	v_mfma_f32_16x16x32_bf16 v[58:61], v[154:157], v[194:197], v[58:61]
	v_mfma_f32_16x16x32_bf16 v[50:53], v[182:185], v[190:193], v[50:53]
	v_mfma_f32_16x16x32_bf16 v[50:53], v[186:189], v[194:197], v[50:53]
	v_mfma_f32_16x16x32_bf16 v[42:45], v[150:153], v[198:201], v[42:45]
	v_mfma_f32_16x16x32_bf16 v[42:45], v[154:157], v[202:205], v[42:45]
	v_mfma_f32_16x16x32_bf16 v[34:37], v[182:185], v[198:201], v[34:37]
	v_mfma_f32_16x16x32_bf16 v[34:37], v[186:189], v[202:205], v[34:37]
	v_mfma_f32_16x16x32_bf16 v[26:29], v[150:153], v[206:209], v[26:29]
	v_mfma_f32_16x16x32_bf16 v[26:29], v[154:157], v[210:213], v[26:29]
	v_mfma_f32_16x16x32_bf16 v[18:21], v[182:185], v[206:209], v[18:21]
	v_mfma_f32_16x16x32_bf16 v[18:21], v[186:189], v[210:213], v[18:21]
	v_mfma_f32_16x16x32_bf16 v[10:13], v[150:153], v[214:217], v[10:13]
	v_mfma_f32_16x16x32_bf16 v[10:13], v[154:157], v[218:221], v[10:13]
	v_mfma_f32_16x16x32_bf16 v[2:5], v[182:185], v[214:217], v[2:5]
	v_mfma_f32_16x16x32_bf16 v[2:5], v[186:189], v[218:221], v[2:5]
	s_barrier
; #define PG8_STAGEX(rs, bufoff, soff, voff) do { _Pragma("unroll") for (int _i = 0; _i < 2; ++_i) \
;         __builtin_amdgcn_raw_ptr_buffer_load_lds(rs, (LAS unsigned*)(lds + (bufoff) + ldsw + _i * 8192), 16, (voff)[_i], (soff), 0, 0); } while (0)
; #define PG8_LDA(dst, b, h) do { _Pragma("unroll") for (int m = 0; m < 4; ++m) _Pragma("unroll") for (int k = 0; k < 2; ++k) dst[m][k] = *(const LAS bf16x8*)(lds + PG8_SA(b, h) + aoff + m * 2048 + k * 1024); } while (0)
; #define PG8_LDB(dst, b, h) do { _Pragma("unroll") for (int n = 0; n < 2; ++n) _Pragma("unroll") for (int k = 0; k < 2; ++k) dst[n][k] = *(const LAS bf16x8*)(lds + PG8_SB(b, h) + boff + n * 2048 + k * 1024); } while (0)
; #define PG8_WAIT_V(n) asm volatile("s_waitcnt vmcnt(" #n ")" ::: "memory")
; #define PG8_WAIT_L(n) asm volatile("s_waitcnt lgkmcnt(" #n ")" ::: "memory")
; #define PG8_BAR __builtin_amdgcn_s_barrier()
; #define PG8_SCHED __builtin_amdgcn_sched_barrier(0)
;     ...
;             PG8_LDB(B0, 1, 0); PG8_LDB(B1, 1, 1); PG8_SCHED; PG8_LDA(At, 1, 0); PG8_STAGEX(rsA, PG8_SA(0, 1), a2 + hstepA, voffA);
;             PG8_WAIT_V(8); PG8_WAIT_L(0); PG8_BAR; PG8_MMA(0, 0, At, B0); PG8_MMA(0, 1, At, B1); PG8_BAR; PG8_SCHED;
;             PG8_LDA(At, 1, 1); PG8_STAGEX(rsB, PG8_SB(1, 0), b3, voffB); PG8_STAGEX(rsB, PG8_SB(1, 1), b3 + hstepB, voffB); PG8_STAGEX(rsA, PG8_SA(1, 0), a3, voffA);
;             PG8_WAIT_V(8); PG8_WAIT_L(0); PG8_BAR; PG8_MMA(1, 0, At, B0); PG8_MMA(1, 1, At, B1); PG8_BAR; PG8_SCHED;
;         }
;     ...
;         if (wr == 0) PG8_BAR;
	s_setprio 0
	v_add_u32_e32 v102, 0x18000, v172
	v_add_u32_e32 v146, 0x1c000, v172
	ds_read_b128 v[82:85], v102
	ds_read_b128 v[86:89], v102 offset:1024
	ds_read_b128 v[98:101], v102 offset:2048
	ds_read_b128 v[102:105], v102 offset:3072
	ds_read_b128 v[150:153], v146
	ds_read_b128 v[154:157], v146 offset:1024
	ds_read_b128 v[182:185], v146 offset:2048
	ds_read_b128 v[186:189], v146 offset:3072
	s_add_i32 s66, s66, 0x80000
	s_mov_b32 m0, s21
	ds_read_b128 v[190:193], v173 offset:32768
	ds_read_b128 v[194:197], v173 offset:33792
	ds_read_b128 v[198:201], v173 offset:34816
	ds_read_b128 v[202:205], v173 offset:35840
	ds_read_b128 v[206:209], v173 offset:36864
	ds_read_b128 v[210:213], v173 offset:37888
	ds_read_b128 v[214:217], v173 offset:38912
	ds_read_b128 v[218:221], v173 offset:39936
	buffer_load_dwordx4 v159, s[76:79], s66 offen lds
	s_mov_b32 m0, s22
	s_nop 0
	buffer_load_dwordx4 v163, s[76:79], s66 offen lds
	s_waitcnt vmcnt(8)
	s_waitcnt lgkmcnt(0)
	s_setprio 1
	s_barrier
	v_mfma_f32_16x16x32_bf16 v[142:145], v[82:85], v[190:193], v[142:145]
	v_mfma_f32_16x16x32_bf16 v[142:145], v[86:89], v[194:197], v[142:145]
	v_mfma_f32_16x16x32_bf16 v[134:137], v[98:101], v[190:193], v[134:137]
	v_mfma_f32_16x16x32_bf16 v[134:137], v[102:105], v[194:197], v[134:137]
	v_mfma_f32_16x16x32_bf16 v[126:129], v[82:85], v[198:201], v[126:129]
	v_mfma_f32_16x16x32_bf16 v[126:129], v[86:89], v[202:205], v[126:129]
	v_mfma_f32_16x16x32_bf16 v[118:121], v[98:101], v[198:201], v[118:121]
	v_mfma_f32_16x16x32_bf16 v[118:121], v[102:105], v[202:205], v[118:121]
	v_mfma_f32_16x16x32_bf16 v[110:113], v[82:85], v[206:209], v[110:113]
	v_mfma_f32_16x16x32_bf16 v[110:113], v[86:89], v[210:213], v[110:113]
	v_mfma_f32_16x16x32_bf16 v[94:97], v[98:101], v[206:209], v[94:97]
	v_mfma_f32_16x16x32_bf16 v[94:97], v[102:105], v[210:213], v[94:97]
	v_mfma_f32_16x16x32_bf16 v[78:81], v[82:85], v[214:217], v[78:81]
	v_mfma_f32_16x16x32_bf16 v[78:81], v[86:89], v[218:221], v[78:81]
	v_mfma_f32_16x16x32_bf16 v[70:73], v[98:101], v[214:217], v[70:73]
	v_mfma_f32_16x16x32_bf16 v[70:73], v[102:105], v[218:221], v[70:73]
	v_mfma_f32_16x16x32_bf16 v[138:141], v[150:153], v[190:193], v[138:141]
	v_mfma_f32_16x16x32_bf16 v[138:141], v[154:157], v[194:197], v[138:141]
	v_mfma_f32_16x16x32_bf16 v[130:133], v[182:185], v[190:193], v[130:133]
	v_mfma_f32_16x16x32_bf16 v[130:133], v[186:189], v[194:197], v[130:133]
	v_mfma_f32_16x16x32_bf16 v[122:125], v[150:153], v[198:201], v[122:125]
	v_mfma_f32_16x16x32_bf16 v[122:125], v[154:157], v[202:205], v[122:125]
	v_mfma_f32_16x16x32_bf16 v[114:117], v[182:185], v[198:201], v[114:117]
	v_mfma_f32_16x16x32_bf16 v[114:117], v[186:189], v[202:205], v[114:117]
	v_mfma_f32_16x16x32_bf16 v[106:109], v[150:153], v[206:209], v[106:109]
	v_mfma_f32_16x16x32_bf16 v[106:109], v[154:157], v[210:213], v[106:109]
	v_mfma_f32_16x16x32_bf16 v[90:93], v[182:185], v[206:209], v[90:93]
	v_mfma_f32_16x16x32_bf16 v[90:93], v[186:189], v[210:213], v[90:93]
	v_mfma_f32_16x16x32_bf16 v[74:77], v[150:153], v[214:217], v[74:77]
	v_mfma_f32_16x16x32_bf16 v[74:77], v[154:157], v[218:221], v[74:77]
	v_mfma_f32_16x16x32_bf16 v[66:69], v[182:185], v[214:217], v[66:69]
	v_mfma_f32_16x16x32_bf16 v[66:69], v[186:189], v[218:221], v[66:69]
	s_barrier
	s_setprio 0
	s_mov_b32 m0, s23
	s_or_b32 s66, s65, 0x80
	ds_read_b128 v[190:193], v173 offset:49152
	ds_read_b128 v[194:197], v173 offset:50176
	ds_read_b128 v[198:201], v173 offset:51200
	ds_read_b128 v[202:205], v173 offset:52224
	ds_read_b128 v[206:209], v173 offset:53248
	ds_read_b128 v[210:213], v173 offset:54272
	ds_read_b128 v[214:217], v173 offset:55296
	ds_read_b128 v[218:221], v173 offset:56320
	buffer_load_dwordx4 v161, s[40:43], s66 offen lds
	s_mov_b32 m0, s24
	s_add_i32 s65, s65, 0x80080
	buffer_load_dwordx4 v165, s[40:43], s66 offen lds
	s_mov_b32 m0, s27
	s_nop 0
	buffer_load_dwordx4 v161, s[40:43], s65 offen lds
	s_mov_b32 m0, s28
	s_nop 0
	buffer_load_dwordx4 v165, s[40:43], s65 offen lds
	s_mov_b32 m0, s25
	s_nop 0
	buffer_load_dwordx4 v159, s[76:79], s64 offen lds
	s_mov_b32 m0, s26
	s_nop 0
	buffer_load_dwordx4 v163, s[76:79], s64 offen lds
	s_waitcnt vmcnt(8)
	s_waitcnt lgkmcnt(0)
	s_setprio 1
	s_barrier
	v_mfma_f32_16x16x32_bf16 v[62:65], v[82:85], v[190:193], v[62:65]
	v_mfma_f32_16x16x32_bf16 v[62:65], v[86:89], v[194:197], v[62:65]
	v_mfma_f32_16x16x32_bf16 v[54:57], v[98:101], v[190:193], v[54:57]
	v_mfma_f32_16x16x32_bf16 v[54:57], v[102:105], v[194:197], v[54:57]
	v_mfma_f32_16x16x32_bf16 v[46:49], v[82:85], v[198:201], v[46:49]
	v_mfma_f32_16x16x32_bf16 v[46:49], v[86:89], v[202:205], v[46:49]
	v_mfma_f32_16x16x32_bf16 v[38:41], v[98:101], v[198:201], v[38:41]
	v_mfma_f32_16x16x32_bf16 v[38:41], v[102:105], v[202:205], v[38:41]
	v_mfma_f32_16x16x32_bf16 v[30:33], v[82:85], v[206:209], v[30:33]
	v_mfma_f32_16x16x32_bf16 v[30:33], v[86:89], v[210:213], v[30:33]
	v_mfma_f32_16x16x32_bf16 v[22:25], v[98:101], v[206:209], v[22:25]
	v_mfma_f32_16x16x32_bf16 v[22:25], v[102:105], v[210:213], v[22:25]
	v_mfma_f32_16x16x32_bf16 v[14:17], v[82:85], v[214:217], v[14:17]
	v_mfma_f32_16x16x32_bf16 v[14:17], v[86:89], v[218:221], v[14:17]
	v_mfma_f32_16x16x32_bf16 v[6:9], v[98:101], v[214:217], v[6:9]
	v_mfma_f32_16x16x32_bf16 v[6:9], v[102:105], v[218:221], v[6:9]
	v_mfma_f32_16x16x32_bf16 v[58:61], v[150:153], v[190:193], v[58:61]
	v_mfma_f32_16x16x32_bf16 v[58:61], v[154:157], v[194:197], v[58:61]
	v_mfma_f32_16x16x32_bf16 v[50:53], v[182:185], v[190:193], v[50:53]
	v_mfma_f32_16x16x32_bf16 v[50:53], v[186:189], v[194:197], v[50:53]
	v_mfma_f32_16x16x32_bf16 v[42:45], v[150:153], v[198:201], v[42:45]
	v_mfma_f32_16x16x32_bf16 v[42:45], v[154:157], v[202:205], v[42:45]
	v_mfma_f32_16x16x32_bf16 v[34:37], v[182:185], v[198:201], v[34:37]
	v_mfma_f32_16x16x32_bf16 v[34:37], v[186:189], v[202:205], v[34:37]
	v_mfma_f32_16x16x32_bf16 v[26:29], v[150:153], v[206:209], v[26:29]
	v_mfma_f32_16x16x32_bf16 v[26:29], v[154:157], v[210:213], v[26:29]
	v_mfma_f32_16x16x32_bf16 v[18:21], v[182:185], v[206:209], v[18:21]
	v_mfma_f32_16x16x32_bf16 v[18:21], v[186:189], v[210:213], v[18:21]
	v_mfma_f32_16x16x32_bf16 v[10:13], v[150:153], v[214:217], v[10:13]
	v_mfma_f32_16x16x32_bf16 v[10:13], v[154:157], v[218:221], v[10:13]
	v_mfma_f32_16x16x32_bf16 v[2:5], v[182:185], v[214:217], v[2:5]
	v_mfma_f32_16x16x32_bf16 v[2:5], v[186:189], v[218:221], v[2:5]
	s_barrier
	s_setprio 0
	s_add_i32 s63, s63, 2
	s_addk_i32 s61, 0x100
	s_addk_i32 s62, 0x100
	s_cmp_gt_u32 s63, 29
	s_cbranch_scc0 .LBB0_1651
	s_and_b64 vcc, exec, s[48:49]
	s_cbranch_vccz .LBB0_1654
	s_barrier

; #define PG8_STAGEX(rs, bufoff, soff, voff) do { _Pragma("unroll") for (int _i = 0; _i < 2; ++_i) \
;         __builtin_amdgcn_raw_ptr_buffer_load_lds(rs, (LAS unsigned*)(lds + (bufoff) + ldsw + _i * 8192), 16, (voff)[_i], (soff), 0, 0); } while (0)
; #define PG8_LDA(dst, b, h) do { _Pragma("unroll") for (int m = 0; m < 4; ++m) _Pragma("unroll") for (int k = 0; k < 2; ++k) dst[m][k] = *(const LAS bf16x8*)(lds + PG8_SA(b, h) + aoff + m * 2048 + k * 1024); } while (0)
; #define PG8_LDB(dst, b, h) do { _Pragma("unroll") for (int n = 0; n < 2; ++n) _Pragma("unroll") for (int k = 0; k < 2; ++k) dst[n][k] = *(const LAS bf16x8*)(lds + PG8_SB(b, h) + boff + n * 2048 + k * 1024); } while (0)
; #define PG8_WAIT_V(n) asm volatile("s_waitcnt vmcnt(" #n ")" ::: "memory")
; #define PG8_WAIT_L(n) asm volatile("s_waitcnt lgkmcnt(" #n ")" ::: "memory")
; #define PG8_BAR __builtin_amdgcn_s_barrier()
; #define PG8_SCHED __builtin_amdgcn_sched_barrier(0)
;     ...
;             for (int t = 0; t < nt; t += 2) {
;                 const bool last = (t == nt - 2);
;                 const unsigned a1 = cA + (unsigned)(t + 1) * kstep;
;                 const unsigned a2 = last ? nA : cA + (unsigned)(t + 2) * kstep, b2 = last ? nB : cB + (unsigned)(t + 2) * kstep;
;                 const unsigned a3 = a2 + kstep, b3 = b2 + kstep;
;                 if (w0) { PG8_LDB(B0, 0, 0); PG8_LDB(B1, 0, 1); PG8_SCHED; PG8_LDA(At, 0, 0); }
;                 PG8_WAIT_L(0); PG8_BAR; if (w0) { PG8_MMA(0, 0, At, B0); PG8_MMA(0, 1, At, B1); } PG8_BAR; PG8_SCHED;
;                 PG8_STAGEX(rsB, PG8_SB(0, 0), b2, voffB); PG8_STAGEX(rsB, PG8_SB(0, 1), b2 + hstepB, voffB); PG8_STAGEX(rsA, PG8_SA(0, 0), a2, voffA);
;                 PG8_WAIT_V(6); PG8_BAR; PG8_BAR; PG8_SCHED;
.LBB0_1668:
	v_add_u32_e32 v86, 0x10000, v72
	v_add_u32_e32 v102, 0x14000, v72
	ds_read_b128 v[74:77], v86
	ds_read_b128 v[78:81], v86 offset:1024
	ds_read_b128 v[82:85], v86 offset:2048
	ds_read_b128 v[86:89], v86 offset:3072
	ds_read_b128 v[90:93], v102
	ds_read_b128 v[94:97], v102 offset:1024
	ds_read_b128 v[98:101], v102 offset:2048
	ds_read_b128 v[102:105], v102 offset:3072
	s_cmp_lg_u32 s27, 28
	s_cselect_b32 s28, s26, 0
	s_add_i32 s29, s28, s17
	s_or_b32 s30, s29, 0x80
	s_add_i32 s28, s28, s10
	ds_read_b128 v[106:109], v73
	ds_read_b128 v[110:113], v73 offset:1024
	ds_read_b128 v[114:117], v73 offset:2048
	ds_read_b128 v[118:121], v73 offset:3072
	ds_read_b128 v[122:125], v73 offset:4096
	ds_read_b128 v[126:129], v73 offset:5120
	ds_read_b128 v[130:133], v73 offset:6144
	ds_read_b128 v[134:137], v73 offset:7168
	s_waitcnt lgkmcnt(0)
	s_setprio 1
	s_barrier
	v_mfma_f32_16x16x32_bf16 v[62:65], v[74:77], v[106:109], v[62:65]
	v_mfma_f32_16x16x32_bf16 v[62:65], v[78:81], v[110:113], v[62:65]
	v_mfma_f32_16x16x32_bf16 v[58:61], v[82:85], v[106:109], v[58:61]
	v_mfma_f32_16x16x32_bf16 v[58:61], v[86:89], v[110:113], v[58:61]
	v_mfma_f32_16x16x32_bf16 v[54:57], v[74:77], v[114:117], v[54:57]
	v_mfma_f32_16x16x32_bf16 v[54:57], v[78:81], v[118:121], v[54:57]
	v_mfma_f32_16x16x32_bf16 v[38:41], v[82:85], v[114:117], v[38:41]
	v_mfma_f32_16x16x32_bf16 v[38:41], v[86:89], v[118:121], v[38:41]
	v_mfma_f32_16x16x32_bf16 v[30:33], v[74:77], v[122:125], v[30:33]
	v_mfma_f32_16x16x32_bf16 v[30:33], v[78:81], v[126:129], v[30:33]
	v_mfma_f32_16x16x32_bf16 v[22:25], v[82:85], v[122:125], v[22:25]
	v_mfma_f32_16x16x32_bf16 v[22:25], v[86:89], v[126:129], v[22:25]
	v_mfma_f32_16x16x32_bf16 v[14:17], v[74:77], v[130:133], v[14:17]
	v_mfma_f32_16x16x32_bf16 v[14:17], v[78:81], v[134:137], v[14:17]
	v_mfma_f32_16x16x32_bf16 v[6:9], v[82:85], v[130:133], v[6:9]
	v_mfma_f32_16x16x32_bf16 v[6:9], v[86:89], v[134:137], v[6:9]
	v_mfma_f32_16x16x32_bf16 v[50:53], v[90:93], v[106:109], v[50:53]
	v_mfma_f32_16x16x32_bf16 v[50:53], v[94:97], v[110:113], v[50:53]
	v_mfma_f32_16x16x32_bf16 v[46:49], v[98:101], v[106:109], v[46:49]
	v_mfma_f32_16x16x32_bf16 v[46:49], v[102:105], v[110:113], v[46:49]
	v_mfma_f32_16x16x32_bf16 v[42:45], v[90:93], v[114:117], v[42:45]
	v_mfma_f32_16x16x32_bf16 v[42:45], v[94:97], v[118:121], v[42:45]
	v_mfma_f32_16x16x32_bf16 v[34:37], v[98:101], v[114:117], v[34:37]
	v_mfma_f32_16x16x32_bf16 v[34:37], v[102:105], v[118:121], v[34:37]
	v_mfma_f32_16x16x32_bf16 v[26:29], v[90:93], v[122:125], v[26:29]
	v_mfma_f32_16x16x32_bf16 v[26:29], v[94:97], v[126:129], v[26:29]
	v_mfma_f32_16x16x32_bf16 v[18:21], v[98:101], v[122:125], v[18:21]
	v_mfma_f32_16x16x32_bf16 v[18:21], v[102:105], v[126:129], v[18:21]
	v_mfma_f32_16x16x32_bf16 v[10:13], v[90:93], v[130:133], v[10:13]
	v_mfma_f32_16x16x32_bf16 v[10:13], v[94:97], v[134:137], v[10:13]
	v_mfma_f32_16x16x32_bf16 v[2:5], v[98:101], v[130:133], v[2:5]
	v_mfma_f32_16x16x32_bf16 v[2:5], v[102:105], v[134:137], v[2:5]
	s_barrier
	s_setprio 0
	s_mov_b32 m0, s13
	s_mov_b32 s42, s78
	s_mov_b32 s43, s79
	buffer_load_dwordx4 v67, s[40:43], s28 offen lds
	s_mov_b32 m0, s14
	s_add_i32 s31, s28, 0x80000
	buffer_load_dwordx4 v69, s[40:43], s28 offen lds
	s_mov_b32 m0, s15
	s_nop 0
	buffer_load_dwordx4 v67, s[40:43], s31 offen lds
	s_mov_b32 m0, s16
	s_nop 0
	buffer_load_dwordx4 v69, s[40:43], s31 offen lds
	s_mov_b32 m0, s12
	s_nop 0
	buffer_load_dwordx4 v66, s[76:79], s29 offen lds
	s_mov_b32 m0, s18
	s_nop 0
	buffer_load_dwordx4 v68, s[76:79], s29 offen lds
	s_waitcnt vmcnt(6)
	s_barrier
	s_barrier
; #define PG8_STAGEX(rs, bufoff, soff, voff) do { _Pragma("unroll") for (int _i = 0; _i < 2; ++_i) \
;         __builtin_amdgcn_raw_ptr_buffer_load_lds(rs, (LAS unsigned*)(lds + (bufoff) + ldsw + _i * 8192), 16, (voff)[_i], (soff), 0, 0); } while (0)
; #define PG8_LDA(dst, b, h) do { _Pragma("unroll") for (int m = 0; m < 4; ++m) _Pragma("unroll") for (int k = 0; k < 2; ++k) dst[m][k] = *(const LAS bf16x8*)(lds + PG8_SA(b, h) + aoff + m * 2048 + k * 1024); } while (0)
; #define PG8_LDB(dst, b, h) do { _Pragma("unroll") for (int n = 0; n < 2; ++n) _Pragma("unroll") for (int k = 0; k < 2; ++k) dst[n][k] = *(const LAS bf16x8*)(lds + PG8_SB(b, h) + boff + n * 2048 + k * 1024); } while (0)
; #define PG8_WAIT_V(n) asm volatile("s_waitcnt vmcnt(" #n ")" ::: "memory")
; #define PG8_WAIT_L(n) asm volatile("s_waitcnt lgkmcnt(" #n ")" ::: "memory")
; #define PG8_BAR __builtin_amdgcn_s_barrier()
; #define PG8_SCHED __builtin_amdgcn_sched_barrier(0)
;     ...
;                 if (w0) { PG8_LDB(B0, 1, 0); PG8_LDB(B1, 1, 1); PG8_SCHED; PG8_LDA(At, 1, 0); }
;                 PG8_WAIT_L(0); PG8_BAR; if (w0) { PG8_MMA(0, 0, At, B0); PG8_MMA(0, 1, At, B1); } PG8_BAR; PG8_SCHED;
;                 PG8_STAGEX(rsB, PG8_SB(1, 0), b3, voffB); PG8_STAGEX(rsB, PG8_SB(1, 1), b3 + hstepB, voffB); PG8_STAGEX(rsA, PG8_SA(1, 0), a3, voffA);
;                 PG8_WAIT_V(6); PG8_BAR; PG8_BAR; PG8_SCHED;
;             }
;         }
;         if (wr == 0) PG8_BAR;
	v_add_u32_e32 v86, 0x18000, v72
	v_add_u32_e32 v102, 0x1c000, v72
	ds_read_b128 v[74:77], v86
	ds_read_b128 v[78:81], v86 offset:1024
	ds_read_b128 v[82:85], v86 offset:2048
	ds_read_b128 v[86:89], v86 offset:3072
	ds_read_b128 v[90:93], v102
	ds_read_b128 v[94:97], v102 offset:1024
	ds_read_b128 v[98:101], v102 offset:2048
	ds_read_b128 v[102:105], v102 offset:3072
	ds_read_b128 v[106:109], v73 offset:32768
	ds_read_b128 v[110:113], v73 offset:33792
	ds_read_b128 v[114:117], v73 offset:34816
	ds_read_b128 v[118:121], v73 offset:35840
	ds_read_b128 v[122:125], v73 offset:36864
	ds_read_b128 v[126:129], v73 offset:37888
	ds_read_b128 v[130:133], v73 offset:38912
	ds_read_b128 v[134:137], v73 offset:39936
	s_waitcnt lgkmcnt(0)
	s_setprio 1
	s_barrier
	v_mfma_f32_16x16x32_bf16 v[62:65], v[74:77], v[106:109], v[62:65]
	v_mfma_f32_16x16x32_bf16 v[58:61], v[82:85], v[106:109], v[58:61]
	v_mfma_f32_16x16x32_bf16 v[54:57], v[74:77], v[114:117], v[54:57]
	v_mfma_f32_16x16x32_bf16 v[38:41], v[82:85], v[114:117], v[38:41]
	v_mfma_f32_16x16x32_bf16 v[30:33], v[74:77], v[122:125], v[30:33]
	v_mfma_f32_16x16x32_bf16 v[22:25], v[82:85], v[122:125], v[22:25]
	v_mfma_f32_16x16x32_bf16 v[14:17], v[74:77], v[130:133], v[14:17]
	v_mfma_f32_16x16x32_bf16 v[6:9], v[82:85], v[130:133], v[6:9]
	v_mfma_f32_16x16x32_bf16 v[62:65], v[78:81], v[110:113], v[62:65]
	v_mfma_f32_16x16x32_bf16 v[58:61], v[86:89], v[110:113], v[58:61]
	v_mfma_f32_16x16x32_bf16 v[54:57], v[78:81], v[118:121], v[54:57]
	v_mfma_f32_16x16x32_bf16 v[38:41], v[86:89], v[118:121], v[38:41]
	v_mfma_f32_16x16x32_bf16 v[30:33], v[78:81], v[126:129], v[30:33]
	v_mfma_f32_16x16x32_bf16 v[22:25], v[86:89], v[126:129], v[22:25]
	v_mfma_f32_16x16x32_bf16 v[14:17], v[78:81], v[134:137], v[14:17]
	v_mfma_f32_16x16x32_bf16 v[6:9], v[86:89], v[134:137], v[6:9]
	v_mfma_f32_16x16x32_bf16 v[50:53], v[90:93], v[106:109], v[50:53]
	s_or_b32 s29, s28, 0x80
	v_mfma_f32_16x16x32_bf16 v[46:49], v[98:101], v[106:109], v[46:49]
	v_mfma_f32_16x16x32_bf16 v[42:45], v[90:93], v[114:117], v[42:45]
	v_mfma_f32_16x16x32_bf16 v[34:37], v[98:101], v[114:117], v[34:37]
	v_mfma_f32_16x16x32_bf16 v[26:29], v[90:93], v[122:125], v[26:29]
	v_mfma_f32_16x16x32_bf16 v[18:21], v[98:101], v[122:125], v[18:21]
	v_mfma_f32_16x16x32_bf16 v[10:13], v[90:93], v[130:133], v[10:13]
	v_mfma_f32_16x16x32_bf16 v[2:5], v[98:101], v[130:133], v[2:5]
	v_mfma_f32_16x16x32_bf16 v[50:53], v[94:97], v[110:113], v[50:53]
	v_mfma_f32_16x16x32_bf16 v[46:49], v[102:105], v[110:113], v[46:49]
	v_mfma_f32_16x16x32_bf16 v[42:45], v[94:97], v[118:121], v[42:45]
	v_mfma_f32_16x16x32_bf16 v[34:37], v[102:105], v[118:121], v[34:37]
	v_mfma_f32_16x16x32_bf16 v[26:29], v[94:97], v[126:129], v[26:29]
	v_mfma_f32_16x16x32_bf16 v[18:21], v[102:105], v[126:129], v[18:21]
	v_mfma_f32_16x16x32_bf16 v[10:13], v[94:97], v[134:137], v[10:13]
	v_mfma_f32_16x16x32_bf16 v[2:5], v[102:105], v[134:137], v[2:5]
	s_barrier
	s_setprio 0
	s_mov_b32 m0, s20
	s_add_i32 s28, s28, 0x80080
	buffer_load_dwordx4 v67, s[40:43], s29 offen lds
	s_mov_b32 m0, s21
	s_nop 0
	buffer_load_dwordx4 v69, s[40:43], s29 offen lds
	s_mov_b32 m0, s24
	s_nop 0
	buffer_load_dwordx4 v67, s[40:43], s28 offen lds
	s_mov_b32 m0, s25
	s_nop 0
	buffer_load_dwordx4 v69, s[40:43], s28 offen lds
	s_mov_b32 m0, s22
	s_nop 0
	buffer_load_dwordx4 v66, s[76:79], s30 offen lds
	s_mov_b32 m0, s23
	s_nop 0
	buffer_load_dwordx4 v68, s[76:79], s30 offen lds
	s_waitcnt vmcnt(6)
	s_barrier
	s_barrier
	s_addk_i32 s26, 0x100
	s_add_i32 s27, s27, 2
	s_cmp_gt_u32 s27, 29
	s_cbranch_scc0 .LBB0_1668
	s_cmpk_lt_u32 s11, 0x100
	s_cbranch_scc0 .LBB0_1671
	s_barrier

; #define PG8_STAGEX(rs, bufoff, soff, voff) do { _Pragma("unroll") for (int _i = 0; _i < 2; ++_i) \
;         __builtin_amdgcn_raw_ptr_buffer_load_lds(rs, (LAS unsigned*)(lds + (bufoff) + ldsw + _i * 8192), 16, (voff)[_i], (soff), 0, 0); } while (0)
; #define PG8_LDA(dst, b, h) do { _Pragma("unroll") for (int m = 0; m < 4; ++m) _Pragma("unroll") for (int k = 0; k < 2; ++k) dst[m][k] = *(const LAS bf16x8*)(lds + PG8_SA(b, h) + aoff + m * 2048 + k * 1024); } while (0)
; #define PG8_LDB(dst, b, h) do { _Pragma("unroll") for (int n = 0; n < 2; ++n) _Pragma("unroll") for (int k = 0; k < 2; ++k) dst[n][k] = *(const LAS bf16x8*)(lds + PG8_SB(b, h) + boff + n * 2048 + k * 1024); } while (0)
; #define PG8_WAIT_V(n) asm volatile("s_waitcnt vmcnt(" #n ")" ::: "memory")
; #define PG8_WAIT_L(n) asm volatile("s_waitcnt lgkmcnt(" #n ")" ::: "memory")
; #define PG8_BAR __builtin_amdgcn_s_barrier()
; #define PG8_SCHED __builtin_amdgcn_sched_barrier(0)
;     ...
;         for (int t = 0; t < nt; t += 2) {
;             const bool last = (t == nt - 2);
;             const unsigned a1 = cA + (unsigned)(t + 1) * kstep;
;             const unsigned a2 = last ? nA : cA + (unsigned)(t + 2) * kstep, b2 = last ? nB : cB + (unsigned)(t + 2) * kstep;
;             const unsigned a3 = a2 + kstep, b3 = b2 + kstep;
;             PG8_LDB(B0, 0, 0); PG8_LDB(B1, 0, 1); PG8_SCHED; PG8_LDA(At, 0, 0); PG8_STAGEX(rsA, PG8_SA(1, 1), a1 + hstepA, voffA);
;             PG8_WAIT_V(8); PG8_WAIT_L(0); PG8_BAR; PG8_MMA(0, 0, At, B0); PG8_MMA(0, 1, At, B1); PG8_BAR; PG8_SCHED;
;             PG8_LDA(At, 0, 1); PG8_STAGEX(rsB, PG8_SB(0, 0), b2, voffB); PG8_STAGEX(rsB, PG8_SB(0, 1), b2 + hstepB, voffB); PG8_STAGEX(rsA, PG8_SA(0, 0), a2, voffA);
;             PG8_WAIT_V(8); PG8_WAIT_L(0); PG8_BAR; PG8_MMA(1, 0, At, B0); PG8_MMA(1, 1, At, B1); PG8_BAR; PG8_SCHED;
.LBB0_1750:
	v_add_u32_e32 v70, 0x10000, v241
	ds_read_b128 v[134:137], v70
	ds_read_b128 v[138:141], v70 offset:1024
	ds_read_b128 v[142:145], v70 offset:2048
	ds_read_b128 v[146:149], v70 offset:3072
	v_add_u32_e32 v70, 0x14000, v241
	ds_read_b128 v[150:153], v70
	ds_read_b128 v[154:157], v70 offset:1024
	ds_read_b128 v[158:161], v70 offset:2048
	ds_read_b128 v[162:165], v70 offset:3072
	s_add_i32 s46, s40, 0xffea8080
	s_cmpk_eq_i32 s60, 0x52
	s_cselect_b32 s63, s30, s46
	s_cselect_b32 s62, s31, s41
	s_or_b32 s61, s63, 0x80
	s_mov_b32 m0, s72
	ds_read_b128 v[166:169], v242
	ds_read_b128 v[170:173], v242 offset:1024
	ds_read_b128 v[184:187], v242 offset:2048
	ds_read_b128 v[188:191], v242 offset:3072
	ds_read_b128 v[192:195], v242 offset:4096
	ds_read_b128 v[196:199], v242 offset:5120
	ds_read_b128 v[200:203], v242 offset:6144
	ds_read_b128 v[204:207], v242 offset:7168
	buffer_load_dwordx4 v178, s[76:79], s40 offen lds
	s_mov_b32 m0, s73
	s_nop 0
	buffer_load_dwordx4 v237, s[76:79], s40 offen lds
	s_waitcnt vmcnt(8)
	s_waitcnt lgkmcnt(0)
	s_setprio 1
	s_barrier
	v_mfma_f32_16x16x32_bf16 v[130:133], v[134:137], v[166:169], v[130:133]
	v_mfma_f32_16x16x32_bf16 v[130:133], v[138:141], v[170:173], v[130:133]
	v_mfma_f32_16x16x32_bf16 v[126:129], v[142:145], v[166:169], v[126:129]
	v_mfma_f32_16x16x32_bf16 v[126:129], v[146:149], v[170:173], v[126:129]
	v_mfma_f32_16x16x32_bf16 v[122:125], v[134:137], v[184:187], v[122:125]
	v_mfma_f32_16x16x32_bf16 v[122:125], v[138:141], v[188:191], v[122:125]
	v_mfma_f32_16x16x32_bf16 v[118:121], v[142:145], v[184:187], v[118:121]
	v_mfma_f32_16x16x32_bf16 v[118:121], v[146:149], v[188:191], v[118:121]
	v_mfma_f32_16x16x32_bf16 v[114:117], v[134:137], v[192:195], v[114:117]
	v_mfma_f32_16x16x32_bf16 v[114:117], v[138:141], v[196:199], v[114:117]
	v_mfma_f32_16x16x32_bf16 v[110:113], v[142:145], v[192:195], v[110:113]
	v_mfma_f32_16x16x32_bf16 v[110:113], v[146:149], v[196:199], v[110:113]
	v_mfma_f32_16x16x32_bf16 v[106:109], v[134:137], v[200:203], v[106:109]
	v_mfma_f32_16x16x32_bf16 v[106:109], v[138:141], v[204:207], v[106:109]
	v_mfma_f32_16x16x32_bf16 v[102:105], v[142:145], v[200:203], v[102:105]
	v_mfma_f32_16x16x32_bf16 v[102:105], v[146:149], v[204:207], v[102:105]
	v_mfma_f32_16x16x32_bf16 v[62:65], v[150:153], v[166:169], v[62:65]
	v_mfma_f32_16x16x32_bf16 v[62:65], v[154:157], v[170:173], v[62:65]
	v_mfma_f32_16x16x32_bf16 v[58:61], v[158:161], v[166:169], v[58:61]
	v_mfma_f32_16x16x32_bf16 v[58:61], v[162:165], v[170:173], v[58:61]
	v_mfma_f32_16x16x32_bf16 v[54:57], v[150:153], v[184:187], v[54:57]
	v_mfma_f32_16x16x32_bf16 v[54:57], v[154:157], v[188:191], v[54:57]
	v_mfma_f32_16x16x32_bf16 v[50:53], v[158:161], v[184:187], v[50:53]
	v_mfma_f32_16x16x32_bf16 v[50:53], v[162:165], v[188:191], v[50:53]
	v_mfma_f32_16x16x32_bf16 v[46:49], v[150:153], v[192:195], v[46:49]
	v_mfma_f32_16x16x32_bf16 v[46:49], v[154:157], v[196:199], v[46:49]
	v_mfma_f32_16x16x32_bf16 v[42:45], v[158:161], v[192:195], v[42:45]
	v_mfma_f32_16x16x32_bf16 v[42:45], v[162:165], v[196:199], v[42:45]
	v_mfma_f32_16x16x32_bf16 v[38:41], v[150:153], v[200:203], v[38:41]
	v_mfma_f32_16x16x32_bf16 v[38:41], v[154:157], v[204:207], v[38:41]
	v_mfma_f32_16x16x32_bf16 v[34:37], v[158:161], v[200:203], v[34:37]
	v_mfma_f32_16x16x32_bf16 v[34:37], v[162:165], v[204:207], v[34:37]
	s_barrier
	s_setprio 0
	s_mov_b32 m0, s17
	s_mov_b32 s46, s78
	s_mov_b32 s47, s79
	ds_read_b128 v[166:169], v242 offset:16384
	ds_read_b128 v[170:173], v242 offset:17408
	ds_read_b128 v[184:187], v242 offset:18432
	ds_read_b128 v[188:191], v242 offset:19456
	ds_read_b128 v[192:195], v242 offset:20480
	ds_read_b128 v[196:199], v242 offset:21504
	ds_read_b128 v[200:203], v242 offset:22528
	ds_read_b128 v[204:207], v242 offset:23552
	buffer_load_dwordx4 v179, s[44:47], s62 offen lds
	s_mov_b32 m0, s18
	s_add_i32 s64, s62, 0x158000
	buffer_load_dwordx4 v238, s[44:47], s62 offen lds
	s_mov_b32 m0, s19
	s_nop 0
	buffer_load_dwordx4 v179, s[44:47], s64 offen lds
	s_mov_b32 m0, s20
	s_nop 0
	buffer_load_dwordx4 v238, s[44:47], s64 offen lds
	s_mov_b32 m0, s16
	s_nop 0
	buffer_load_dwordx4 v178, s[76:79], s63 offen lds
	s_mov_b32 m0, s21
	s_nop 0
	buffer_load_dwordx4 v237, s[76:79], s63 offen lds
	s_waitcnt vmcnt(8)
	s_waitcnt lgkmcnt(0)
	s_setprio 1
	s_barrier
	v_mfma_f32_16x16x32_bf16 v[98:101], v[134:137], v[166:169], v[98:101]
	v_mfma_f32_16x16x32_bf16 v[94:97], v[142:145], v[166:169], v[94:97]
	v_mfma_f32_16x16x32_bf16 v[90:93], v[134:137], v[184:187], v[90:93]
	v_mfma_f32_16x16x32_bf16 v[86:89], v[142:145], v[184:187], v[86:89]
	v_mfma_f32_16x16x32_bf16 v[82:85], v[134:137], v[192:195], v[82:85]
	v_mfma_f32_16x16x32_bf16 v[76:79], v[142:145], v[192:195], v[78:81]
	v_mfma_f32_16x16x32_bf16 v[70:73], v[134:137], v[200:203], v[72:75]
	v_mfma_f32_16x16x32_bf16 v[66:69], v[142:145], v[200:203], v[66:69]
	v_mfma_f32_16x16x32_bf16 v[98:101], v[138:141], v[170:173], v[98:101]
	v_mfma_f32_16x16x32_bf16 v[94:97], v[146:149], v[170:173], v[94:97]
	v_mfma_f32_16x16x32_bf16 v[90:93], v[138:141], v[188:191], v[90:93]
	v_mfma_f32_16x16x32_bf16 v[86:89], v[146:149], v[188:191], v[86:89]
	v_mfma_f32_16x16x32_bf16 v[82:85], v[138:141], v[196:199], v[82:85]
	v_mfma_f32_16x16x32_bf16 v[76:79], v[146:149], v[196:199], v[76:79]
	v_mfma_f32_16x16x32_bf16 v[70:73], v[138:141], v[204:207], v[70:73]
	v_mfma_f32_16x16x32_bf16 v[66:69], v[146:149], v[204:207], v[66:69]
	v_mfma_f32_16x16x32_bf16 v[30:33], v[150:153], v[166:169], v[30:33]
	v_mfma_f32_16x16x32_bf16 v[26:29], v[158:161], v[166:169], v[26:29]
	v_mfma_f32_16x16x32_bf16 v[22:25], v[150:153], v[184:187], v[22:25]
	v_mfma_f32_16x16x32_bf16 v[18:21], v[158:161], v[184:187], v[18:21]
	v_mfma_f32_16x16x32_bf16 v[14:17], v[150:153], v[192:195], v[14:17]
	v_mfma_f32_16x16x32_bf16 v[10:13], v[158:161], v[192:195], v[10:13]
	v_mfma_f32_16x16x32_bf16 v[6:9], v[150:153], v[200:203], v[6:9]
	v_mfma_f32_16x16x32_bf16 v[2:5], v[158:161], v[200:203], v[2:5]
	v_mfma_f32_16x16x32_bf16 v[30:33], v[154:157], v[170:173], v[30:33]
	v_mfma_f32_16x16x32_bf16 v[26:29], v[162:165], v[170:173], v[26:29]
	v_mfma_f32_16x16x32_bf16 v[22:25], v[154:157], v[188:191], v[22:25]
	v_mfma_f32_16x16x32_bf16 v[18:21], v[162:165], v[188:191], v[18:21]
	v_mfma_f32_16x16x32_bf16 v[14:17], v[154:157], v[196:199], v[14:17]
	v_mfma_f32_16x16x32_bf16 v[10:13], v[162:165], v[196:199], v[10:13]
	v_mfma_f32_16x16x32_bf16 v[6:9], v[154:157], v[204:207], v[6:9]
	v_mfma_f32_16x16x32_bf16 v[2:5], v[162:165], v[204:207], v[2:5]
	s_barrier
; #define PG8_STAGEX(rs, bufoff, soff, voff) do { _Pragma("unroll") for (int _i = 0; _i < 2; ++_i) \
;         __builtin_amdgcn_raw_ptr_buffer_load_lds(rs, (LAS unsigned*)(lds + (bufoff) + ldsw + _i * 8192), 16, (voff)[_i], (soff), 0, 0); } while (0)
; #define PG8_LDA(dst, b, h) do { _Pragma("unroll") for (int m = 0; m < 4; ++m) _Pragma("unroll") for (int k = 0; k < 2; ++k) dst[m][k] = *(const LAS bf16x8*)(lds + PG8_SA(b, h) + aoff + m * 2048 + k * 1024); } while (0)
; #define PG8_LDB(dst, b, h) do { _Pragma("unroll") for (int n = 0; n < 2; ++n) _Pragma("unroll") for (int k = 0; k < 2; ++k) dst[n][k] = *(const LAS bf16x8*)(lds + PG8_SB(b, h) + boff + n * 2048 + k * 1024); } while (0)
; #define PG8_WAIT_V(n) asm volatile("s_waitcnt vmcnt(" #n ")" ::: "memory")
; #define PG8_WAIT_L(n) asm volatile("s_waitcnt lgkmcnt(" #n ")" ::: "memory")
; #define PG8_BAR __builtin_amdgcn_s_barrier()
; #define PG8_SCHED __builtin_amdgcn_sched_barrier(0)
;     ...
;             PG8_LDB(B0, 1, 0); PG8_LDB(B1, 1, 1); PG8_SCHED; PG8_LDA(At, 1, 0); PG8_STAGEX(rsA, PG8_SA(0, 1), a2 + hstepA, voffA);
;             PG8_WAIT_V(8); PG8_WAIT_L(0); PG8_BAR; PG8_MMA(0, 0, At, B0); PG8_MMA(0, 1, At, B1); PG8_BAR; PG8_SCHED;
;             PG8_LDA(At, 1, 1); PG8_STAGEX(rsB, PG8_SB(1, 0), b3, voffB); PG8_STAGEX(rsB, PG8_SB(1, 1), b3 + hstepB, voffB); PG8_STAGEX(rsA, PG8_SA(1, 0), a3, voffA);
;             PG8_WAIT_V(8); PG8_WAIT_L(0); PG8_BAR; PG8_MMA(1, 0, At, B0); PG8_MMA(1, 1, At, B1); PG8_BAR; PG8_SCHED;
;         }
;     ...
;         if (wr == 0) PG8_BAR;
	s_setprio 0
	v_add_u32_e32 v74, 0x18000, v241
	ds_read_b128 v[134:137], v74
	ds_read_b128 v[138:141], v74 offset:1024
	ds_read_b128 v[142:145], v74 offset:2048
	ds_read_b128 v[146:149], v74 offset:3072
	v_add_u32_e32 v74, 0x1c000, v241
	ds_read_b128 v[150:153], v74
	ds_read_b128 v[154:157], v74 offset:1024
	ds_read_b128 v[158:161], v74 offset:2048
	ds_read_b128 v[162:165], v74 offset:3072
	s_add_i32 s63, s63, 0x158000
	s_mov_b32 m0, s22
	ds_read_b128 v[166:169], v242 offset:32768
	ds_read_b128 v[170:173], v242 offset:33792
	ds_read_b128 v[184:187], v242 offset:34816
	ds_read_b128 v[188:191], v242 offset:35840
	ds_read_b128 v[192:195], v242 offset:36864
	ds_read_b128 v[196:199], v242 offset:37888
	ds_read_b128 v[200:203], v242 offset:38912
	ds_read_b128 v[204:207], v242 offset:39936
	buffer_load_dwordx4 v178, s[76:79], s63 offen lds
	s_mov_b32 m0, s23
	s_nop 0
	buffer_load_dwordx4 v237, s[76:79], s63 offen lds
	s_waitcnt vmcnt(8)
	s_waitcnt lgkmcnt(0)
	s_setprio 1
	s_barrier
	v_mfma_f32_16x16x32_bf16 v[130:133], v[134:137], v[166:169], v[130:133]
	v_mfma_f32_16x16x32_bf16 v[130:133], v[138:141], v[170:173], v[130:133]
	v_mfma_f32_16x16x32_bf16 v[126:129], v[142:145], v[166:169], v[126:129]
	v_mfma_f32_16x16x32_bf16 v[126:129], v[146:149], v[170:173], v[126:129]
	v_mfma_f32_16x16x32_bf16 v[122:125], v[134:137], v[184:187], v[122:125]
	v_mfma_f32_16x16x32_bf16 v[122:125], v[138:141], v[188:191], v[122:125]
	v_mfma_f32_16x16x32_bf16 v[118:121], v[142:145], v[184:187], v[118:121]
	v_mfma_f32_16x16x32_bf16 v[118:121], v[146:149], v[188:191], v[118:121]
	v_mfma_f32_16x16x32_bf16 v[114:117], v[134:137], v[192:195], v[114:117]
	v_mfma_f32_16x16x32_bf16 v[114:117], v[138:141], v[196:199], v[114:117]
	v_mfma_f32_16x16x32_bf16 v[110:113], v[142:145], v[192:195], v[110:113]
	v_mfma_f32_16x16x32_bf16 v[110:113], v[146:149], v[196:199], v[110:113]
	v_mfma_f32_16x16x32_bf16 v[106:109], v[134:137], v[200:203], v[106:109]
	v_mfma_f32_16x16x32_bf16 v[106:109], v[138:141], v[204:207], v[106:109]
	v_mfma_f32_16x16x32_bf16 v[102:105], v[142:145], v[200:203], v[102:105]
	v_mfma_f32_16x16x32_bf16 v[102:105], v[146:149], v[204:207], v[102:105]
	v_mfma_f32_16x16x32_bf16 v[62:65], v[150:153], v[166:169], v[62:65]
	v_mfma_f32_16x16x32_bf16 v[62:65], v[154:157], v[170:173], v[62:65]
	v_mfma_f32_16x16x32_bf16 v[58:61], v[158:161], v[166:169], v[58:61]
	v_mfma_f32_16x16x32_bf16 v[58:61], v[162:165], v[170:173], v[58:61]
	v_mfma_f32_16x16x32_bf16 v[54:57], v[150:153], v[184:187], v[54:57]
	v_mfma_f32_16x16x32_bf16 v[54:57], v[154:157], v[188:191], v[54:57]
	v_mfma_f32_16x16x32_bf16 v[50:53], v[158:161], v[184:187], v[50:53]
	v_mfma_f32_16x16x32_bf16 v[50:53], v[162:165], v[188:191], v[50:53]
	v_mfma_f32_16x16x32_bf16 v[46:49], v[150:153], v[192:195], v[46:49]
	v_mfma_f32_16x16x32_bf16 v[46:49], v[154:157], v[196:199], v[46:49]
	v_mfma_f32_16x16x32_bf16 v[42:45], v[158:161], v[192:195], v[42:45]
	v_mfma_f32_16x16x32_bf16 v[42:45], v[162:165], v[196:199], v[42:45]
	v_mfma_f32_16x16x32_bf16 v[38:41], v[150:153], v[200:203], v[38:41]
	v_mfma_f32_16x16x32_bf16 v[38:41], v[154:157], v[204:207], v[38:41]
	v_mfma_f32_16x16x32_bf16 v[34:37], v[158:161], v[200:203], v[34:37]
	v_mfma_f32_16x16x32_bf16 v[34:37], v[162:165], v[204:207], v[34:37]
	s_barrier
	s_setprio 0
	s_mov_b32 m0, s54
	s_or_b32 s63, s62, 0x80
	ds_read_b128 v[166:169], v242 offset:49152
	ds_read_b128 v[170:173], v242 offset:50176
	ds_read_b128 v[184:187], v242 offset:51200
	ds_read_b128 v[188:191], v242 offset:52224
	ds_read_b128 v[192:195], v242 offset:53248
	ds_read_b128 v[196:199], v242 offset:54272
	ds_read_b128 v[200:203], v242 offset:55296
	ds_read_b128 v[204:207], v242 offset:56320
	buffer_load_dwordx4 v179, s[44:47], s63 offen lds
	s_mov_b32 m0, s55
	s_add_i32 s62, s62, 0x158080
	buffer_load_dwordx4 v238, s[44:47], s63 offen lds
	s_mov_b32 m0, s70
	s_nop 0
	buffer_load_dwordx4 v179, s[44:47], s62 offen lds
	s_mov_b32 m0, s71
	s_nop 0
	buffer_load_dwordx4 v238, s[44:47], s62 offen lds
	s_mov_b32 m0, s68
	s_nop 0
	buffer_load_dwordx4 v178, s[76:79], s61 offen lds
	s_mov_b32 m0, s69
	s_nop 0
	buffer_load_dwordx4 v237, s[76:79], s61 offen lds
	s_waitcnt vmcnt(8)
	s_waitcnt lgkmcnt(0)
	s_setprio 1
	s_barrier
	v_mfma_f32_16x16x32_bf16 v[98:101], v[134:137], v[166:169], v[98:101]
	v_mfma_f32_16x16x32_bf16 v[94:97], v[142:145], v[166:169], v[94:97]
	v_mfma_f32_16x16x32_bf16 v[90:93], v[134:137], v[184:187], v[90:93]
	v_mfma_f32_16x16x32_bf16 v[86:89], v[142:145], v[184:187], v[86:89]
	v_mfma_f32_16x16x32_bf16 v[80:83], v[134:137], v[192:195], v[82:85]
	v_mfma_f32_16x16x32_bf16 v[74:77], v[142:145], v[192:195], v[76:79]
	v_mfma_f32_16x16x32_bf16 v[70:73], v[134:137], v[200:203], v[70:73]
	v_mfma_f32_16x16x32_bf16 v[66:69], v[142:145], v[200:203], v[66:69]
	v_mfma_f32_16x16x32_bf16 v[98:101], v[138:141], v[170:173], v[98:101]
	v_mfma_f32_16x16x32_bf16 v[94:97], v[146:149], v[170:173], v[94:97]
	v_mfma_f32_16x16x32_bf16 v[90:93], v[138:141], v[188:191], v[90:93]
	v_mfma_f32_16x16x32_bf16 v[86:89], v[146:149], v[188:191], v[86:89]
	v_mfma_f32_16x16x32_bf16 v[82:85], v[138:141], v[196:199], v[80:83]
	v_mfma_f32_16x16x32_bf16 v[78:81], v[146:149], v[196:199], v[74:77]
	v_mfma_f32_16x16x32_bf16 v[72:75], v[138:141], v[204:207], v[70:73]
	v_mfma_f32_16x16x32_bf16 v[66:69], v[146:149], v[204:207], v[66:69]
	v_mfma_f32_16x16x32_bf16 v[30:33], v[150:153], v[166:169], v[30:33]
	v_mfma_f32_16x16x32_bf16 v[26:29], v[158:161], v[166:169], v[26:29]
	v_mfma_f32_16x16x32_bf16 v[22:25], v[150:153], v[184:187], v[22:25]
	v_mfma_f32_16x16x32_bf16 v[18:21], v[158:161], v[184:187], v[18:21]
	v_mfma_f32_16x16x32_bf16 v[14:17], v[150:153], v[192:195], v[14:17]
	v_mfma_f32_16x16x32_bf16 v[10:13], v[158:161], v[192:195], v[10:13]
	v_mfma_f32_16x16x32_bf16 v[6:9], v[150:153], v[200:203], v[6:9]
	v_mfma_f32_16x16x32_bf16 v[2:5], v[158:161], v[200:203], v[2:5]
	v_mfma_f32_16x16x32_bf16 v[30:33], v[154:157], v[170:173], v[30:33]
	v_mfma_f32_16x16x32_bf16 v[26:29], v[162:165], v[170:173], v[26:29]
	v_mfma_f32_16x16x32_bf16 v[22:25], v[154:157], v[188:191], v[22:25]
	v_mfma_f32_16x16x32_bf16 v[18:21], v[162:165], v[188:191], v[18:21]
	v_mfma_f32_16x16x32_bf16 v[14:17], v[154:157], v[196:199], v[14:17]
	v_mfma_f32_16x16x32_bf16 v[10:13], v[162:165], v[196:199], v[10:13]
	v_mfma_f32_16x16x32_bf16 v[6:9], v[154:157], v[204:207], v[6:9]
	v_mfma_f32_16x16x32_bf16 v[2:5], v[162:165], v[204:207], v[2:5]
	s_barrier
	s_setprio 0
	s_add_i32 s60, s60, 2
	s_addk_i32 s40, 0x100
	s_addk_i32 s41, 0x100
	s_cmpk_gt_u32 s60, 0x53
	s_cbranch_scc0 .LBB0_1750
	s_and_b64 vcc, exec, s[50:51]
	s_cbranch_vccz .LBB0_1753
	s_barrier
